# store coalescing also in YA/YB epilogues; delayed stores always flushed before any counted vmcnt wait
# baseline (speedup 1.0000x reference)
; __device__ __forceinline__ unsigned cvt_pk_bf16(float lo, float hi) { f32x2 v = {lo, hi}; bf16x2_t b = __builtin_convertvector(v, bf16x2_t); return __builtin_bit_cast(unsigned, b); }
; __device__ __forceinline__ float bf_lo(unsigned w) { return __uint_as_float(w << 16); }
; __device__ __forceinline__ float bf_hi(unsigned w) { return __uint_as_float(w & 0xffff0000u); }
; __device__ __forceinline__ float sigm(float v) { return __builtin_amdgcn_rcpf(1.0f + __builtin_amdgcn_exp2f(-1.44269504089f * v)); }
; #define EPI_FENCE asm volatile("" ::: "memory")
; __device__ __forceinline__ void epi_run(const Epi& E, f32x4 (&acc)[2][2][4][2], const Unit& u, int wr, int wc, int fr, int fq) {
;     ...
;     } else if (mode == MODE_YB) {
; #pragma unroll
;         for (int ai = 0; ai < 2; ++ai) { u32x4 g[4][2], c[4][2];
; #pragma unroll
;             for (int m = 0; m < 4; ++m)
; #pragma unroll
;                 for (int bj = 0; bj < 2; ++bj) { const bf16_t* gp = E.Z + (size_t)(row0 + ai * 128 + m * 16) * NIN + 4096 + col0 + bj * 128; g[m][bj] = *(const u32x4*)gp; c[m][bj] = *(const u32x4*)(gp - 1024); }
; #pragma unroll
;             for (int m = 0; m < 4; ++m)
; #pragma unroll
;                 for (int bj = 0; bj < 2; ++bj) { const f32x4 v0 = acc[ai][bj][m][0], v1 = acc[ai][bj][m][1]; const u32x4 gg = g[m][bj], cc = c[m][bj]; u32x4 w;
;                     w.x = cvt_pk_bf16(bf_lo(cc.x) + v0[0] * sigm(bf_lo(gg.x)), bf_hi(cc.x) + v0[1] * sigm(bf_hi(gg.x))); w.y = cvt_pk_bf16(bf_lo(cc.y) + v0[2] * sigm(bf_lo(gg.y)), bf_hi(cc.y) + v0[3] * sigm(bf_hi(gg.y)));
;                     w.z = cvt_pk_bf16(bf_lo(cc.z) + v1[0] * sigm(bf_lo(gg.z)), bf_hi(cc.z) + v1[1] * sigm(bf_hi(gg.z))); w.w = cvt_pk_bf16(bf_lo(cc.w) + v1[2] * sigm(bf_lo(gg.w)), bf_hi(cc.w) + v1[3] * sigm(bf_hi(gg.w)));
;                     *(u32x4*)(E.Z + (size_t)(row0 + ai * 128 + m * 16) * NIN + 4096 + col0 + bj * 128) = w; }
;             EPI_FENCE; }
.LBB0_295:
	s_and_b64 vcc, exec, s[8:9]
	s_cbranch_vccz .LBB0_298
	v_lshrrev_b32_e32 v244, 2, v201
	v_and_b32_e32 v245, 3, v201
	v_lshl_add_u32 v243, v245, 4, v244
	v_lshlrev_b32_e32 v243, 2, v243
	v_and_b32_e32 v246, 15, v201
	v_sub_u32_e32 v244, v244, v246
	v_lshrrev_b32_e32 v246, 4, v201
	v_sub_u32_e32 v245, v245, v246
	v_lshlrev_b32_e32 v245, 4, v245
	v_mul_lo_u32 v244, v244, s69
	v_add_u32_e32 v230, v244, v245
	v_ashrrev_i32_e32 v231, 31, v230
	v_ashrrev_i32_e32 v213, 31, v212
	v_mov_b64_e32 v[214:215], s[70:71]
	s_waitcnt lgkmcnt(0)
	v_mad_i64_i32 v[130:131], s[8:9], v210, s69, v[214:215]
	v_lshlrev_b64 v[216:217], 1, v[212:213]
	v_lshl_add_u64 v[130:131], v[130:131], 0, v[216:217]
	v_add_co_u32_e32 v224, vcc, 0x2000, v130
	s_mov_b64 s[20:21], 0x2000
	s_nop 0
	v_addc_co_u32_e32 v225, vcc, 0, v131, vcc
	v_lshl_add_u64 v[132:133], v[130:131], 0, s[20:21]
	global_load_dwordx4 v[190:193], v[224:225], off
	global_load_dwordx4 v[186:189], v[132:133], off offset:-2048
	global_load_dwordx4 v[182:185], v[132:133], off offset:256
	global_load_dwordx4 v[178:181], v[132:133], off offset:-1792
	v_or_b32_e32 v0, 16, v210
	v_mad_i64_i32 v[130:131], s[8:9], v0, s69, v[214:215]
	v_lshl_add_u64 v[130:131], v[130:131], 0, v[216:217]
	v_add_co_u32_e32 v222, vcc, s3, v130
	v_or_b32_e32 v0, 32, v210
	v_lshl_add_u64 v[132:133], v[130:131], 0, s[20:21]
	v_addc_co_u32_e32 v223, vcc, 0, v131, vcc
	v_mad_i64_i32 v[130:131], s[8:9], v0, s69, v[214:215]
	v_lshl_add_u64 v[130:131], v[130:131], 0, v[216:217]
	v_add_co_u32_e32 v220, vcc, s3, v130
	v_or_b32_e32 v0, 48, v210
	global_load_dwordx4 v[174:177], v[222:223], off
	global_load_dwordx4 v[170:173], v[132:133], off offset:-2048
	global_load_dwordx4 v[166:169], v[132:133], off offset:256
	global_load_dwordx4 v[162:165], v[132:133], off offset:-1792
	v_lshl_add_u64 v[132:133], v[130:131], 0, s[20:21]
	v_addc_co_u32_e32 v221, vcc, 0, v131, vcc
	v_mad_i64_i32 v[130:131], s[8:9], v0, s69, v[214:215]
	v_lshl_add_u64 v[130:131], v[130:131], 0, v[216:217]
	v_add_co_u32_e32 v218, vcc, s3, v130
	global_load_dwordx4 v[158:161], v[220:221], off
	global_load_dwordx4 v[154:157], v[132:133], off offset:-2048
	global_load_dwordx4 v[150:153], v[132:133], off offset:256
	global_load_dwordx4 v[146:149], v[132:133], off offset:-1792
	v_lshl_add_u64 v[132:133], v[130:131], 0, s[20:21]
	v_addc_co_u32_e32 v219, vcc, 0, v131, vcc
	global_load_dwordx4 v[138:141], v[218:219], off
	global_load_dwordx4 v[142:145], v[132:133], off offset:-2048
	global_load_dwordx4 v[134:137], v[132:133], off offset:256
	s_nop 0
	global_load_dwordx4 v[130:133], v[132:133], off offset:-1792
	s_waitcnt vmcnt(0)
	v_lshlrev_b32_e32 v0, 16, v190
	v_mul_f32_e32 v0, 0xbfb8aa3b, v0
	v_exp_f32_e32 v0, v0
	v_lshlrev_b32_e32 v228, 16, v186
	v_and_b32_e32 v229, 0xffff0000, v186
	v_add_f32_e32 v0, 1.0, v0
	v_rcp_f32_e32 v226, v0
	v_and_b32_e32 v0, 0xffff0000, v190
	v_mul_f32_e32 v0, 0xbfb8aa3b, v0
	v_exp_f32_e32 v0, v0
	s_nop 0
	v_add_f32_e32 v0, 1.0, v0
	v_rcp_f32_e32 v227, v0
	v_lshlrev_b32_e32 v0, 16, v191
	v_mul_f32_e32 v0, 0xbfb8aa3b, v0
	v_exp_f32_e32 v0, v0
	v_pk_fma_f32 v[226:227], v[126:127], v[226:227], v[228:229]
	v_add_f32_e32 v0, 1.0, v0
	v_rcp_f32_e32 v190, v0
	v_and_b32_e32 v0, 0xffff0000, v191
	v_mul_f32_e32 v0, 0xbfb8aa3b, v0
	v_exp_f32_e32 v0, v0
	v_cvt_pk_bf16_f32 v186, v226, v227
	v_lshlrev_b32_e32 v226, 16, v187
	v_and_b32_e32 v227, 0xffff0000, v187
	v_add_f32_e32 v0, 1.0, v0
	v_rcp_f32_e32 v191, v0
	v_lshlrev_b32_e32 v0, 16, v192
	v_mul_f32_e32 v0, 0xbfb8aa3b, v0
	v_exp_f32_e32 v0, v0
	v_pk_fma_f32 v[190:191], v[128:129], v[190:191], v[226:227]
	v_lshlrev_b32_e32 v226, 16, v188
	v_cvt_pk_bf16_f32 v187, v190, v191
	v_add_f32_e32 v0, 1.0, v0
	v_rcp_f32_e32 v190, v0
	v_and_b32_e32 v0, 0xffff0000, v192
	v_mul_f32_e32 v0, 0xbfb8aa3b, v0
	v_exp_f32_e32 v0, v0
	v_and_b32_e32 v227, 0xffff0000, v188
	v_lshlrev_b32_e32 v192, 16, v189
	v_add_f32_e32 v0, 1.0, v0
	v_rcp_f32_e32 v191, v0
	v_lshlrev_b32_e32 v0, 16, v193
	v_mul_f32_e32 v0, 0xbfb8aa3b, v0
	v_exp_f32_e32 v0, v0
	v_pk_fma_f32 v[190:191], v[122:123], v[190:191], v[226:227]
	v_add_f32_e32 v0, 1.0, v0
	v_cvt_pk_bf16_f32 v188, v190, v191
	v_rcp_f32_e32 v190, v0
	v_and_b32_e32 v0, 0xffff0000, v193
	v_mul_f32_e32 v0, 0xbfb8aa3b, v0
	v_exp_f32_e32 v0, v0
	v_and_b32_e32 v193, 0xffff0000, v189
	v_add_f32_e32 v0, 1.0, v0
	v_rcp_f32_e32 v191, v0
	v_lshlrev_b32_e32 v0, 16, v182
	v_mul_f32_e32 v0, 0xbfb8aa3b, v0
	v_exp_f32_e32 v0, v0
	v_pk_fma_f32 v[190:191], v[124:125], v[190:191], v[192:193]
	v_add_f32_e32 v0, 1.0, v0
	v_cvt_pk_bf16_f32 v189, v190, v191
	v_lshl_add_u64 v[224:225], v[224:225], 0, v[230:231]
	ds_bpermute_b32 v244, v243, v186
	ds_bpermute_b32 v245, v243, v187
	ds_bpermute_b32 v246, v243, v188
	ds_bpermute_b32 v247, v243, v189
	s_nop 1
	v_rcp_f32_e32 v186, v0
	v_and_b32_e32 v0, 0xffff0000, v182
	v_mul_f32_e32 v0, 0xbfb8aa3b, v0
	v_exp_f32_e32 v0, v0
	v_lshlrev_b32_e32 v188, 16, v178
	v_and_b32_e32 v189, 0xffff0000, v178
	v_add_f32_e32 v0, 1.0, v0
	v_rcp_f32_e32 v187, v0
	v_lshlrev_b32_e32 v0, 16, v183
	v_mul_f32_e32 v0, 0xbfb8aa3b, v0
	v_exp_f32_e32 v0, v0
	v_pk_fma_f32 v[186:187], v[118:119], v[186:187], v[188:189]
	v_add_f32_e32 v0, 1.0, v0
	v_rcp_f32_e32 v182, v0
	v_and_b32_e32 v0, 0xffff0000, v183
	v_mul_f32_e32 v0, 0xbfb8aa3b, v0
	v_exp_f32_e32 v0, v0
	v_cvt_pk_bf16_f32 v178, v186, v187
	v_lshlrev_b32_e32 v186, 16, v179
	v_and_b32_e32 v187, 0xffff0000, v179
	v_add_f32_e32 v0, 1.0, v0
	v_rcp_f32_e32 v183, v0
	v_lshlrev_b32_e32 v0, 16, v184
	v_mul_f32_e32 v0, 0xbfb8aa3b, v0
	v_exp_f32_e32 v0, v0
	v_pk_fma_f32 v[182:183], v[120:121], v[182:183], v[186:187]
	v_lshlrev_b32_e32 v186, 16, v180
	v_cvt_pk_bf16_f32 v179, v182, v183
	v_add_f32_e32 v0, 1.0, v0
	v_rcp_f32_e32 v182, v0
	v_and_b32_e32 v0, 0xffff0000, v184
	v_mul_f32_e32 v0, 0xbfb8aa3b, v0
	v_exp_f32_e32 v0, v0
	v_and_b32_e32 v187, 0xffff0000, v180
	v_lshlrev_b32_e32 v184, 16, v181
	v_add_f32_e32 v0, 1.0, v0
	v_rcp_f32_e32 v183, v0
	v_lshlrev_b32_e32 v0, 16, v185
	v_mul_f32_e32 v0, 0xbfb8aa3b, v0
	v_exp_f32_e32 v0, v0
	v_pk_fma_f32 v[182:183], v[114:115], v[182:183], v[186:187]
	v_add_f32_e32 v0, 1.0, v0
	v_cvt_pk_bf16_f32 v180, v182, v183
	v_rcp_f32_e32 v182, v0
	v_and_b32_e32 v0, 0xffff0000, v185
	v_mul_f32_e32 v0, 0xbfb8aa3b, v0
	v_exp_f32_e32 v0, v0
	v_and_b32_e32 v185, 0xffff0000, v181
	v_add_f32_e32 v0, 1.0, v0
	v_rcp_f32_e32 v183, v0
	v_lshlrev_b32_e32 v0, 16, v174
	v_mul_f32_e32 v0, 0xbfb8aa3b, v0
	v_exp_f32_e32 v0, v0
	v_pk_fma_f32 v[182:183], v[116:117], v[182:183], v[184:185]
	v_add_f32_e32 v0, 1.0, v0
	v_cvt_pk_bf16_f32 v181, v182, v183
	s_waitcnt lgkmcnt(0)
; __device__ __forceinline__ unsigned cvt_pk_bf16(float lo, float hi) { f32x2 v = {lo, hi}; bf16x2_t b = __builtin_convertvector(v, bf16x2_t); return __builtin_bit_cast(unsigned, b); }
; __device__ __forceinline__ float bf_lo(unsigned w) { return __uint_as_float(w << 16); }
; __device__ __forceinline__ float bf_hi(unsigned w) { return __uint_as_float(w & 0xffff0000u); }
; __device__ __forceinline__ float sigm(float v) { return __builtin_amdgcn_rcpf(1.0f + __builtin_amdgcn_exp2f(-1.44269504089f * v)); }
; #define EPI_FENCE asm volatile("" ::: "memory")
; __device__ __forceinline__ void epi_run(const Epi& E, f32x4 (&acc)[2][2][4][2], const Unit& u, int wr, int wc, int fr, int fq) {
;     ...
;     } else if (mode == MODE_YB) {
; #pragma unroll
;         for (int ai = 0; ai < 2; ++ai) { u32x4 g[4][2], c[4][2];
; #pragma unroll
;             for (int m = 0; m < 4; ++m)
; #pragma unroll
;                 for (int bj = 0; bj < 2; ++bj) { const bf16_t* gp = E.Z + (size_t)(row0 + ai * 128 + m * 16) * NIN + 4096 + col0 + bj * 128; g[m][bj] = *(const u32x4*)gp; c[m][bj] = *(const u32x4*)(gp - 1024); }
; #pragma unroll
;             for (int m = 0; m < 4; ++m)
; #pragma unroll
;                 for (int bj = 0; bj < 2; ++bj) { const f32x4 v0 = acc[ai][bj][m][0], v1 = acc[ai][bj][m][1]; const u32x4 gg = g[m][bj], cc = c[m][bj]; u32x4 w;
;                     w.x = cvt_pk_bf16(bf_lo(cc.x) + v0[0] * sigm(bf_lo(gg.x)), bf_hi(cc.x) + v0[1] * sigm(bf_hi(gg.x))); w.y = cvt_pk_bf16(bf_lo(cc.y) + v0[2] * sigm(bf_lo(gg.y)), bf_hi(cc.y) + v0[3] * sigm(bf_hi(gg.y)));
;                     w.z = cvt_pk_bf16(bf_lo(cc.z) + v1[0] * sigm(bf_lo(gg.z)), bf_hi(cc.z) + v1[1] * sigm(bf_hi(gg.z))); w.w = cvt_pk_bf16(bf_lo(cc.w) + v1[2] * sigm(bf_lo(gg.w)), bf_hi(cc.w) + v1[3] * sigm(bf_hi(gg.w)));
;                     *(u32x4*)(E.Z + (size_t)(row0 + ai * 128 + m * 16) * NIN + 4096 + col0 + bj * 128) = w; }
;             EPI_FENCE; }
	global_store_dwordx4 v[224:225], v[244:247], off
	s_nop 1
	ds_bpermute_b32 v244, v243, v178
	ds_bpermute_b32 v245, v243, v179
	ds_bpermute_b32 v246, v243, v180
	ds_bpermute_b32 v247, v243, v181
	s_nop 1
	v_rcp_f32_e32 v178, v0
	v_and_b32_e32 v0, 0xffff0000, v174
	v_mul_f32_e32 v0, 0xbfb8aa3b, v0
	v_exp_f32_e32 v0, v0
	v_lshlrev_b32_e32 v180, 16, v170
	v_and_b32_e32 v181, 0xffff0000, v170
	v_add_f32_e32 v0, 1.0, v0
	v_rcp_f32_e32 v179, v0
	v_lshlrev_b32_e32 v0, 16, v175
	v_mul_f32_e32 v0, 0xbfb8aa3b, v0
	v_exp_f32_e32 v0, v0
	v_pk_fma_f32 v[178:179], v[110:111], v[178:179], v[180:181]
	v_add_f32_e32 v0, 1.0, v0
	v_rcp_f32_e32 v174, v0
	v_and_b32_e32 v0, 0xffff0000, v175
	v_mul_f32_e32 v0, 0xbfb8aa3b, v0
	v_exp_f32_e32 v0, v0
	v_cvt_pk_bf16_f32 v170, v178, v179
	v_lshlrev_b32_e32 v178, 16, v171
	v_and_b32_e32 v179, 0xffff0000, v171
	v_add_f32_e32 v0, 1.0, v0
	v_rcp_f32_e32 v175, v0
	v_lshlrev_b32_e32 v0, 16, v176
	v_mul_f32_e32 v0, 0xbfb8aa3b, v0
	v_exp_f32_e32 v0, v0
	v_pk_fma_f32 v[174:175], v[112:113], v[174:175], v[178:179]
	v_lshlrev_b32_e32 v178, 16, v172
	v_cvt_pk_bf16_f32 v171, v174, v175
	v_add_f32_e32 v0, 1.0, v0
	v_rcp_f32_e32 v174, v0
	v_and_b32_e32 v0, 0xffff0000, v176
	v_mul_f32_e32 v0, 0xbfb8aa3b, v0
	v_exp_f32_e32 v0, v0
	v_and_b32_e32 v179, 0xffff0000, v172
	v_lshlrev_b32_e32 v176, 16, v173
	v_add_f32_e32 v0, 1.0, v0
	v_rcp_f32_e32 v175, v0
	v_lshlrev_b32_e32 v0, 16, v177
	v_mul_f32_e32 v0, 0xbfb8aa3b, v0
	v_exp_f32_e32 v0, v0
	v_pk_fma_f32 v[174:175], v[106:107], v[174:175], v[178:179]
	v_add_f32_e32 v0, 1.0, v0
	v_cvt_pk_bf16_f32 v172, v174, v175
	v_rcp_f32_e32 v174, v0
	v_and_b32_e32 v0, 0xffff0000, v177
	v_mul_f32_e32 v0, 0xbfb8aa3b, v0
	v_exp_f32_e32 v0, v0
	v_and_b32_e32 v177, 0xffff0000, v173
	v_add_f32_e32 v0, 1.0, v0
	v_rcp_f32_e32 v175, v0
	v_lshlrev_b32_e32 v0, 16, v166
	v_mul_f32_e32 v0, 0xbfb8aa3b, v0
	v_exp_f32_e32 v0, v0
	v_pk_fma_f32 v[174:175], v[108:109], v[174:175], v[176:177]
	v_add_f32_e32 v0, 1.0, v0
	v_cvt_pk_bf16_f32 v173, v174, v175
	s_waitcnt lgkmcnt(0)
	global_store_dwordx4 v[224:225], v[244:247], off offset:256
	v_lshl_add_u64 v[222:223], v[222:223], 0, v[230:231]
	ds_bpermute_b32 v244, v243, v170
	ds_bpermute_b32 v245, v243, v171
	ds_bpermute_b32 v246, v243, v172
	ds_bpermute_b32 v247, v243, v173
	s_nop 1
	v_rcp_f32_e32 v170, v0
	v_and_b32_e32 v0, 0xffff0000, v166
	v_mul_f32_e32 v0, 0xbfb8aa3b, v0
	v_exp_f32_e32 v0, v0
	v_lshlrev_b32_e32 v172, 16, v162
	v_and_b32_e32 v173, 0xffff0000, v162
	v_add_f32_e32 v0, 1.0, v0
	v_rcp_f32_e32 v171, v0
	v_lshlrev_b32_e32 v0, 16, v167
	v_mul_f32_e32 v0, 0xbfb8aa3b, v0
	v_exp_f32_e32 v0, v0
	v_pk_fma_f32 v[170:171], v[102:103], v[170:171], v[172:173]
	v_add_f32_e32 v0, 1.0, v0
	v_rcp_f32_e32 v166, v0
	v_and_b32_e32 v0, 0xffff0000, v167
	v_mul_f32_e32 v0, 0xbfb8aa3b, v0
	v_exp_f32_e32 v0, v0
	v_cvt_pk_bf16_f32 v162, v170, v171
	v_lshlrev_b32_e32 v170, 16, v163
	v_and_b32_e32 v171, 0xffff0000, v163
	v_add_f32_e32 v0, 1.0, v0
	v_rcp_f32_e32 v167, v0
	v_lshlrev_b32_e32 v0, 16, v168
	v_mul_f32_e32 v0, 0xbfb8aa3b, v0
	v_exp_f32_e32 v0, v0
	v_pk_fma_f32 v[166:167], v[104:105], v[166:167], v[170:171]
	v_lshlrev_b32_e32 v170, 16, v164
	v_cvt_pk_bf16_f32 v163, v166, v167
	v_add_f32_e32 v0, 1.0, v0
	v_rcp_f32_e32 v166, v0
	v_and_b32_e32 v0, 0xffff0000, v168
	v_mul_f32_e32 v0, 0xbfb8aa3b, v0
	v_exp_f32_e32 v0, v0
	v_and_b32_e32 v171, 0xffff0000, v164
	v_lshlrev_b32_e32 v168, 16, v165
	v_add_f32_e32 v0, 1.0, v0
	v_rcp_f32_e32 v167, v0
	v_lshlrev_b32_e32 v0, 16, v169
	v_mul_f32_e32 v0, 0xbfb8aa3b, v0
	v_exp_f32_e32 v0, v0
	v_pk_fma_f32 v[166:167], v[94:95], v[166:167], v[170:171]
	v_add_f32_e32 v0, 1.0, v0
	v_cvt_pk_bf16_f32 v164, v166, v167
	v_rcp_f32_e32 v166, v0
	v_and_b32_e32 v0, 0xffff0000, v169
	v_mul_f32_e32 v0, 0xbfb8aa3b, v0
	v_exp_f32_e32 v0, v0
	v_and_b32_e32 v169, 0xffff0000, v165
	v_add_f32_e32 v0, 1.0, v0
	v_rcp_f32_e32 v167, v0
	v_lshlrev_b32_e32 v0, 16, v158
	v_mul_f32_e32 v0, 0xbfb8aa3b, v0
	v_exp_f32_e32 v0, v0
	v_pk_fma_f32 v[166:167], v[96:97], v[166:167], v[168:169]
	v_add_f32_e32 v0, 1.0, v0
	v_cvt_pk_bf16_f32 v165, v166, v167
	s_waitcnt lgkmcnt(0)
	global_store_dwordx4 v[222:223], v[244:247], off
	s_nop 1
	ds_bpermute_b32 v244, v243, v162
	ds_bpermute_b32 v245, v243, v163
	ds_bpermute_b32 v246, v243, v164
	ds_bpermute_b32 v247, v243, v165
	s_nop 1
	v_rcp_f32_e32 v162, v0
	v_and_b32_e32 v0, 0xffff0000, v158
	v_mul_f32_e32 v0, 0xbfb8aa3b, v0
	v_exp_f32_e32 v0, v0
	v_lshlrev_b32_e32 v164, 16, v154
	v_and_b32_e32 v165, 0xffff0000, v154
	v_add_f32_e32 v0, 1.0, v0
	v_rcp_f32_e32 v163, v0
	v_lshlrev_b32_e32 v0, 16, v159
	v_mul_f32_e32 v0, 0xbfb8aa3b, v0
	v_exp_f32_e32 v0, v0
	v_pk_fma_f32 v[162:163], v[98:99], v[162:163], v[164:165]
	v_add_f32_e32 v0, 1.0, v0
	v_rcp_f32_e32 v158, v0
	v_and_b32_e32 v0, 0xffff0000, v159
	v_mul_f32_e32 v0, 0xbfb8aa3b, v0
	v_exp_f32_e32 v0, v0
	v_cvt_pk_bf16_f32 v154, v162, v163
	v_lshlrev_b32_e32 v162, 16, v155
	v_and_b32_e32 v163, 0xffff0000, v155
	v_add_f32_e32 v0, 1.0, v0
	v_rcp_f32_e32 v159, v0
	v_lshlrev_b32_e32 v0, 16, v160
	v_mul_f32_e32 v0, 0xbfb8aa3b, v0
	v_exp_f32_e32 v0, v0
	v_pk_fma_f32 v[158:159], v[100:101], v[158:159], v[162:163]
	v_lshlrev_b32_e32 v162, 16, v156
	v_cvt_pk_bf16_f32 v155, v158, v159
	v_add_f32_e32 v0, 1.0, v0
	v_rcp_f32_e32 v158, v0
	v_and_b32_e32 v0, 0xffff0000, v160
	v_mul_f32_e32 v0, 0xbfb8aa3b, v0
	v_exp_f32_e32 v0, v0
	v_and_b32_e32 v163, 0xffff0000, v156
	v_lshlrev_b32_e32 v160, 16, v157
	v_add_f32_e32 v0, 1.0, v0
	v_rcp_f32_e32 v159, v0
	v_lshlrev_b32_e32 v0, 16, v161
	v_mul_f32_e32 v0, 0xbfb8aa3b, v0
	v_exp_f32_e32 v0, v0
	v_pk_fma_f32 v[158:159], v[90:91], v[158:159], v[162:163]
	v_add_f32_e32 v0, 1.0, v0
	v_cvt_pk_bf16_f32 v156, v158, v159
	v_rcp_f32_e32 v158, v0
	v_and_b32_e32 v0, 0xffff0000, v161
	v_mul_f32_e32 v0, 0xbfb8aa3b, v0
	v_exp_f32_e32 v0, v0
	v_and_b32_e32 v161, 0xffff0000, v157
	v_add_f32_e32 v0, 1.0, v0
	v_rcp_f32_e32 v159, v0
	v_lshlrev_b32_e32 v0, 16, v150
	v_mul_f32_e32 v0, 0xbfb8aa3b, v0
	v_exp_f32_e32 v0, v0
	v_pk_fma_f32 v[158:159], v[92:93], v[158:159], v[160:161]
	v_add_f32_e32 v0, 1.0, v0
	v_cvt_pk_bf16_f32 v157, v158, v159
	s_waitcnt lgkmcnt(0)
; __device__ __forceinline__ unsigned cvt_pk_bf16(float lo, float hi) { f32x2 v = {lo, hi}; bf16x2_t b = __builtin_convertvector(v, bf16x2_t); return __builtin_bit_cast(unsigned, b); }
; __device__ __forceinline__ float bf_lo(unsigned w) { return __uint_as_float(w << 16); }
; __device__ __forceinline__ float bf_hi(unsigned w) { return __uint_as_float(w & 0xffff0000u); }
; __device__ __forceinline__ float sigm(float v) { return __builtin_amdgcn_rcpf(1.0f + __builtin_amdgcn_exp2f(-1.44269504089f * v)); }
; #define EPI_FENCE asm volatile("" ::: "memory")
; __device__ __forceinline__ void epi_run(const Epi& E, f32x4 (&acc)[2][2][4][2], const Unit& u, int wr, int wc, int fr, int fq) {
;     ...
;     } else if (mode == MODE_YB) {
; #pragma unroll
;         for (int ai = 0; ai < 2; ++ai) { u32x4 g[4][2], c[4][2];
; #pragma unroll
;             for (int m = 0; m < 4; ++m)
; #pragma unroll
;                 for (int bj = 0; bj < 2; ++bj) { const bf16_t* gp = E.Z + (size_t)(row0 + ai * 128 + m * 16) * NIN + 4096 + col0 + bj * 128; g[m][bj] = *(const u32x4*)gp; c[m][bj] = *(const u32x4*)(gp - 1024); }
; #pragma unroll
;             for (int m = 0; m < 4; ++m)
; #pragma unroll
;                 for (int bj = 0; bj < 2; ++bj) { const f32x4 v0 = acc[ai][bj][m][0], v1 = acc[ai][bj][m][1]; const u32x4 gg = g[m][bj], cc = c[m][bj]; u32x4 w;
;                     w.x = cvt_pk_bf16(bf_lo(cc.x) + v0[0] * sigm(bf_lo(gg.x)), bf_hi(cc.x) + v0[1] * sigm(bf_hi(gg.x))); w.y = cvt_pk_bf16(bf_lo(cc.y) + v0[2] * sigm(bf_lo(gg.y)), bf_hi(cc.y) + v0[3] * sigm(bf_hi(gg.y)));
;                     w.z = cvt_pk_bf16(bf_lo(cc.z) + v1[0] * sigm(bf_lo(gg.z)), bf_hi(cc.z) + v1[1] * sigm(bf_hi(gg.z))); w.w = cvt_pk_bf16(bf_lo(cc.w) + v1[2] * sigm(bf_lo(gg.w)), bf_hi(cc.w) + v1[3] * sigm(bf_hi(gg.w)));
;                     *(u32x4*)(E.Z + (size_t)(row0 + ai * 128 + m * 16) * NIN + 4096 + col0 + bj * 128) = w; }
;             EPI_FENCE; }
	global_store_dwordx4 v[222:223], v[244:247], off offset:256
	v_lshl_add_u64 v[220:221], v[220:221], 0, v[230:231]
	ds_bpermute_b32 v244, v243, v154
	ds_bpermute_b32 v245, v243, v155
	ds_bpermute_b32 v246, v243, v156
	ds_bpermute_b32 v247, v243, v157
	s_nop 1
	v_rcp_f32_e32 v154, v0
	v_and_b32_e32 v0, 0xffff0000, v150
	v_mul_f32_e32 v0, 0xbfb8aa3b, v0
	v_exp_f32_e32 v0, v0
	v_lshlrev_b32_e32 v156, 16, v146
	v_and_b32_e32 v157, 0xffff0000, v146
	v_add_f32_e32 v0, 1.0, v0
	v_rcp_f32_e32 v155, v0
	v_lshlrev_b32_e32 v0, 16, v151
	v_mul_f32_e32 v0, 0xbfb8aa3b, v0
	v_exp_f32_e32 v0, v0
	v_pk_fma_f32 v[154:155], v[86:87], v[154:155], v[156:157]
	v_add_f32_e32 v0, 1.0, v0
	v_rcp_f32_e32 v150, v0
	v_and_b32_e32 v0, 0xffff0000, v151
	v_mul_f32_e32 v0, 0xbfb8aa3b, v0
	v_exp_f32_e32 v0, v0
	v_cvt_pk_bf16_f32 v146, v154, v155
	v_lshlrev_b32_e32 v154, 16, v147
	v_and_b32_e32 v155, 0xffff0000, v147
	v_add_f32_e32 v0, 1.0, v0
	v_rcp_f32_e32 v151, v0
	v_lshlrev_b32_e32 v0, 16, v152
	v_mul_f32_e32 v0, 0xbfb8aa3b, v0
	v_exp_f32_e32 v0, v0
	v_pk_fma_f32 v[150:151], v[88:89], v[150:151], v[154:155]
	v_lshlrev_b32_e32 v154, 16, v148
	v_cvt_pk_bf16_f32 v147, v150, v151
	v_add_f32_e32 v0, 1.0, v0
	v_rcp_f32_e32 v150, v0
	v_and_b32_e32 v0, 0xffff0000, v152
	v_mul_f32_e32 v0, 0xbfb8aa3b, v0
	v_exp_f32_e32 v0, v0
	v_and_b32_e32 v155, 0xffff0000, v148
	v_lshlrev_b32_e32 v152, 16, v149
	v_add_f32_e32 v0, 1.0, v0
	v_rcp_f32_e32 v151, v0
	v_lshlrev_b32_e32 v0, 16, v153
	v_mul_f32_e32 v0, 0xbfb8aa3b, v0
	v_exp_f32_e32 v0, v0
	v_pk_fma_f32 v[150:151], v[78:79], v[150:151], v[154:155]
	v_add_f32_e32 v0, 1.0, v0
	v_cvt_pk_bf16_f32 v148, v150, v151
	v_rcp_f32_e32 v150, v0
	v_and_b32_e32 v0, 0xffff0000, v153
	v_mul_f32_e32 v0, 0xbfb8aa3b, v0
	v_exp_f32_e32 v0, v0
	v_and_b32_e32 v153, 0xffff0000, v149
	v_add_f32_e32 v0, 1.0, v0
	v_rcp_f32_e32 v151, v0
	v_lshlrev_b32_e32 v0, 16, v138
	v_mul_f32_e32 v0, 0xbfb8aa3b, v0
	v_exp_f32_e32 v0, v0
	v_pk_fma_f32 v[150:151], v[80:81], v[150:151], v[152:153]
	v_add_f32_e32 v0, 1.0, v0
	v_cvt_pk_bf16_f32 v149, v150, v151
	s_waitcnt lgkmcnt(0)
	global_store_dwordx4 v[220:221], v[244:247], off
	s_nop 1
	ds_bpermute_b32 v244, v243, v146
	ds_bpermute_b32 v245, v243, v147
	ds_bpermute_b32 v246, v243, v148
	ds_bpermute_b32 v247, v243, v149
	s_nop 1
	v_rcp_f32_e32 v146, v0
	v_and_b32_e32 v0, 0xffff0000, v138
	v_mul_f32_e32 v0, 0xbfb8aa3b, v0
	v_exp_f32_e32 v0, v0
	v_lshlrev_b32_e32 v148, 16, v142
	v_and_b32_e32 v149, 0xffff0000, v142
	v_lshlrev_b32_e32 v142, 16, v143
	v_add_f32_e32 v0, 1.0, v0
	v_rcp_f32_e32 v147, v0
	v_lshlrev_b32_e32 v0, 16, v139
	v_mul_f32_e32 v0, 0xbfb8aa3b, v0
	v_exp_f32_e32 v0, v0
	v_pk_fma_f32 v[146:147], v[82:83], v[146:147], v[148:149]
	v_and_b32_e32 v143, 0xffff0000, v143
	v_cvt_pk_bf16_f32 v138, v146, v147
	v_add_f32_e32 v0, 1.0, v0
	v_rcp_f32_e32 v146, v0
	v_and_b32_e32 v0, 0xffff0000, v139
	v_mul_f32_e32 v0, 0xbfb8aa3b, v0
	v_exp_f32_e32 v0, v0
	s_nop 0
	v_add_f32_e32 v0, 1.0, v0
	v_rcp_f32_e32 v147, v0
	v_lshlrev_b32_e32 v0, 16, v140
	v_mul_f32_e32 v0, 0xbfb8aa3b, v0
	v_exp_f32_e32 v0, v0
	v_pk_fma_f32 v[142:143], v[84:85], v[146:147], v[142:143]
	v_lshlrev_b32_e32 v146, 16, v144
	v_cvt_pk_bf16_f32 v139, v142, v143
	v_add_f32_e32 v0, 1.0, v0
	v_rcp_f32_e32 v142, v0
	v_and_b32_e32 v0, 0xffff0000, v140
	v_mul_f32_e32 v0, 0xbfb8aa3b, v0
	v_exp_f32_e32 v0, v0
	v_and_b32_e32 v147, 0xffff0000, v144
	v_lshlrev_b32_e32 v144, 16, v145
	v_and_b32_e32 v145, 0xffff0000, v145
	v_add_f32_e32 v0, 1.0, v0
	v_rcp_f32_e32 v143, v0
	v_lshlrev_b32_e32 v0, 16, v141
	v_mul_f32_e32 v0, 0xbfb8aa3b, v0
	v_exp_f32_e32 v0, v0
	v_pk_fma_f32 v[142:143], v[74:75], v[142:143], v[146:147]
	v_add_f32_e32 v0, 1.0, v0
	v_cvt_pk_bf16_f32 v140, v142, v143
	v_rcp_f32_e32 v142, v0
	v_and_b32_e32 v0, 0xffff0000, v141
	v_mul_f32_e32 v0, 0xbfb8aa3b, v0
	v_exp_f32_e32 v0, v0
	s_nop 0
	v_add_f32_e32 v0, 1.0, v0
	v_rcp_f32_e32 v143, v0
	v_lshlrev_b32_e32 v0, 16, v134
	v_mul_f32_e32 v0, 0xbfb8aa3b, v0
	v_exp_f32_e32 v0, v0
	v_pk_fma_f32 v[142:143], v[76:77], v[142:143], v[144:145]
	v_add_f32_e32 v0, 1.0, v0
	v_cvt_pk_bf16_f32 v141, v142, v143
	s_waitcnt lgkmcnt(0)
	global_store_dwordx4 v[220:221], v[244:247], off offset:256
	v_lshl_add_u64 v[218:219], v[218:219], 0, v[230:231]
	ds_bpermute_b32 v244, v243, v138
	ds_bpermute_b32 v245, v243, v139
	ds_bpermute_b32 v246, v243, v140
	ds_bpermute_b32 v247, v243, v141
	s_nop 1
	v_rcp_f32_e32 v138, v0
	v_and_b32_e32 v0, 0xffff0000, v134
	v_mul_f32_e32 v0, 0xbfb8aa3b, v0
	v_exp_f32_e32 v0, v0
	v_lshlrev_b32_e32 v140, 16, v130
	v_and_b32_e32 v141, 0xffff0000, v130
	v_add_f32_e32 v0, 1.0, v0
	v_rcp_f32_e32 v139, v0
	v_lshlrev_b32_e32 v0, 16, v135
	v_mul_f32_e32 v0, 0xbfb8aa3b, v0
	v_exp_f32_e32 v0, v0
	v_pk_fma_f32 v[138:139], v[70:71], v[138:139], v[140:141]
	v_add_f32_e32 v0, 1.0, v0
	v_rcp_f32_e32 v134, v0
	v_and_b32_e32 v0, 0xffff0000, v135
	v_mul_f32_e32 v0, 0xbfb8aa3b, v0
	v_exp_f32_e32 v0, v0
	v_cvt_pk_bf16_f32 v130, v138, v139
	v_lshlrev_b32_e32 v138, 16, v131
	v_and_b32_e32 v139, 0xffff0000, v131
	v_add_f32_e32 v0, 1.0, v0
	v_rcp_f32_e32 v135, v0
	v_lshlrev_b32_e32 v0, 16, v136
	v_mul_f32_e32 v0, 0xbfb8aa3b, v0
	v_exp_f32_e32 v0, v0
	v_pk_fma_f32 v[134:135], v[72:73], v[134:135], v[138:139]
	v_lshlrev_b32_e32 v138, 16, v132
	v_cvt_pk_bf16_f32 v131, v134, v135
	v_add_f32_e32 v0, 1.0, v0
	v_rcp_f32_e32 v134, v0
	v_and_b32_e32 v0, 0xffff0000, v136
	v_mul_f32_e32 v0, 0xbfb8aa3b, v0
	v_exp_f32_e32 v0, v0
	v_and_b32_e32 v139, 0xffff0000, v132
	v_lshlrev_b32_e32 v136, 16, v133
	v_add_f32_e32 v0, 1.0, v0
	v_rcp_f32_e32 v135, v0
	v_lshlrev_b32_e32 v0, 16, v137
	v_mul_f32_e32 v0, 0xbfb8aa3b, v0
	v_exp_f32_e32 v0, v0
	v_pk_fma_f32 v[134:135], v[66:67], v[134:135], v[138:139]
	v_add_f32_e32 v0, 1.0, v0
	v_cvt_pk_bf16_f32 v132, v134, v135
	v_rcp_f32_e32 v134, v0
	v_and_b32_e32 v0, 0xffff0000, v137
	v_mul_f32_e32 v0, 0xbfb8aa3b, v0
	v_exp_f32_e32 v0, v0
	v_and_b32_e32 v137, 0xffff0000, v133
	v_add_f32_e32 v0, 1.0, v0
	v_rcp_f32_e32 v135, v0
	v_add_u32_e32 v0, 0x80, v210
	v_pk_fma_f32 v[134:135], v[68:69], v[134:135], v[136:137]
	s_nop 0
	v_cvt_pk_bf16_f32 v133, v134, v135
	s_waitcnt lgkmcnt(0)
; __device__ __forceinline__ unsigned cvt_pk_bf16(float lo, float hi) { f32x2 v = {lo, hi}; bf16x2_t b = __builtin_convertvector(v, bf16x2_t); return __builtin_bit_cast(unsigned, b); }
; __device__ __forceinline__ float bf_lo(unsigned w) { return __uint_as_float(w << 16); }
; __device__ __forceinline__ float bf_hi(unsigned w) { return __uint_as_float(w & 0xffff0000u); }
; __device__ __forceinline__ float sigm(float v) { return __builtin_amdgcn_rcpf(1.0f + __builtin_amdgcn_exp2f(-1.44269504089f * v)); }
; #define EPI_FENCE asm volatile("" ::: "memory")
; __device__ __forceinline__ void epi_run(const Epi& E, f32x4 (&acc)[2][2][4][2], const Unit& u, int wr, int wc, int fr, int fq) {
;     ...
;     } else if (mode == MODE_YB) {
; #pragma unroll
;         for (int ai = 0; ai < 2; ++ai) { u32x4 g[4][2], c[4][2];
; #pragma unroll
;             for (int m = 0; m < 4; ++m)
; #pragma unroll
;                 for (int bj = 0; bj < 2; ++bj) { const bf16_t* gp = E.Z + (size_t)(row0 + ai * 128 + m * 16) * NIN + 4096 + col0 + bj * 128; g[m][bj] = *(const u32x4*)gp; c[m][bj] = *(const u32x4*)(gp - 1024); }
; #pragma unroll
;             for (int m = 0; m < 4; ++m)
; #pragma unroll
;                 for (int bj = 0; bj < 2; ++bj) { const f32x4 v0 = acc[ai][bj][m][0], v1 = acc[ai][bj][m][1]; const u32x4 gg = g[m][bj], cc = c[m][bj]; u32x4 w;
;                     w.x = cvt_pk_bf16(bf_lo(cc.x) + v0[0] * sigm(bf_lo(gg.x)), bf_hi(cc.x) + v0[1] * sigm(bf_hi(gg.x))); w.y = cvt_pk_bf16(bf_lo(cc.y) + v0[2] * sigm(bf_lo(gg.y)), bf_hi(cc.y) + v0[3] * sigm(bf_hi(gg.y)));
;                     w.z = cvt_pk_bf16(bf_lo(cc.z) + v1[0] * sigm(bf_lo(gg.z)), bf_hi(cc.z) + v1[1] * sigm(bf_hi(gg.z))); w.w = cvt_pk_bf16(bf_lo(cc.w) + v1[2] * sigm(bf_lo(gg.w)), bf_hi(cc.w) + v1[3] * sigm(bf_hi(gg.w)));
;                     *(u32x4*)(E.Z + (size_t)(row0 + ai * 128 + m * 16) * NIN + 4096 + col0 + bj * 128) = w; }
;             EPI_FENCE; }
	global_store_dwordx4 v[218:219], v[244:247], off
	s_nop 1
	ds_bpermute_b32 v244, v243, v130
	ds_bpermute_b32 v245, v243, v131
	ds_bpermute_b32 v246, v243, v132
	ds_bpermute_b32 v247, v243, v133
	s_nop 1
	v_mad_i64_i32 v[130:131], s[8:9], v0, s69, v[214:215]
	v_lshl_add_u64 v[130:131], v[130:131], 0, v[216:217]
	v_add_co_u32_e32 v192, vcc, s3, v130
	v_lshl_add_u64 v[132:133], v[130:131], 0, s[20:21]
	s_nop 0
	v_addc_co_u32_e32 v193, vcc, 0, v131, vcc
	s_waitcnt lgkmcnt(0)
	global_store_dwordx4 v[218:219], v[244:247], off offset:256
	global_load_dwordx4 v[218:221], v[192:193], off
	global_load_dwordx4 v[222:225], v[132:133], off offset:-2048
	global_load_dwordx4 v[182:185], v[132:133], off offset:256
	global_load_dwordx4 v[178:181], v[132:133], off offset:-1792
	v_add_u32_e32 v0, 0x90, v210
	v_mad_i64_i32 v[130:131], s[8:9], v0, s69, v[214:215]
	v_lshl_add_u64 v[130:131], v[130:131], 0, v[216:217]
	v_add_co_u32_e32 v190, vcc, s3, v130
	v_add_u32_e32 v0, 0xa0, v210
	v_lshl_add_u64 v[132:133], v[130:131], 0, s[20:21]
	v_addc_co_u32_e32 v191, vcc, 0, v131, vcc
	v_mad_i64_i32 v[130:131], s[8:9], v0, s69, v[214:215]
	v_lshl_add_u64 v[130:131], v[130:131], 0, v[216:217]
	v_add_co_u32_e32 v188, vcc, s3, v130
	v_add_u32_e32 v0, 0xb0, v210
	global_load_dwordx4 v[174:177], v[190:191], off
	global_load_dwordx4 v[170:173], v[132:133], off offset:-2048
	global_load_dwordx4 v[166:169], v[132:133], off offset:256
	global_load_dwordx4 v[162:165], v[132:133], off offset:-1792
	v_lshl_add_u64 v[132:133], v[130:131], 0, s[20:21]
	v_addc_co_u32_e32 v189, vcc, 0, v131, vcc
	v_mad_i64_i32 v[130:131], s[8:9], v0, s69, v[214:215]
	v_lshl_add_u64 v[130:131], v[130:131], 0, v[216:217]
	v_add_co_u32_e32 v186, vcc, s3, v130
	global_load_dwordx4 v[158:161], v[188:189], off
	global_load_dwordx4 v[154:157], v[132:133], off offset:-2048
	global_load_dwordx4 v[150:153], v[132:133], off offset:256
	global_load_dwordx4 v[146:149], v[132:133], off offset:-1792
	v_lshl_add_u64 v[132:133], v[130:131], 0, s[20:21]
	v_addc_co_u32_e32 v187, vcc, 0, v131, vcc
	global_load_dwordx4 v[142:145], v[186:187], off
	global_load_dwordx4 v[138:141], v[132:133], off offset:-2048
	global_load_dwordx4 v[134:137], v[132:133], off offset:256
	s_nop 0
	global_load_dwordx4 v[130:133], v[132:133], off offset:-1792
	s_mov_b64 s[8:9], 0
	s_waitcnt vmcnt(15)
	v_lshlrev_b32_e32 v0, 16, v218
	v_mul_f32_e32 v0, 0xbfb8aa3b, v0
	v_exp_f32_e32 v0, v0
	s_waitcnt vmcnt(14)
	v_lshlrev_b32_e32 v216, 16, v222
	v_and_b32_e32 v217, 0xffff0000, v222
	v_add_f32_e32 v0, 1.0, v0
	v_rcp_f32_e32 v214, v0
	v_and_b32_e32 v0, 0xffff0000, v218
	v_mul_f32_e32 v0, 0xbfb8aa3b, v0
	v_exp_f32_e32 v0, v0
	v_lshlrev_b32_e32 v218, 16, v223
	v_add_f32_e32 v0, 1.0, v0
	v_rcp_f32_e32 v215, v0
	v_lshlrev_b32_e32 v0, 16, v219
	v_mul_f32_e32 v0, 0xbfb8aa3b, v0
	v_exp_f32_e32 v0, v0
	v_pk_fma_f32 v[214:215], v[62:63], v[214:215], v[216:217]
	v_add_f32_e32 v0, 1.0, v0
	v_rcp_f32_e32 v216, v0
	v_and_b32_e32 v0, 0xffff0000, v219
	v_mul_f32_e32 v0, 0xbfb8aa3b, v0
	v_exp_f32_e32 v0, v0
	v_and_b32_e32 v219, 0xffff0000, v223
	v_cvt_pk_bf16_f32 v214, v214, v215
	v_add_f32_e32 v0, 1.0, v0
	v_rcp_f32_e32 v217, v0
	v_lshlrev_b32_e32 v0, 16, v220
	v_mul_f32_e32 v0, 0xbfb8aa3b, v0
	v_exp_f32_e32 v0, v0
	v_pk_fma_f32 v[216:217], v[64:65], v[216:217], v[218:219]
	v_lshlrev_b32_e32 v218, 16, v224
	v_cvt_pk_bf16_f32 v215, v216, v217
	v_add_f32_e32 v0, 1.0, v0
	v_rcp_f32_e32 v216, v0
	v_and_b32_e32 v0, 0xffff0000, v220
	v_mul_f32_e32 v0, 0xbfb8aa3b, v0
	v_exp_f32_e32 v0, v0
	v_and_b32_e32 v219, 0xffff0000, v224
	v_lshlrev_b32_e32 v220, 16, v225
	v_add_f32_e32 v0, 1.0, v0
	v_rcp_f32_e32 v217, v0
	v_lshlrev_b32_e32 v0, 16, v221
	v_mul_f32_e32 v0, 0xbfb8aa3b, v0
	v_exp_f32_e32 v0, v0
	v_pk_fma_f32 v[216:217], v[58:59], v[216:217], v[218:219]
	v_add_f32_e32 v0, 1.0, v0
	v_rcp_f32_e32 v218, v0
	v_and_b32_e32 v0, 0xffff0000, v221
	v_mul_f32_e32 v0, 0xbfb8aa3b, v0
	v_exp_f32_e32 v0, v0
	v_and_b32_e32 v221, 0xffff0000, v225
	v_cvt_pk_bf16_f32 v216, v216, v217
	v_add_f32_e32 v0, 1.0, v0
	v_rcp_f32_e32 v219, v0
	s_waitcnt vmcnt(13)
	v_lshlrev_b32_e32 v0, 16, v182
	v_mul_f32_e32 v0, 0xbfb8aa3b, v0
	v_exp_f32_e32 v0, v0
	v_pk_fma_f32 v[218:219], v[60:61], v[218:219], v[220:221]
	v_add_f32_e32 v0, 1.0, v0
	v_cvt_pk_bf16_f32 v217, v218, v219
	v_lshl_add_u64 v[192:193], v[192:193], 0, v[230:231]
	ds_bpermute_b32 v244, v243, v214
	ds_bpermute_b32 v245, v243, v215
	ds_bpermute_b32 v246, v243, v216
	ds_bpermute_b32 v247, v243, v217
	s_nop 1
	v_rcp_f32_e32 v214, v0
	v_and_b32_e32 v0, 0xffff0000, v182
	v_mul_f32_e32 v0, 0xbfb8aa3b, v0
	v_exp_f32_e32 v0, v0
	s_waitcnt lgkmcnt(0)
	global_store_dwordx4 v[192:193], v[244:247], off
	s_waitcnt vmcnt(13)
	v_lshlrev_b32_e32 v216, 16, v178
	v_and_b32_e32 v217, 0xffff0000, v178
	v_add_f32_e32 v0, 1.0, v0
	v_rcp_f32_e32 v215, v0
	v_lshlrev_b32_e32 v0, 16, v183
	v_mul_f32_e32 v0, 0xbfb8aa3b, v0
	v_exp_f32_e32 v0, v0
	v_pk_fma_f32 v[214:215], v[54:55], v[214:215], v[216:217]
	v_add_f32_e32 v0, 1.0, v0
	v_rcp_f32_e32 v182, v0
	v_and_b32_e32 v0, 0xffff0000, v183
	v_mul_f32_e32 v0, 0xbfb8aa3b, v0
	v_exp_f32_e32 v0, v0
	v_cvt_pk_bf16_f32 v178, v214, v215
	v_lshlrev_b32_e32 v214, 16, v179
	v_and_b32_e32 v215, 0xffff0000, v179
	v_add_f32_e32 v0, 1.0, v0
	v_rcp_f32_e32 v183, v0
	v_lshlrev_b32_e32 v0, 16, v184
	v_mul_f32_e32 v0, 0xbfb8aa3b, v0
	v_exp_f32_e32 v0, v0
	v_pk_fma_f32 v[182:183], v[56:57], v[182:183], v[214:215]
	v_lshlrev_b32_e32 v214, 16, v180
	v_cvt_pk_bf16_f32 v179, v182, v183
	v_add_f32_e32 v0, 1.0, v0
	v_rcp_f32_e32 v182, v0
	v_and_b32_e32 v0, 0xffff0000, v184
	v_mul_f32_e32 v0, 0xbfb8aa3b, v0
	v_exp_f32_e32 v0, v0
	v_and_b32_e32 v215, 0xffff0000, v180
	v_lshlrev_b32_e32 v184, 16, v181
	v_add_f32_e32 v0, 1.0, v0
	v_rcp_f32_e32 v183, v0
	v_lshlrev_b32_e32 v0, 16, v185
	v_mul_f32_e32 v0, 0xbfb8aa3b, v0
	v_exp_f32_e32 v0, v0
	v_pk_fma_f32 v[182:183], v[50:51], v[182:183], v[214:215]
	v_add_f32_e32 v0, 1.0, v0
	v_cvt_pk_bf16_f32 v180, v182, v183
	v_rcp_f32_e32 v182, v0
	v_and_b32_e32 v0, 0xffff0000, v185
	v_mul_f32_e32 v0, 0xbfb8aa3b, v0
	v_exp_f32_e32 v0, v0
	v_and_b32_e32 v185, 0xffff0000, v181
	v_add_f32_e32 v0, 1.0, v0
	v_rcp_f32_e32 v183, v0
	s_waitcnt vmcnt(12)
; __device__ __forceinline__ unsigned cvt_pk_bf16(float lo, float hi) { f32x2 v = {lo, hi}; bf16x2_t b = __builtin_convertvector(v, bf16x2_t); return __builtin_bit_cast(unsigned, b); }
; __device__ __forceinline__ float bf_lo(unsigned w) { return __uint_as_float(w << 16); }
; __device__ __forceinline__ float bf_hi(unsigned w) { return __uint_as_float(w & 0xffff0000u); }
; __device__ __forceinline__ float sigm(float v) { return __builtin_amdgcn_rcpf(1.0f + __builtin_amdgcn_exp2f(-1.44269504089f * v)); }
; #define EPI_FENCE asm volatile("" ::: "memory")
; __device__ __forceinline__ void epi_run(const Epi& E, f32x4 (&acc)[2][2][4][2], const Unit& u, int wr, int wc, int fr, int fq) {
;     ...
;     } else if (mode == MODE_YB) {
; #pragma unroll
;         for (int ai = 0; ai < 2; ++ai) { u32x4 g[4][2], c[4][2];
; #pragma unroll
;             for (int m = 0; m < 4; ++m)
; #pragma unroll
;                 for (int bj = 0; bj < 2; ++bj) { const bf16_t* gp = E.Z + (size_t)(row0 + ai * 128 + m * 16) * NIN + 4096 + col0 + bj * 128; g[m][bj] = *(const u32x4*)gp; c[m][bj] = *(const u32x4*)(gp - 1024); }
; #pragma unroll
;             for (int m = 0; m < 4; ++m)
; #pragma unroll
;                 for (int bj = 0; bj < 2; ++bj) { const f32x4 v0 = acc[ai][bj][m][0], v1 = acc[ai][bj][m][1]; const u32x4 gg = g[m][bj], cc = c[m][bj]; u32x4 w;
;                     w.x = cvt_pk_bf16(bf_lo(cc.x) + v0[0] * sigm(bf_lo(gg.x)), bf_hi(cc.x) + v0[1] * sigm(bf_hi(gg.x))); w.y = cvt_pk_bf16(bf_lo(cc.y) + v0[2] * sigm(bf_lo(gg.y)), bf_hi(cc.y) + v0[3] * sigm(bf_hi(gg.y)));
;                     w.z = cvt_pk_bf16(bf_lo(cc.z) + v1[0] * sigm(bf_lo(gg.z)), bf_hi(cc.z) + v1[1] * sigm(bf_hi(gg.z))); w.w = cvt_pk_bf16(bf_lo(cc.w) + v1[2] * sigm(bf_lo(gg.w)), bf_hi(cc.w) + v1[3] * sigm(bf_hi(gg.w)));
;                     *(u32x4*)(E.Z + (size_t)(row0 + ai * 128 + m * 16) * NIN + 4096 + col0 + bj * 128) = w; }
;             EPI_FENCE; }
	v_lshlrev_b32_e32 v0, 16, v174
	v_mul_f32_e32 v0, 0xbfb8aa3b, v0
	v_exp_f32_e32 v0, v0
	v_pk_fma_f32 v[182:183], v[52:53], v[182:183], v[184:185]
	v_add_f32_e32 v0, 1.0, v0
	v_cvt_pk_bf16_f32 v181, v182, v183
	s_nop 1
	ds_bpermute_b32 v244, v243, v178
	ds_bpermute_b32 v245, v243, v179
	ds_bpermute_b32 v246, v243, v180
	ds_bpermute_b32 v247, v243, v181
	s_nop 1
	v_rcp_f32_e32 v178, v0
	v_and_b32_e32 v0, 0xffff0000, v174
	v_mul_f32_e32 v0, 0xbfb8aa3b, v0
	v_exp_f32_e32 v0, v0
	s_waitcnt lgkmcnt(0)
	global_store_dwordx4 v[192:193], v[244:247], off offset:256
	s_waitcnt vmcnt(12)
	v_lshlrev_b32_e32 v180, 16, v170
	v_and_b32_e32 v181, 0xffff0000, v170
	v_add_f32_e32 v0, 1.0, v0
	v_rcp_f32_e32 v179, v0
	v_lshlrev_b32_e32 v0, 16, v175
	v_mul_f32_e32 v0, 0xbfb8aa3b, v0
	v_exp_f32_e32 v0, v0
	v_pk_fma_f32 v[178:179], v[46:47], v[178:179], v[180:181]
	v_add_f32_e32 v0, 1.0, v0
	v_rcp_f32_e32 v174, v0
	v_and_b32_e32 v0, 0xffff0000, v175
	v_mul_f32_e32 v0, 0xbfb8aa3b, v0
	v_exp_f32_e32 v0, v0
	v_cvt_pk_bf16_f32 v170, v178, v179
	v_lshlrev_b32_e32 v178, 16, v171
	v_and_b32_e32 v179, 0xffff0000, v171
	v_add_f32_e32 v0, 1.0, v0
	v_rcp_f32_e32 v175, v0
	v_lshlrev_b32_e32 v0, 16, v176
	v_mul_f32_e32 v0, 0xbfb8aa3b, v0
	v_exp_f32_e32 v0, v0
	v_pk_fma_f32 v[174:175], v[48:49], v[174:175], v[178:179]
	v_lshlrev_b32_e32 v178, 16, v172
	v_cvt_pk_bf16_f32 v171, v174, v175
	v_add_f32_e32 v0, 1.0, v0
	v_rcp_f32_e32 v174, v0
	v_and_b32_e32 v0, 0xffff0000, v176
	v_mul_f32_e32 v0, 0xbfb8aa3b, v0
	v_exp_f32_e32 v0, v0
	v_and_b32_e32 v179, 0xffff0000, v172
	v_lshlrev_b32_e32 v176, 16, v173
	v_add_f32_e32 v0, 1.0, v0
	v_rcp_f32_e32 v175, v0
	v_lshlrev_b32_e32 v0, 16, v177
	v_mul_f32_e32 v0, 0xbfb8aa3b, v0
	v_exp_f32_e32 v0, v0
	v_pk_fma_f32 v[174:175], v[42:43], v[174:175], v[178:179]
	v_add_f32_e32 v0, 1.0, v0
	v_cvt_pk_bf16_f32 v172, v174, v175
	v_rcp_f32_e32 v174, v0
	v_and_b32_e32 v0, 0xffff0000, v177
	v_mul_f32_e32 v0, 0xbfb8aa3b, v0
	v_exp_f32_e32 v0, v0
	v_and_b32_e32 v177, 0xffff0000, v173
	v_add_f32_e32 v0, 1.0, v0
	v_rcp_f32_e32 v175, v0
	s_waitcnt vmcnt(11)
	v_lshlrev_b32_e32 v0, 16, v166
	v_mul_f32_e32 v0, 0xbfb8aa3b, v0
	v_exp_f32_e32 v0, v0
	v_pk_fma_f32 v[174:175], v[44:45], v[174:175], v[176:177]
	v_add_f32_e32 v0, 1.0, v0
	v_cvt_pk_bf16_f32 v173, v174, v175
	v_lshl_add_u64 v[190:191], v[190:191], 0, v[230:231]
	ds_bpermute_b32 v244, v243, v170
	ds_bpermute_b32 v245, v243, v171
	ds_bpermute_b32 v246, v243, v172
	ds_bpermute_b32 v247, v243, v173
	s_nop 1
	v_rcp_f32_e32 v170, v0
	v_and_b32_e32 v0, 0xffff0000, v166
	v_mul_f32_e32 v0, 0xbfb8aa3b, v0
	v_exp_f32_e32 v0, v0
	s_waitcnt lgkmcnt(0)
	global_store_dwordx4 v[190:191], v[244:247], off
	s_waitcnt vmcnt(11)
	v_lshlrev_b32_e32 v172, 16, v162
	v_and_b32_e32 v173, 0xffff0000, v162
	v_add_f32_e32 v0, 1.0, v0
	v_rcp_f32_e32 v171, v0
	v_lshlrev_b32_e32 v0, 16, v167
	v_mul_f32_e32 v0, 0xbfb8aa3b, v0
	v_exp_f32_e32 v0, v0
	v_pk_fma_f32 v[170:171], v[38:39], v[170:171], v[172:173]
	v_add_f32_e32 v0, 1.0, v0
	v_rcp_f32_e32 v166, v0
	v_and_b32_e32 v0, 0xffff0000, v167
	v_mul_f32_e32 v0, 0xbfb8aa3b, v0
	v_exp_f32_e32 v0, v0
	v_cvt_pk_bf16_f32 v162, v170, v171
	v_lshlrev_b32_e32 v170, 16, v163
	v_and_b32_e32 v171, 0xffff0000, v163
	v_add_f32_e32 v0, 1.0, v0
	v_rcp_f32_e32 v167, v0
	v_lshlrev_b32_e32 v0, 16, v168
	v_mul_f32_e32 v0, 0xbfb8aa3b, v0
	v_exp_f32_e32 v0, v0
	v_pk_fma_f32 v[166:167], v[40:41], v[166:167], v[170:171]
	v_lshlrev_b32_e32 v170, 16, v164
	v_cvt_pk_bf16_f32 v163, v166, v167
	v_add_f32_e32 v0, 1.0, v0
	v_rcp_f32_e32 v166, v0
	v_and_b32_e32 v0, 0xffff0000, v168
	v_mul_f32_e32 v0, 0xbfb8aa3b, v0
	v_exp_f32_e32 v0, v0
	v_and_b32_e32 v171, 0xffff0000, v164
	v_lshlrev_b32_e32 v168, 16, v165
	v_add_f32_e32 v0, 1.0, v0
	v_rcp_f32_e32 v167, v0
	v_lshlrev_b32_e32 v0, 16, v169
	v_mul_f32_e32 v0, 0xbfb8aa3b, v0
	v_exp_f32_e32 v0, v0
	v_pk_fma_f32 v[166:167], v[34:35], v[166:167], v[170:171]
	v_add_f32_e32 v0, 1.0, v0
	v_cvt_pk_bf16_f32 v164, v166, v167
	v_rcp_f32_e32 v166, v0
	v_and_b32_e32 v0, 0xffff0000, v169
	v_mul_f32_e32 v0, 0xbfb8aa3b, v0
	v_exp_f32_e32 v0, v0
	v_and_b32_e32 v169, 0xffff0000, v165
	v_add_f32_e32 v0, 1.0, v0
	v_rcp_f32_e32 v167, v0
	s_waitcnt vmcnt(10)
	v_lshlrev_b32_e32 v0, 16, v158
	v_mul_f32_e32 v0, 0xbfb8aa3b, v0
	v_exp_f32_e32 v0, v0
	v_pk_fma_f32 v[166:167], v[36:37], v[166:167], v[168:169]
	v_add_f32_e32 v0, 1.0, v0
	v_cvt_pk_bf16_f32 v165, v166, v167
	s_nop 1
	ds_bpermute_b32 v244, v243, v162
	ds_bpermute_b32 v245, v243, v163
	ds_bpermute_b32 v246, v243, v164
	ds_bpermute_b32 v247, v243, v165
	s_nop 1
	v_rcp_f32_e32 v162, v0
	v_and_b32_e32 v0, 0xffff0000, v158
	v_mul_f32_e32 v0, 0xbfb8aa3b, v0
	v_exp_f32_e32 v0, v0
	s_waitcnt lgkmcnt(0)
	global_store_dwordx4 v[190:191], v[244:247], off offset:256
	s_waitcnt vmcnt(10)
	v_lshlrev_b32_e32 v164, 16, v154
	v_and_b32_e32 v165, 0xffff0000, v154
	v_add_f32_e32 v0, 1.0, v0
	v_rcp_f32_e32 v163, v0
	v_lshlrev_b32_e32 v0, 16, v159
	v_mul_f32_e32 v0, 0xbfb8aa3b, v0
	v_exp_f32_e32 v0, v0
	v_pk_fma_f32 v[162:163], v[30:31], v[162:163], v[164:165]
	v_add_f32_e32 v0, 1.0, v0
	v_rcp_f32_e32 v158, v0
	v_and_b32_e32 v0, 0xffff0000, v159
	v_mul_f32_e32 v0, 0xbfb8aa3b, v0
	v_exp_f32_e32 v0, v0
	v_cvt_pk_bf16_f32 v154, v162, v163
	v_lshlrev_b32_e32 v162, 16, v155
	v_and_b32_e32 v163, 0xffff0000, v155
	v_add_f32_e32 v0, 1.0, v0
	v_rcp_f32_e32 v159, v0
	v_lshlrev_b32_e32 v0, 16, v160
	v_mul_f32_e32 v0, 0xbfb8aa3b, v0
	v_exp_f32_e32 v0, v0
	v_pk_fma_f32 v[158:159], v[32:33], v[158:159], v[162:163]
	v_lshlrev_b32_e32 v162, 16, v156
	v_cvt_pk_bf16_f32 v155, v158, v159
	v_add_f32_e32 v0, 1.0, v0
	v_rcp_f32_e32 v158, v0
	v_and_b32_e32 v0, 0xffff0000, v160
	v_mul_f32_e32 v0, 0xbfb8aa3b, v0
	v_exp_f32_e32 v0, v0
	v_and_b32_e32 v163, 0xffff0000, v156
	v_lshlrev_b32_e32 v160, 16, v157
	v_add_f32_e32 v0, 1.0, v0
	v_rcp_f32_e32 v159, v0
	v_lshlrev_b32_e32 v0, 16, v161
	v_mul_f32_e32 v0, 0xbfb8aa3b, v0
	v_exp_f32_e32 v0, v0
	v_pk_fma_f32 v[158:159], v[26:27], v[158:159], v[162:163]
	v_add_f32_e32 v0, 1.0, v0
	v_cvt_pk_bf16_f32 v156, v158, v159
	v_rcp_f32_e32 v158, v0
	v_and_b32_e32 v0, 0xffff0000, v161
	v_mul_f32_e32 v0, 0xbfb8aa3b, v0
	v_exp_f32_e32 v0, v0
	v_and_b32_e32 v161, 0xffff0000, v157
	v_add_f32_e32 v0, 1.0, v0
	v_rcp_f32_e32 v159, v0
	s_waitcnt vmcnt(9)
; __device__ __forceinline__ unsigned cvt_pk_bf16(float lo, float hi) { f32x2 v = {lo, hi}; bf16x2_t b = __builtin_convertvector(v, bf16x2_t); return __builtin_bit_cast(unsigned, b); }
; __device__ __forceinline__ float bf_lo(unsigned w) { return __uint_as_float(w << 16); }
; __device__ __forceinline__ float bf_hi(unsigned w) { return __uint_as_float(w & 0xffff0000u); }
; __device__ __forceinline__ float sigm(float v) { return __builtin_amdgcn_rcpf(1.0f + __builtin_amdgcn_exp2f(-1.44269504089f * v)); }
; #define EPI_FENCE asm volatile("" ::: "memory")
; __device__ __forceinline__ void epi_run(const Epi& E, f32x4 (&acc)[2][2][4][2], const Unit& u, int wr, int wc, int fr, int fq) {
;     ...
;     } else if (mode == MODE_YB) {
; #pragma unroll
;         for (int ai = 0; ai < 2; ++ai) { u32x4 g[4][2], c[4][2];
; #pragma unroll
;             for (int m = 0; m < 4; ++m)
; #pragma unroll
;                 for (int bj = 0; bj < 2; ++bj) { const bf16_t* gp = E.Z + (size_t)(row0 + ai * 128 + m * 16) * NIN + 4096 + col0 + bj * 128; g[m][bj] = *(const u32x4*)gp; c[m][bj] = *(const u32x4*)(gp - 1024); }
; #pragma unroll
;             for (int m = 0; m < 4; ++m)
; #pragma unroll
;                 for (int bj = 0; bj < 2; ++bj) { const f32x4 v0 = acc[ai][bj][m][0], v1 = acc[ai][bj][m][1]; const u32x4 gg = g[m][bj], cc = c[m][bj]; u32x4 w;
;                     w.x = cvt_pk_bf16(bf_lo(cc.x) + v0[0] * sigm(bf_lo(gg.x)), bf_hi(cc.x) + v0[1] * sigm(bf_hi(gg.x))); w.y = cvt_pk_bf16(bf_lo(cc.y) + v0[2] * sigm(bf_lo(gg.y)), bf_hi(cc.y) + v0[3] * sigm(bf_hi(gg.y)));
;                     w.z = cvt_pk_bf16(bf_lo(cc.z) + v1[0] * sigm(bf_lo(gg.z)), bf_hi(cc.z) + v1[1] * sigm(bf_hi(gg.z))); w.w = cvt_pk_bf16(bf_lo(cc.w) + v1[2] * sigm(bf_lo(gg.w)), bf_hi(cc.w) + v1[3] * sigm(bf_hi(gg.w)));
;                     *(u32x4*)(E.Z + (size_t)(row0 + ai * 128 + m * 16) * NIN + 4096 + col0 + bj * 128) = w; }
;             EPI_FENCE; }
	v_lshlrev_b32_e32 v0, 16, v150
	v_mul_f32_e32 v0, 0xbfb8aa3b, v0
	v_exp_f32_e32 v0, v0
	v_pk_fma_f32 v[158:159], v[28:29], v[158:159], v[160:161]
	v_add_f32_e32 v0, 1.0, v0
	v_cvt_pk_bf16_f32 v157, v158, v159
	v_lshl_add_u64 v[188:189], v[188:189], 0, v[230:231]
	ds_bpermute_b32 v244, v243, v154
	ds_bpermute_b32 v245, v243, v155
	ds_bpermute_b32 v246, v243, v156
	ds_bpermute_b32 v247, v243, v157
	s_nop 1
	v_rcp_f32_e32 v154, v0
	v_and_b32_e32 v0, 0xffff0000, v150
	v_mul_f32_e32 v0, 0xbfb8aa3b, v0
	v_exp_f32_e32 v0, v0
	s_waitcnt lgkmcnt(0)
	global_store_dwordx4 v[188:189], v[244:247], off
	s_waitcnt vmcnt(9)
	v_lshlrev_b32_e32 v156, 16, v146
	v_and_b32_e32 v157, 0xffff0000, v146
	v_add_f32_e32 v0, 1.0, v0
	v_rcp_f32_e32 v155, v0
	v_lshlrev_b32_e32 v0, 16, v151
	v_mul_f32_e32 v0, 0xbfb8aa3b, v0
	v_exp_f32_e32 v0, v0
	v_pk_fma_f32 v[154:155], v[22:23], v[154:155], v[156:157]
	v_add_f32_e32 v0, 1.0, v0
	v_rcp_f32_e32 v150, v0
	v_and_b32_e32 v0, 0xffff0000, v151
	v_mul_f32_e32 v0, 0xbfb8aa3b, v0
	v_exp_f32_e32 v0, v0
	v_cvt_pk_bf16_f32 v146, v154, v155
	v_lshlrev_b32_e32 v154, 16, v147
	v_and_b32_e32 v155, 0xffff0000, v147
	v_add_f32_e32 v0, 1.0, v0
	v_rcp_f32_e32 v151, v0
	v_lshlrev_b32_e32 v0, 16, v152
	v_mul_f32_e32 v0, 0xbfb8aa3b, v0
	v_exp_f32_e32 v0, v0
	v_pk_fma_f32 v[150:151], v[24:25], v[150:151], v[154:155]
	v_lshlrev_b32_e32 v154, 16, v148
	v_cvt_pk_bf16_f32 v147, v150, v151
	v_add_f32_e32 v0, 1.0, v0
	v_rcp_f32_e32 v150, v0
	v_and_b32_e32 v0, 0xffff0000, v152
	v_mul_f32_e32 v0, 0xbfb8aa3b, v0
	v_exp_f32_e32 v0, v0
	v_and_b32_e32 v155, 0xffff0000, v148
	v_lshlrev_b32_e32 v152, 16, v149
	v_add_f32_e32 v0, 1.0, v0
	v_rcp_f32_e32 v151, v0
	v_lshlrev_b32_e32 v0, 16, v153
	v_mul_f32_e32 v0, 0xbfb8aa3b, v0
	v_exp_f32_e32 v0, v0
	v_pk_fma_f32 v[150:151], v[18:19], v[150:151], v[154:155]
	v_add_f32_e32 v0, 1.0, v0
	v_cvt_pk_bf16_f32 v148, v150, v151
	v_rcp_f32_e32 v150, v0
	v_and_b32_e32 v0, 0xffff0000, v153
	v_mul_f32_e32 v0, 0xbfb8aa3b, v0
	v_exp_f32_e32 v0, v0
	v_and_b32_e32 v153, 0xffff0000, v149
	v_add_f32_e32 v0, 1.0, v0
	v_rcp_f32_e32 v151, v0
	s_waitcnt vmcnt(8)
	v_lshlrev_b32_e32 v0, 16, v142
	v_mul_f32_e32 v0, 0xbfb8aa3b, v0
	v_exp_f32_e32 v0, v0
	v_pk_fma_f32 v[150:151], v[20:21], v[150:151], v[152:153]
	v_add_f32_e32 v0, 1.0, v0
	v_cvt_pk_bf16_f32 v149, v150, v151
	s_nop 1
	ds_bpermute_b32 v244, v243, v146
	ds_bpermute_b32 v245, v243, v147
	ds_bpermute_b32 v246, v243, v148
	ds_bpermute_b32 v247, v243, v149
	s_nop 1
	v_rcp_f32_e32 v146, v0
	v_and_b32_e32 v0, 0xffff0000, v142
	v_mul_f32_e32 v0, 0xbfb8aa3b, v0
	v_exp_f32_e32 v0, v0
	s_waitcnt lgkmcnt(0)
	global_store_dwordx4 v[188:189], v[244:247], off offset:256
	s_waitcnt vmcnt(8)
	v_lshlrev_b32_e32 v148, 16, v138
	v_and_b32_e32 v149, 0xffff0000, v138
	v_add_f32_e32 v0, 1.0, v0
	v_rcp_f32_e32 v147, v0
	v_lshlrev_b32_e32 v0, 16, v143
	v_mul_f32_e32 v0, 0xbfb8aa3b, v0
	v_exp_f32_e32 v0, v0
	v_pk_fma_f32 v[146:147], v[14:15], v[146:147], v[148:149]
	v_add_f32_e32 v0, 1.0, v0
	v_rcp_f32_e32 v142, v0
	v_and_b32_e32 v0, 0xffff0000, v143
	v_mul_f32_e32 v0, 0xbfb8aa3b, v0
	v_exp_f32_e32 v0, v0
	v_cvt_pk_bf16_f32 v138, v146, v147
	v_lshlrev_b32_e32 v146, 16, v139
	v_and_b32_e32 v147, 0xffff0000, v139
	v_add_f32_e32 v0, 1.0, v0
	v_rcp_f32_e32 v143, v0
	v_lshlrev_b32_e32 v0, 16, v144
	v_mul_f32_e32 v0, 0xbfb8aa3b, v0
	v_exp_f32_e32 v0, v0
	v_pk_fma_f32 v[142:143], v[16:17], v[142:143], v[146:147]
	v_lshlrev_b32_e32 v146, 16, v140
	v_cvt_pk_bf16_f32 v139, v142, v143
	v_add_f32_e32 v0, 1.0, v0
	v_rcp_f32_e32 v142, v0
	v_and_b32_e32 v0, 0xffff0000, v144
	v_mul_f32_e32 v0, 0xbfb8aa3b, v0
	v_exp_f32_e32 v0, v0
	v_and_b32_e32 v147, 0xffff0000, v140
	v_lshlrev_b32_e32 v144, 16, v141
	v_add_f32_e32 v0, 1.0, v0
	v_rcp_f32_e32 v143, v0
	v_lshlrev_b32_e32 v0, 16, v145
	v_mul_f32_e32 v0, 0xbfb8aa3b, v0
	v_exp_f32_e32 v0, v0
	v_pk_fma_f32 v[142:143], v[10:11], v[142:143], v[146:147]
	v_add_f32_e32 v0, 1.0, v0
	v_cvt_pk_bf16_f32 v140, v142, v143
	v_rcp_f32_e32 v142, v0
	v_and_b32_e32 v0, 0xffff0000, v145
	v_mul_f32_e32 v0, 0xbfb8aa3b, v0
	v_exp_f32_e32 v0, v0
	v_and_b32_e32 v145, 0xffff0000, v141
	v_add_f32_e32 v0, 1.0, v0
	v_rcp_f32_e32 v143, v0
	s_waitcnt vmcnt(7)
	v_lshlrev_b32_e32 v0, 16, v134
	v_mul_f32_e32 v0, 0xbfb8aa3b, v0
	v_exp_f32_e32 v0, v0
	v_pk_fma_f32 v[142:143], v[12:13], v[142:143], v[144:145]
	v_add_f32_e32 v0, 1.0, v0
	v_cvt_pk_bf16_f32 v141, v142, v143
	v_lshl_add_u64 v[186:187], v[186:187], 0, v[230:231]
	ds_bpermute_b32 v244, v243, v138
	ds_bpermute_b32 v245, v243, v139
	ds_bpermute_b32 v246, v243, v140
	ds_bpermute_b32 v247, v243, v141
	s_nop 1
	v_rcp_f32_e32 v138, v0
	v_and_b32_e32 v0, 0xffff0000, v134
	v_mul_f32_e32 v0, 0xbfb8aa3b, v0
	v_exp_f32_e32 v0, v0
	s_waitcnt lgkmcnt(0)
	global_store_dwordx4 v[186:187], v[244:247], off
	s_waitcnt vmcnt(7)
	v_lshlrev_b32_e32 v140, 16, v130
	v_and_b32_e32 v141, 0xffff0000, v130
	v_add_f32_e32 v0, 1.0, v0
	v_rcp_f32_e32 v139, v0
	v_lshlrev_b32_e32 v0, 16, v135
	v_mul_f32_e32 v0, 0xbfb8aa3b, v0
	v_exp_f32_e32 v0, v0
	v_pk_fma_f32 v[138:139], v[6:7], v[138:139], v[140:141]
	v_add_f32_e32 v0, 1.0, v0
	v_rcp_f32_e32 v134, v0
	v_and_b32_e32 v0, 0xffff0000, v135
	v_mul_f32_e32 v0, 0xbfb8aa3b, v0
	v_exp_f32_e32 v0, v0
	v_cvt_pk_bf16_f32 v130, v138, v139
	v_lshlrev_b32_e32 v138, 16, v131
	v_and_b32_e32 v139, 0xffff0000, v131
	v_add_f32_e32 v0, 1.0, v0
	v_rcp_f32_e32 v135, v0
	v_lshlrev_b32_e32 v0, 16, v136
	v_mul_f32_e32 v0, 0xbfb8aa3b, v0
	v_exp_f32_e32 v0, v0
	v_pk_fma_f32 v[134:135], v[8:9], v[134:135], v[138:139]
	v_lshlrev_b32_e32 v138, 16, v132
	v_cvt_pk_bf16_f32 v131, v134, v135
	v_add_f32_e32 v0, 1.0, v0
	v_rcp_f32_e32 v134, v0
	v_and_b32_e32 v0, 0xffff0000, v136
	v_mul_f32_e32 v0, 0xbfb8aa3b, v0
	v_exp_f32_e32 v0, v0
	v_and_b32_e32 v139, 0xffff0000, v132
	v_lshlrev_b32_e32 v136, 16, v133
	v_add_f32_e32 v0, 1.0, v0
	v_rcp_f32_e32 v135, v0
	v_lshlrev_b32_e32 v0, 16, v137
	v_mul_f32_e32 v0, 0xbfb8aa3b, v0
	v_exp_f32_e32 v0, v0
	v_pk_fma_f32 v[134:135], v[2:3], v[134:135], v[138:139]
	v_add_f32_e32 v0, 1.0, v0
	v_cvt_pk_bf16_f32 v132, v134, v135
	v_rcp_f32_e32 v134, v0
	v_and_b32_e32 v0, 0xffff0000, v137
	v_mul_f32_e32 v0, 0xbfb8aa3b, v0
	v_exp_f32_e32 v0, v0
	v_and_b32_e32 v137, 0xffff0000, v133
	v_add_f32_e32 v0, 1.0, v0
	v_rcp_f32_e32 v135, v0
	s_nop 0
	v_pk_fma_f32 v[134:135], v[4:5], v[134:135], v[136:137]
	s_nop 0
	v_cvt_pk_bf16_f32 v133, v134, v135
	s_nop 1
	ds_bpermute_b32 v244, v243, v130
	ds_bpermute_b32 v245, v243, v131
	ds_bpermute_b32 v246, v243, v132
	ds_bpermute_b32 v247, v243, v133
	s_waitcnt lgkmcnt(0)
	global_store_dwordx4 v[186:187], v[244:247], off offset:256
	s_branch .LBB0_299

; __device__ __forceinline__ unsigned cvt_pk_bf16(float lo, float hi) { f32x2 v = {lo, hi}; bf16x2_t b = __builtin_convertvector(v, bf16x2_t); return __builtin_bit_cast(unsigned, b); }
; __device__ __forceinline__ float bf_lo(unsigned w) { return __uint_as_float(w << 16); }
; __device__ __forceinline__ float bf_hi(unsigned w) { return __uint_as_float(w & 0xffff0000u); }
; __device__ __forceinline__ float sigm(float v) { return __builtin_amdgcn_rcpf(1.0f + __builtin_amdgcn_exp2f(-1.44269504089f * v)); }
; __device__ __forceinline__ void epi_run(const Epi& E, f32x4 (&acc)[2][2][4][2], const Unit& u, int wr, int wc, int fr, int fq) {
;     ...
;     } else if (mode == MODE_YA) {
;         u32x4 g[2][4][2];
; #pragma unroll
;         for (int ai = 0; ai < 2; ++ai)
; #pragma unroll
;             for (int m = 0; m < 4; ++m)
; #pragma unroll
;                 for (int bj = 0; bj < 2; ++bj) g[ai][m][bj] = *(const u32x4*)(E.Z + (size_t)(row0 + ai * 128 + m * 16) * NIN + 3072 + col0 + bj * 128);
; #pragma unroll
;         for (int ai = 0; ai < 2; ++ai)
; #pragma unroll
;             for (int m = 0; m < 4; ++m)
; #pragma unroll
;                 for (int bj = 0; bj < 2; ++bj) { const f32x4 v0 = acc[ai][bj][m][0], v1 = acc[ai][bj][m][1]; const u32x4 gg = g[ai][m][bj]; u32x4 w;
;                     w.x = cvt_pk_bf16(v0[0] * sigm(bf_lo(gg.x)), v0[1] * sigm(bf_hi(gg.x))); w.y = cvt_pk_bf16(v0[2] * sigm(bf_lo(gg.y)), v0[3] * sigm(bf_hi(gg.y)));
;                     w.z = cvt_pk_bf16(v1[0] * sigm(bf_lo(gg.z)), v1[1] * sigm(bf_hi(gg.z))); w.w = cvt_pk_bf16(v1[2] * sigm(bf_lo(gg.w)), v1[3] * sigm(bf_hi(gg.w)));
;                     *(u32x4*)(E.Z + (size_t)(row0 + ai * 128 + m * 16) * NIN + 3072 + col0 + bj * 128) = w; }
.LBB0_299:
	s_and_b64 vcc, exec, s[8:9]
	s_cbranch_vccz .LBB0_308
	s_cmp_gt_i32 s83, 0
	s_mov_b64 s[8:9], -1
	s_cbranch_scc0 .LBB0_306
	s_cmp_gt_i32 s83, 1
	s_cbranch_scc0 .LBB0_303
	v_lshrrev_b32_e32 v244, 2, v201
	v_and_b32_e32 v245, 3, v201
	v_lshl_add_u32 v243, v245, 4, v244
	v_lshlrev_b32_e32 v243, 2, v243
	v_and_b32_e32 v246, 15, v201
	v_sub_u32_e32 v244, v244, v246
	v_lshrrev_b32_e32 v246, 4, v201
	v_sub_u32_e32 v245, v245, v246
	v_lshlrev_b32_e32 v245, 4, v245
	v_mul_lo_u32 v244, v244, s69
	v_add_u32_e32 v248, v244, v245
	v_ashrrev_i32_e32 v249, 31, v248
	v_ashrrev_i32_e32 v213, 31, v212
	s_waitcnt lgkmcnt(0)
	v_mov_b64_e32 v[130:131], s[70:71]
	v_mad_i64_i32 v[132:133], s[8:9], v210, s69, v[130:131]
	v_lshlrev_b64 v[134:135], 1, v[212:213]
	v_lshl_add_u64 v[132:133], v[132:133], 0, v[134:135]
	v_add_co_u32_e32 v224, vcc, 0x1000, v132
	s_mov_b64 s[20:21], 0x1800
	s_nop 0
	v_addc_co_u32_e32 v225, vcc, 0, v133, vcc
	v_lshl_add_u64 v[136:137], v[132:133], 0, s[20:21]
	global_load_dwordx4 v[226:229], v[224:225], off offset:2048
	global_load_dwordx4 v[186:189], v[136:137], off offset:256
	v_or_b32_e32 v0, 16, v210
	v_mad_i64_i32 v[132:133], s[8:9], v0, s69, v[130:131]
	v_lshl_add_u64 v[132:133], v[132:133], 0, v[134:135]
	v_add_co_u32_e32 v222, vcc, 0x1000, v132
	v_or_b32_e32 v0, 32, v210
	v_lshl_add_u64 v[136:137], v[132:133], 0, s[20:21]
	v_addc_co_u32_e32 v223, vcc, 0, v133, vcc
	v_mad_i64_i32 v[132:133], s[8:9], v0, s69, v[130:131]
	v_lshl_add_u64 v[132:133], v[132:133], 0, v[134:135]
	v_add_co_u32_e32 v220, vcc, 0x1000, v132
	v_or_b32_e32 v0, 48, v210
	global_load_dwordx4 v[182:185], v[222:223], off offset:2048
	global_load_dwordx4 v[178:181], v[136:137], off offset:256
	v_lshl_add_u64 v[136:137], v[132:133], 0, s[20:21]
	v_addc_co_u32_e32 v221, vcc, 0, v133, vcc
	v_mad_i64_i32 v[132:133], s[8:9], v0, s69, v[130:131]
	v_lshl_add_u64 v[132:133], v[132:133], 0, v[134:135]
	v_add_co_u32_e32 v218, vcc, 0x1000, v132
	v_add_u32_e32 v0, 0x80, v210
	global_load_dwordx4 v[174:177], v[220:221], off offset:2048
	global_load_dwordx4 v[170:173], v[136:137], off offset:256
	v_lshl_add_u64 v[136:137], v[132:133], 0, s[20:21]
	v_addc_co_u32_e32 v219, vcc, 0, v133, vcc
	v_mad_i64_i32 v[132:133], s[8:9], v0, s69, v[130:131]
	v_lshl_add_u64 v[132:133], v[132:133], 0, v[134:135]
	v_add_co_u32_e32 v216, vcc, 0x1000, v132
	v_add_u32_e32 v0, 0x90, v210
	global_load_dwordx4 v[166:169], v[218:219], off offset:2048
	global_load_dwordx4 v[162:165], v[136:137], off offset:256
	v_lshl_add_u64 v[136:137], v[132:133], 0, s[20:21]
	v_addc_co_u32_e32 v217, vcc, 0, v133, vcc
	v_mad_i64_i32 v[132:133], s[8:9], v0, s69, v[130:131]
	v_lshl_add_u64 v[132:133], v[132:133], 0, v[134:135]
	v_add_co_u32_e32 v214, vcc, 0x1000, v132
	v_add_u32_e32 v0, 0xa0, v210
	global_load_dwordx4 v[158:161], v[216:217], off offset:2048
	global_load_dwordx4 v[154:157], v[136:137], off offset:256
	v_lshl_add_u64 v[136:137], v[132:133], 0, s[20:21]
	v_addc_co_u32_e32 v215, vcc, 0, v133, vcc
	v_mad_i64_i32 v[132:133], s[8:9], v0, s69, v[130:131]
	v_add_u32_e32 v0, 0xb0, v210
	v_mad_i64_i32 v[130:131], s[8:9], v0, s69, v[130:131]
	v_lshl_add_u64 v[132:133], v[132:133], 0, v[134:135]
	v_add_co_u32_e32 v192, vcc, 0x1000, v132
	v_lshl_add_u64 v[130:131], v[130:131], 0, v[134:135]
	s_nop 0
	v_addc_co_u32_e32 v193, vcc, 0, v133, vcc
	v_add_co_u32_e32 v190, vcc, 0x1000, v130
	global_load_dwordx4 v[150:153], v[214:215], off offset:2048
	global_load_dwordx4 v[146:149], v[136:137], off offset:256
	v_lshl_add_u64 v[136:137], v[132:133], 0, s[20:21]
	v_lshl_add_u64 v[132:133], v[130:131], 0, s[20:21]
	v_addc_co_u32_e32 v191, vcc, 0, v131, vcc
	global_load_dwordx4 v[142:145], v[192:193], off offset:2048
	global_load_dwordx4 v[138:141], v[136:137], off offset:256
	s_nop 0
	global_load_dwordx4 v[134:137], v[190:191], off offset:2048
	s_nop 0
	global_load_dwordx4 v[130:133], v[132:133], off offset:256
	s_mov_b64 s[8:9], 0
	s_waitcnt vmcnt(0)
	v_lshlrev_b32_e32 v0, 16, v226
	v_mul_f32_e32 v0, 0xbfb8aa3b, v0
	v_exp_f32_e32 v0, v0
	s_nop 0
	v_add_f32_e32 v0, 1.0, v0
	v_rcp_f32_e32 v230, v0
	v_and_b32_e32 v0, 0xffff0000, v226
	v_mul_f32_e32 v0, 0xbfb8aa3b, v0
	v_exp_f32_e32 v0, v0
	s_nop 0
	v_add_f32_e32 v0, 1.0, v0
	v_rcp_f32_e32 v231, v0
	v_lshlrev_b32_e32 v0, 16, v227
	v_mul_f32_e32 v0, 0xbfb8aa3b, v0
	v_exp_f32_e32 v0, v0
	v_pk_mul_f32 v[230:231], v[126:127], v[230:231]
	v_add_f32_e32 v0, 1.0, v0
	v_cvt_pk_bf16_f32 v226, v230, v231
	v_rcp_f32_e32 v230, v0
	v_and_b32_e32 v0, 0xffff0000, v227
	v_mul_f32_e32 v0, 0xbfb8aa3b, v0
	v_exp_f32_e32 v0, v0
	s_nop 0
	v_add_f32_e32 v0, 1.0, v0
	v_rcp_f32_e32 v231, v0
	v_lshlrev_b32_e32 v0, 16, v228
	v_mul_f32_e32 v0, 0xbfb8aa3b, v0
	v_exp_f32_e32 v0, v0
	v_pk_mul_f32 v[230:231], v[128:129], v[230:231]
	v_add_f32_e32 v0, 1.0, v0
	v_cvt_pk_bf16_f32 v227, v230, v231
	v_rcp_f32_e32 v230, v0
	v_and_b32_e32 v0, 0xffff0000, v228
	v_mul_f32_e32 v0, 0xbfb8aa3b, v0
	v_exp_f32_e32 v0, v0
	s_nop 0
	v_add_f32_e32 v0, 1.0, v0
	v_rcp_f32_e32 v231, v0
	v_lshlrev_b32_e32 v0, 16, v229
	v_mul_f32_e32 v0, 0xbfb8aa3b, v0
	v_exp_f32_e32 v0, v0
	v_pk_mul_f32 v[230:231], v[122:123], v[230:231]
	v_add_f32_e32 v0, 1.0, v0
	v_cvt_pk_bf16_f32 v228, v230, v231
	v_rcp_f32_e32 v230, v0
	v_and_b32_e32 v0, 0xffff0000, v229
	v_mul_f32_e32 v0, 0xbfb8aa3b, v0
	v_exp_f32_e32 v0, v0
	s_nop 0
	v_add_f32_e32 v0, 1.0, v0
	v_rcp_f32_e32 v231, v0
	v_lshlrev_b32_e32 v0, 16, v186
	v_mul_f32_e32 v0, 0xbfb8aa3b, v0
	v_exp_f32_e32 v0, v0
	v_pk_mul_f32 v[230:231], v[124:125], v[230:231]
	v_add_f32_e32 v0, 1.0, v0
	v_cvt_pk_bf16_f32 v229, v230, v231
	v_lshl_add_u64 v[224:225], v[224:225], 0, v[248:249]
; __device__ __forceinline__ unsigned cvt_pk_bf16(float lo, float hi) { f32x2 v = {lo, hi}; bf16x2_t b = __builtin_convertvector(v, bf16x2_t); return __builtin_bit_cast(unsigned, b); }
; __device__ __forceinline__ float bf_lo(unsigned w) { return __uint_as_float(w << 16); }
; __device__ __forceinline__ float bf_hi(unsigned w) { return __uint_as_float(w & 0xffff0000u); }
; __device__ __forceinline__ float sigm(float v) { return __builtin_amdgcn_rcpf(1.0f + __builtin_amdgcn_exp2f(-1.44269504089f * v)); }
; __device__ __forceinline__ void epi_run(const Epi& E, f32x4 (&acc)[2][2][4][2], const Unit& u, int wr, int wc, int fr, int fq) {
;     ...
;     } else if (mode == MODE_YA) {
;         u32x4 g[2][4][2];
; #pragma unroll
;         for (int ai = 0; ai < 2; ++ai)
; #pragma unroll
;             for (int m = 0; m < 4; ++m)
; #pragma unroll
;                 for (int bj = 0; bj < 2; ++bj) g[ai][m][bj] = *(const u32x4*)(E.Z + (size_t)(row0 + ai * 128 + m * 16) * NIN + 3072 + col0 + bj * 128);
; #pragma unroll
;         for (int ai = 0; ai < 2; ++ai)
; #pragma unroll
;             for (int m = 0; m < 4; ++m)
; #pragma unroll
;                 for (int bj = 0; bj < 2; ++bj) { const f32x4 v0 = acc[ai][bj][m][0], v1 = acc[ai][bj][m][1]; const u32x4 gg = g[ai][m][bj]; u32x4 w;
;                     w.x = cvt_pk_bf16(v0[0] * sigm(bf_lo(gg.x)), v0[1] * sigm(bf_hi(gg.x))); w.y = cvt_pk_bf16(v0[2] * sigm(bf_lo(gg.y)), v0[3] * sigm(bf_hi(gg.y)));
;                     w.z = cvt_pk_bf16(v1[0] * sigm(bf_lo(gg.z)), v1[1] * sigm(bf_hi(gg.z))); w.w = cvt_pk_bf16(v1[2] * sigm(bf_lo(gg.w)), v1[3] * sigm(bf_hi(gg.w)));
;                     *(u32x4*)(E.Z + (size_t)(row0 + ai * 128 + m * 16) * NIN + 3072 + col0 + bj * 128) = w; }
	ds_bpermute_b32 v244, v243, v226
	ds_bpermute_b32 v245, v243, v227
	ds_bpermute_b32 v246, v243, v228
	ds_bpermute_b32 v247, v243, v229
	s_nop 1
	v_rcp_f32_e32 v226, v0
	v_and_b32_e32 v0, 0xffff0000, v186
	v_mul_f32_e32 v0, 0xbfb8aa3b, v0
	v_exp_f32_e32 v0, v0
	s_nop 0
	v_add_f32_e32 v0, 1.0, v0
	v_rcp_f32_e32 v227, v0
	v_lshlrev_b32_e32 v0, 16, v187
	v_mul_f32_e32 v0, 0xbfb8aa3b, v0
	v_exp_f32_e32 v0, v0
	v_pk_mul_f32 v[226:227], v[118:119], v[226:227]
	v_add_f32_e32 v0, 1.0, v0
	v_cvt_pk_bf16_f32 v186, v226, v227
	v_rcp_f32_e32 v226, v0
	v_and_b32_e32 v0, 0xffff0000, v187
	v_mul_f32_e32 v0, 0xbfb8aa3b, v0
	v_exp_f32_e32 v0, v0
	s_nop 0
	v_add_f32_e32 v0, 1.0, v0
	v_rcp_f32_e32 v227, v0
	v_lshlrev_b32_e32 v0, 16, v188
	v_mul_f32_e32 v0, 0xbfb8aa3b, v0
	v_exp_f32_e32 v0, v0
	v_pk_mul_f32 v[226:227], v[120:121], v[226:227]
	v_add_f32_e32 v0, 1.0, v0
	v_cvt_pk_bf16_f32 v187, v226, v227
	v_rcp_f32_e32 v226, v0
	v_and_b32_e32 v0, 0xffff0000, v188
	v_mul_f32_e32 v0, 0xbfb8aa3b, v0
	v_exp_f32_e32 v0, v0
	s_nop 0
	v_add_f32_e32 v0, 1.0, v0
	v_rcp_f32_e32 v227, v0
	v_lshlrev_b32_e32 v0, 16, v189
	v_mul_f32_e32 v0, 0xbfb8aa3b, v0
	v_exp_f32_e32 v0, v0
	v_pk_mul_f32 v[226:227], v[114:115], v[226:227]
	v_add_f32_e32 v0, 1.0, v0
	v_cvt_pk_bf16_f32 v188, v226, v227
	v_rcp_f32_e32 v226, v0
	v_and_b32_e32 v0, 0xffff0000, v189
	v_mul_f32_e32 v0, 0xbfb8aa3b, v0
	v_exp_f32_e32 v0, v0
	s_nop 0
	v_add_f32_e32 v0, 1.0, v0
	v_rcp_f32_e32 v227, v0
	v_lshlrev_b32_e32 v0, 16, v182
	v_mul_f32_e32 v0, 0xbfb8aa3b, v0
	v_exp_f32_e32 v0, v0
	v_pk_mul_f32 v[226:227], v[116:117], v[226:227]
	v_add_f32_e32 v0, 1.0, v0
	v_cvt_pk_bf16_f32 v189, v226, v227
	s_waitcnt lgkmcnt(0)
	global_store_dwordx4 v[224:225], v[244:247], off offset:2048
	s_nop 1
	ds_bpermute_b32 v244, v243, v186
	ds_bpermute_b32 v245, v243, v187
	ds_bpermute_b32 v246, v243, v188
	ds_bpermute_b32 v247, v243, v189
	s_nop 1
	v_rcp_f32_e32 v186, v0
	v_and_b32_e32 v0, 0xffff0000, v182
	v_mul_f32_e32 v0, 0xbfb8aa3b, v0
	v_exp_f32_e32 v0, v0
	s_nop 0
	v_add_f32_e32 v0, 1.0, v0
	v_rcp_f32_e32 v187, v0
	v_lshlrev_b32_e32 v0, 16, v183
	v_mul_f32_e32 v0, 0xbfb8aa3b, v0
	v_exp_f32_e32 v0, v0
	v_pk_mul_f32 v[186:187], v[110:111], v[186:187]
	v_add_f32_e32 v0, 1.0, v0
	v_cvt_pk_bf16_f32 v182, v186, v187
	v_rcp_f32_e32 v186, v0
	v_and_b32_e32 v0, 0xffff0000, v183
	v_mul_f32_e32 v0, 0xbfb8aa3b, v0
	v_exp_f32_e32 v0, v0
	s_nop 0
	v_add_f32_e32 v0, 1.0, v0
	v_rcp_f32_e32 v187, v0
	v_lshlrev_b32_e32 v0, 16, v184
	v_mul_f32_e32 v0, 0xbfb8aa3b, v0
	v_exp_f32_e32 v0, v0
	v_pk_mul_f32 v[186:187], v[112:113], v[186:187]
	v_add_f32_e32 v0, 1.0, v0
	v_cvt_pk_bf16_f32 v183, v186, v187
	v_rcp_f32_e32 v186, v0
	v_and_b32_e32 v0, 0xffff0000, v184
	v_mul_f32_e32 v0, 0xbfb8aa3b, v0
	v_exp_f32_e32 v0, v0
	s_nop 0
	v_add_f32_e32 v0, 1.0, v0
	v_rcp_f32_e32 v187, v0
	v_lshlrev_b32_e32 v0, 16, v185
	v_mul_f32_e32 v0, 0xbfb8aa3b, v0
	v_exp_f32_e32 v0, v0
	v_pk_mul_f32 v[186:187], v[106:107], v[186:187]
	v_add_f32_e32 v0, 1.0, v0
	v_cvt_pk_bf16_f32 v184, v186, v187
	v_rcp_f32_e32 v186, v0
	v_and_b32_e32 v0, 0xffff0000, v185
	v_mul_f32_e32 v0, 0xbfb8aa3b, v0
	v_exp_f32_e32 v0, v0
	s_nop 0
	v_add_f32_e32 v0, 1.0, v0
	v_rcp_f32_e32 v187, v0
	v_lshlrev_b32_e32 v0, 16, v178
	v_mul_f32_e32 v0, 0xbfb8aa3b, v0
	v_exp_f32_e32 v0, v0
	v_pk_mul_f32 v[186:187], v[108:109], v[186:187]
	v_add_f32_e32 v0, 1.0, v0
	v_cvt_pk_bf16_f32 v185, v186, v187
	s_waitcnt lgkmcnt(0)
	global_store_dwordx4 v[224:225], v[244:247], off offset:2304
	v_lshl_add_u64 v[222:223], v[222:223], 0, v[248:249]
	ds_bpermute_b32 v244, v243, v182
	ds_bpermute_b32 v245, v243, v183
	ds_bpermute_b32 v246, v243, v184
	ds_bpermute_b32 v247, v243, v185
	s_nop 1
	v_rcp_f32_e32 v182, v0
	v_and_b32_e32 v0, 0xffff0000, v178
	v_mul_f32_e32 v0, 0xbfb8aa3b, v0
	v_exp_f32_e32 v0, v0
	s_nop 0
	v_add_f32_e32 v0, 1.0, v0
	v_rcp_f32_e32 v183, v0
	v_lshlrev_b32_e32 v0, 16, v179
	v_mul_f32_e32 v0, 0xbfb8aa3b, v0
	v_exp_f32_e32 v0, v0
	v_pk_mul_f32 v[182:183], v[102:103], v[182:183]
	v_add_f32_e32 v0, 1.0, v0
	v_cvt_pk_bf16_f32 v178, v182, v183
	v_rcp_f32_e32 v182, v0
	v_and_b32_e32 v0, 0xffff0000, v179
	v_mul_f32_e32 v0, 0xbfb8aa3b, v0
	v_exp_f32_e32 v0, v0
	s_nop 0
	v_add_f32_e32 v0, 1.0, v0
	v_rcp_f32_e32 v183, v0
	v_lshlrev_b32_e32 v0, 16, v180
	v_mul_f32_e32 v0, 0xbfb8aa3b, v0
	v_exp_f32_e32 v0, v0
	v_pk_mul_f32 v[182:183], v[104:105], v[182:183]
	v_add_f32_e32 v0, 1.0, v0
	v_cvt_pk_bf16_f32 v179, v182, v183
	v_rcp_f32_e32 v182, v0
	v_and_b32_e32 v0, 0xffff0000, v180
	v_mul_f32_e32 v0, 0xbfb8aa3b, v0
	v_exp_f32_e32 v0, v0
	s_nop 0
	v_add_f32_e32 v0, 1.0, v0
	v_rcp_f32_e32 v183, v0
	v_lshlrev_b32_e32 v0, 16, v181
	v_mul_f32_e32 v0, 0xbfb8aa3b, v0
	v_exp_f32_e32 v0, v0
	v_pk_mul_f32 v[182:183], v[94:95], v[182:183]
	v_add_f32_e32 v0, 1.0, v0
	v_cvt_pk_bf16_f32 v180, v182, v183
	v_rcp_f32_e32 v182, v0
	v_and_b32_e32 v0, 0xffff0000, v181
	v_mul_f32_e32 v0, 0xbfb8aa3b, v0
	v_exp_f32_e32 v0, v0
	s_nop 0
	v_add_f32_e32 v0, 1.0, v0
	v_rcp_f32_e32 v183, v0
	v_lshlrev_b32_e32 v0, 16, v174
	v_mul_f32_e32 v0, 0xbfb8aa3b, v0
	v_exp_f32_e32 v0, v0
	v_pk_mul_f32 v[182:183], v[96:97], v[182:183]
	v_add_f32_e32 v0, 1.0, v0
	v_cvt_pk_bf16_f32 v181, v182, v183
	s_waitcnt lgkmcnt(0)
; __device__ __forceinline__ unsigned cvt_pk_bf16(float lo, float hi) { f32x2 v = {lo, hi}; bf16x2_t b = __builtin_convertvector(v, bf16x2_t); return __builtin_bit_cast(unsigned, b); }
; __device__ __forceinline__ float bf_lo(unsigned w) { return __uint_as_float(w << 16); }
; __device__ __forceinline__ float bf_hi(unsigned w) { return __uint_as_float(w & 0xffff0000u); }
; __device__ __forceinline__ float sigm(float v) { return __builtin_amdgcn_rcpf(1.0f + __builtin_amdgcn_exp2f(-1.44269504089f * v)); }
; __device__ __forceinline__ void epi_run(const Epi& E, f32x4 (&acc)[2][2][4][2], const Unit& u, int wr, int wc, int fr, int fq) {
;     ...
;     } else if (mode == MODE_YA) {
;         u32x4 g[2][4][2];
; #pragma unroll
;         for (int ai = 0; ai < 2; ++ai)
; #pragma unroll
;             for (int m = 0; m < 4; ++m)
; #pragma unroll
;                 for (int bj = 0; bj < 2; ++bj) g[ai][m][bj] = *(const u32x4*)(E.Z + (size_t)(row0 + ai * 128 + m * 16) * NIN + 3072 + col0 + bj * 128);
; #pragma unroll
;         for (int ai = 0; ai < 2; ++ai)
; #pragma unroll
;             for (int m = 0; m < 4; ++m)
; #pragma unroll
;                 for (int bj = 0; bj < 2; ++bj) { const f32x4 v0 = acc[ai][bj][m][0], v1 = acc[ai][bj][m][1]; const u32x4 gg = g[ai][m][bj]; u32x4 w;
;                     w.x = cvt_pk_bf16(v0[0] * sigm(bf_lo(gg.x)), v0[1] * sigm(bf_hi(gg.x))); w.y = cvt_pk_bf16(v0[2] * sigm(bf_lo(gg.y)), v0[3] * sigm(bf_hi(gg.y)));
;                     w.z = cvt_pk_bf16(v1[0] * sigm(bf_lo(gg.z)), v1[1] * sigm(bf_hi(gg.z))); w.w = cvt_pk_bf16(v1[2] * sigm(bf_lo(gg.w)), v1[3] * sigm(bf_hi(gg.w)));
;                     *(u32x4*)(E.Z + (size_t)(row0 + ai * 128 + m * 16) * NIN + 3072 + col0 + bj * 128) = w; }
	global_store_dwordx4 v[222:223], v[244:247], off offset:2048
	s_nop 1
	ds_bpermute_b32 v244, v243, v178
	ds_bpermute_b32 v245, v243, v179
	ds_bpermute_b32 v246, v243, v180
	ds_bpermute_b32 v247, v243, v181
	s_nop 1
	v_rcp_f32_e32 v178, v0
	v_and_b32_e32 v0, 0xffff0000, v174
	v_mul_f32_e32 v0, 0xbfb8aa3b, v0
	v_exp_f32_e32 v0, v0
	s_nop 0
	v_add_f32_e32 v0, 1.0, v0
	v_rcp_f32_e32 v179, v0
	v_lshlrev_b32_e32 v0, 16, v175
	v_mul_f32_e32 v0, 0xbfb8aa3b, v0
	v_exp_f32_e32 v0, v0
	v_pk_mul_f32 v[178:179], v[98:99], v[178:179]
	v_add_f32_e32 v0, 1.0, v0
	v_cvt_pk_bf16_f32 v174, v178, v179
	v_rcp_f32_e32 v178, v0
	v_and_b32_e32 v0, 0xffff0000, v175
	v_mul_f32_e32 v0, 0xbfb8aa3b, v0
	v_exp_f32_e32 v0, v0
	s_nop 0
	v_add_f32_e32 v0, 1.0, v0
	v_rcp_f32_e32 v179, v0
	v_lshlrev_b32_e32 v0, 16, v176
	v_mul_f32_e32 v0, 0xbfb8aa3b, v0
	v_exp_f32_e32 v0, v0
	v_pk_mul_f32 v[178:179], v[100:101], v[178:179]
	v_add_f32_e32 v0, 1.0, v0
	v_cvt_pk_bf16_f32 v175, v178, v179
	v_rcp_f32_e32 v178, v0
	v_and_b32_e32 v0, 0xffff0000, v176
	v_mul_f32_e32 v0, 0xbfb8aa3b, v0
	v_exp_f32_e32 v0, v0
	s_nop 0
	v_add_f32_e32 v0, 1.0, v0
	v_rcp_f32_e32 v179, v0
	v_lshlrev_b32_e32 v0, 16, v177
	v_mul_f32_e32 v0, 0xbfb8aa3b, v0
	v_exp_f32_e32 v0, v0
	v_pk_mul_f32 v[178:179], v[90:91], v[178:179]
	v_add_f32_e32 v0, 1.0, v0
	v_cvt_pk_bf16_f32 v176, v178, v179
	v_rcp_f32_e32 v178, v0
	v_and_b32_e32 v0, 0xffff0000, v177
	v_mul_f32_e32 v0, 0xbfb8aa3b, v0
	v_exp_f32_e32 v0, v0
	s_nop 0
	v_add_f32_e32 v0, 1.0, v0
	v_rcp_f32_e32 v179, v0
	v_lshlrev_b32_e32 v0, 16, v170
	v_mul_f32_e32 v0, 0xbfb8aa3b, v0
	v_exp_f32_e32 v0, v0
	v_pk_mul_f32 v[178:179], v[92:93], v[178:179]
	v_add_f32_e32 v0, 1.0, v0
	v_cvt_pk_bf16_f32 v177, v178, v179
	s_waitcnt lgkmcnt(0)
	global_store_dwordx4 v[222:223], v[244:247], off offset:2304
	v_lshl_add_u64 v[220:221], v[220:221], 0, v[248:249]
	ds_bpermute_b32 v244, v243, v174
	ds_bpermute_b32 v245, v243, v175
	ds_bpermute_b32 v246, v243, v176
	ds_bpermute_b32 v247, v243, v177
	s_nop 1
	v_rcp_f32_e32 v174, v0
	v_and_b32_e32 v0, 0xffff0000, v170
	v_mul_f32_e32 v0, 0xbfb8aa3b, v0
	v_exp_f32_e32 v0, v0
	s_nop 0
	v_add_f32_e32 v0, 1.0, v0
	v_rcp_f32_e32 v175, v0
	v_lshlrev_b32_e32 v0, 16, v171
	v_mul_f32_e32 v0, 0xbfb8aa3b, v0
	v_exp_f32_e32 v0, v0
	v_pk_mul_f32 v[174:175], v[86:87], v[174:175]
	v_add_f32_e32 v0, 1.0, v0
	v_cvt_pk_bf16_f32 v170, v174, v175
	v_rcp_f32_e32 v174, v0
	v_and_b32_e32 v0, 0xffff0000, v171
	v_mul_f32_e32 v0, 0xbfb8aa3b, v0
	v_exp_f32_e32 v0, v0
	s_nop 0
	v_add_f32_e32 v0, 1.0, v0
	v_rcp_f32_e32 v175, v0
	v_lshlrev_b32_e32 v0, 16, v172
	v_mul_f32_e32 v0, 0xbfb8aa3b, v0
	v_exp_f32_e32 v0, v0
	v_pk_mul_f32 v[174:175], v[88:89], v[174:175]
	v_add_f32_e32 v0, 1.0, v0
	v_cvt_pk_bf16_f32 v171, v174, v175
	v_rcp_f32_e32 v174, v0
	v_and_b32_e32 v0, 0xffff0000, v172
	v_mul_f32_e32 v0, 0xbfb8aa3b, v0
	v_exp_f32_e32 v0, v0
	s_nop 0
	v_add_f32_e32 v0, 1.0, v0
	v_rcp_f32_e32 v175, v0
	v_lshlrev_b32_e32 v0, 16, v173
	v_mul_f32_e32 v0, 0xbfb8aa3b, v0
	v_exp_f32_e32 v0, v0
	v_pk_mul_f32 v[174:175], v[78:79], v[174:175]
	v_add_f32_e32 v0, 1.0, v0
	v_cvt_pk_bf16_f32 v172, v174, v175
	v_rcp_f32_e32 v174, v0
	v_and_b32_e32 v0, 0xffff0000, v173
	v_mul_f32_e32 v0, 0xbfb8aa3b, v0
	v_exp_f32_e32 v0, v0
	s_nop 0
	v_add_f32_e32 v0, 1.0, v0
	v_rcp_f32_e32 v175, v0
	v_lshlrev_b32_e32 v0, 16, v166
	v_mul_f32_e32 v0, 0xbfb8aa3b, v0
	v_exp_f32_e32 v0, v0
	v_pk_mul_f32 v[174:175], v[80:81], v[174:175]
	v_add_f32_e32 v0, 1.0, v0
	v_cvt_pk_bf16_f32 v173, v174, v175
	s_waitcnt lgkmcnt(0)
	global_store_dwordx4 v[220:221], v[244:247], off offset:2048
	s_nop 1
	ds_bpermute_b32 v244, v243, v170
	ds_bpermute_b32 v245, v243, v171
	ds_bpermute_b32 v246, v243, v172
	ds_bpermute_b32 v247, v243, v173
	s_nop 1
	v_rcp_f32_e32 v170, v0
	v_and_b32_e32 v0, 0xffff0000, v166
	v_mul_f32_e32 v0, 0xbfb8aa3b, v0
	v_exp_f32_e32 v0, v0
	s_nop 0
	v_add_f32_e32 v0, 1.0, v0
	v_rcp_f32_e32 v171, v0
	v_lshlrev_b32_e32 v0, 16, v167
	v_mul_f32_e32 v0, 0xbfb8aa3b, v0
	v_exp_f32_e32 v0, v0
	v_pk_mul_f32 v[170:171], v[82:83], v[170:171]
	v_add_f32_e32 v0, 1.0, v0
	v_cvt_pk_bf16_f32 v166, v170, v171
	v_rcp_f32_e32 v170, v0
	v_and_b32_e32 v0, 0xffff0000, v167
	v_mul_f32_e32 v0, 0xbfb8aa3b, v0
	v_exp_f32_e32 v0, v0
	s_nop 0
	v_add_f32_e32 v0, 1.0, v0
	v_rcp_f32_e32 v171, v0
	v_lshlrev_b32_e32 v0, 16, v168
	v_mul_f32_e32 v0, 0xbfb8aa3b, v0
	v_exp_f32_e32 v0, v0
	v_pk_mul_f32 v[170:171], v[84:85], v[170:171]
	v_add_f32_e32 v0, 1.0, v0
	v_cvt_pk_bf16_f32 v167, v170, v171
	v_rcp_f32_e32 v170, v0
	v_and_b32_e32 v0, 0xffff0000, v168
	v_mul_f32_e32 v0, 0xbfb8aa3b, v0
	v_exp_f32_e32 v0, v0
	s_nop 0
	v_add_f32_e32 v0, 1.0, v0
	v_rcp_f32_e32 v171, v0
	v_lshlrev_b32_e32 v0, 16, v169
	v_mul_f32_e32 v0, 0xbfb8aa3b, v0
	v_exp_f32_e32 v0, v0
	v_pk_mul_f32 v[170:171], v[74:75], v[170:171]
	v_add_f32_e32 v0, 1.0, v0
	v_cvt_pk_bf16_f32 v168, v170, v171
	v_rcp_f32_e32 v170, v0
	v_and_b32_e32 v0, 0xffff0000, v169
	v_mul_f32_e32 v0, 0xbfb8aa3b, v0
	v_exp_f32_e32 v0, v0
	s_nop 0
	v_add_f32_e32 v0, 1.0, v0
	v_rcp_f32_e32 v171, v0
	v_lshlrev_b32_e32 v0, 16, v162
	v_mul_f32_e32 v0, 0xbfb8aa3b, v0
	v_exp_f32_e32 v0, v0
	v_pk_mul_f32 v[170:171], v[76:77], v[170:171]
	v_add_f32_e32 v0, 1.0, v0
	v_cvt_pk_bf16_f32 v169, v170, v171
	s_waitcnt lgkmcnt(0)
; __device__ __forceinline__ unsigned cvt_pk_bf16(float lo, float hi) { f32x2 v = {lo, hi}; bf16x2_t b = __builtin_convertvector(v, bf16x2_t); return __builtin_bit_cast(unsigned, b); }
; __device__ __forceinline__ float bf_lo(unsigned w) { return __uint_as_float(w << 16); }
; __device__ __forceinline__ float bf_hi(unsigned w) { return __uint_as_float(w & 0xffff0000u); }
; __device__ __forceinline__ float sigm(float v) { return __builtin_amdgcn_rcpf(1.0f + __builtin_amdgcn_exp2f(-1.44269504089f * v)); }
; __device__ __forceinline__ void epi_run(const Epi& E, f32x4 (&acc)[2][2][4][2], const Unit& u, int wr, int wc, int fr, int fq) {
;     ...
;     } else if (mode == MODE_YA) {
;         u32x4 g[2][4][2];
; #pragma unroll
;         for (int ai = 0; ai < 2; ++ai)
; #pragma unroll
;             for (int m = 0; m < 4; ++m)
; #pragma unroll
;                 for (int bj = 0; bj < 2; ++bj) g[ai][m][bj] = *(const u32x4*)(E.Z + (size_t)(row0 + ai * 128 + m * 16) * NIN + 3072 + col0 + bj * 128);
; #pragma unroll
;         for (int ai = 0; ai < 2; ++ai)
; #pragma unroll
;             for (int m = 0; m < 4; ++m)
; #pragma unroll
;                 for (int bj = 0; bj < 2; ++bj) { const f32x4 v0 = acc[ai][bj][m][0], v1 = acc[ai][bj][m][1]; const u32x4 gg = g[ai][m][bj]; u32x4 w;
;                     w.x = cvt_pk_bf16(v0[0] * sigm(bf_lo(gg.x)), v0[1] * sigm(bf_hi(gg.x))); w.y = cvt_pk_bf16(v0[2] * sigm(bf_lo(gg.y)), v0[3] * sigm(bf_hi(gg.y)));
;                     w.z = cvt_pk_bf16(v1[0] * sigm(bf_lo(gg.z)), v1[1] * sigm(bf_hi(gg.z))); w.w = cvt_pk_bf16(v1[2] * sigm(bf_lo(gg.w)), v1[3] * sigm(bf_hi(gg.w)));
;                     *(u32x4*)(E.Z + (size_t)(row0 + ai * 128 + m * 16) * NIN + 3072 + col0 + bj * 128) = w; }
	global_store_dwordx4 v[220:221], v[244:247], off offset:2304
	v_lshl_add_u64 v[218:219], v[218:219], 0, v[248:249]
	ds_bpermute_b32 v244, v243, v166
	ds_bpermute_b32 v245, v243, v167
	ds_bpermute_b32 v246, v243, v168
	ds_bpermute_b32 v247, v243, v169
	s_nop 1
	v_rcp_f32_e32 v166, v0
	v_and_b32_e32 v0, 0xffff0000, v162
	v_mul_f32_e32 v0, 0xbfb8aa3b, v0
	v_exp_f32_e32 v0, v0
	s_nop 0
	v_add_f32_e32 v0, 1.0, v0
	v_rcp_f32_e32 v167, v0
	v_lshlrev_b32_e32 v0, 16, v163
	v_mul_f32_e32 v0, 0xbfb8aa3b, v0
	v_exp_f32_e32 v0, v0
	v_pk_mul_f32 v[166:167], v[70:71], v[166:167]
	v_add_f32_e32 v0, 1.0, v0
	v_cvt_pk_bf16_f32 v162, v166, v167
	v_rcp_f32_e32 v166, v0
	v_and_b32_e32 v0, 0xffff0000, v163
	v_mul_f32_e32 v0, 0xbfb8aa3b, v0
	v_exp_f32_e32 v0, v0
	s_nop 0
	v_add_f32_e32 v0, 1.0, v0
	v_rcp_f32_e32 v167, v0
	v_lshlrev_b32_e32 v0, 16, v164
	v_mul_f32_e32 v0, 0xbfb8aa3b, v0
	v_exp_f32_e32 v0, v0
	v_pk_mul_f32 v[166:167], v[72:73], v[166:167]
	v_add_f32_e32 v0, 1.0, v0
	v_cvt_pk_bf16_f32 v163, v166, v167
	v_rcp_f32_e32 v166, v0
	v_and_b32_e32 v0, 0xffff0000, v164
	v_mul_f32_e32 v0, 0xbfb8aa3b, v0
	v_exp_f32_e32 v0, v0
	s_nop 0
	v_add_f32_e32 v0, 1.0, v0
	v_rcp_f32_e32 v167, v0
	v_lshlrev_b32_e32 v0, 16, v165
	v_mul_f32_e32 v0, 0xbfb8aa3b, v0
	v_exp_f32_e32 v0, v0
	v_pk_mul_f32 v[166:167], v[66:67], v[166:167]
	v_add_f32_e32 v0, 1.0, v0
	v_cvt_pk_bf16_f32 v164, v166, v167
	v_rcp_f32_e32 v166, v0
	v_and_b32_e32 v0, 0xffff0000, v165
	v_mul_f32_e32 v0, 0xbfb8aa3b, v0
	v_exp_f32_e32 v0, v0
	s_nop 0
	v_add_f32_e32 v0, 1.0, v0
	v_rcp_f32_e32 v167, v0
	v_lshlrev_b32_e32 v0, 16, v158
	v_mul_f32_e32 v0, 0xbfb8aa3b, v0
	v_exp_f32_e32 v0, v0
	v_pk_mul_f32 v[166:167], v[68:69], v[166:167]
	v_add_f32_e32 v0, 1.0, v0
	v_cvt_pk_bf16_f32 v165, v166, v167
	s_waitcnt lgkmcnt(0)
	global_store_dwordx4 v[218:219], v[244:247], off offset:2048
	s_nop 1
	ds_bpermute_b32 v244, v243, v162
	ds_bpermute_b32 v245, v243, v163
	ds_bpermute_b32 v246, v243, v164
	ds_bpermute_b32 v247, v243, v165
	s_nop 1
	v_rcp_f32_e32 v162, v0
	v_and_b32_e32 v0, 0xffff0000, v158
	v_mul_f32_e32 v0, 0xbfb8aa3b, v0
	v_exp_f32_e32 v0, v0
	s_nop 0
	v_add_f32_e32 v0, 1.0, v0
	v_rcp_f32_e32 v163, v0
	v_lshlrev_b32_e32 v0, 16, v159
	v_mul_f32_e32 v0, 0xbfb8aa3b, v0
	v_exp_f32_e32 v0, v0
	v_pk_mul_f32 v[162:163], v[62:63], v[162:163]
	v_add_f32_e32 v0, 1.0, v0
	v_cvt_pk_bf16_f32 v158, v162, v163
	v_rcp_f32_e32 v162, v0
	v_and_b32_e32 v0, 0xffff0000, v159
	v_mul_f32_e32 v0, 0xbfb8aa3b, v0
	v_exp_f32_e32 v0, v0
	s_nop 0
	v_add_f32_e32 v0, 1.0, v0
	v_rcp_f32_e32 v163, v0
	v_lshlrev_b32_e32 v0, 16, v160
	v_mul_f32_e32 v0, 0xbfb8aa3b, v0
	v_exp_f32_e32 v0, v0
	v_pk_mul_f32 v[162:163], v[64:65], v[162:163]
	v_add_f32_e32 v0, 1.0, v0
	v_cvt_pk_bf16_f32 v159, v162, v163
	v_rcp_f32_e32 v162, v0
	v_and_b32_e32 v0, 0xffff0000, v160
	v_mul_f32_e32 v0, 0xbfb8aa3b, v0
	v_exp_f32_e32 v0, v0
	s_nop 0
	v_add_f32_e32 v0, 1.0, v0
	v_rcp_f32_e32 v163, v0
	v_lshlrev_b32_e32 v0, 16, v161
	v_mul_f32_e32 v0, 0xbfb8aa3b, v0
	v_exp_f32_e32 v0, v0
	v_pk_mul_f32 v[162:163], v[58:59], v[162:163]
	v_add_f32_e32 v0, 1.0, v0
	v_cvt_pk_bf16_f32 v160, v162, v163
	v_rcp_f32_e32 v162, v0
	v_and_b32_e32 v0, 0xffff0000, v161
	v_mul_f32_e32 v0, 0xbfb8aa3b, v0
	v_exp_f32_e32 v0, v0
	s_nop 0
	v_add_f32_e32 v0, 1.0, v0
	v_rcp_f32_e32 v163, v0
	v_lshlrev_b32_e32 v0, 16, v154
	v_mul_f32_e32 v0, 0xbfb8aa3b, v0
	v_exp_f32_e32 v0, v0
	v_pk_mul_f32 v[162:163], v[60:61], v[162:163]
	v_add_f32_e32 v0, 1.0, v0
	v_cvt_pk_bf16_f32 v161, v162, v163
	s_waitcnt lgkmcnt(0)
	global_store_dwordx4 v[218:219], v[244:247], off offset:2304
	v_lshl_add_u64 v[216:217], v[216:217], 0, v[248:249]
	ds_bpermute_b32 v244, v243, v158
	ds_bpermute_b32 v245, v243, v159
	ds_bpermute_b32 v246, v243, v160
	ds_bpermute_b32 v247, v243, v161
	s_nop 1
	v_rcp_f32_e32 v158, v0
	v_and_b32_e32 v0, 0xffff0000, v154
	v_mul_f32_e32 v0, 0xbfb8aa3b, v0
	v_exp_f32_e32 v0, v0
	s_nop 0
	v_add_f32_e32 v0, 1.0, v0
	v_rcp_f32_e32 v159, v0
	v_lshlrev_b32_e32 v0, 16, v155
	v_mul_f32_e32 v0, 0xbfb8aa3b, v0
	v_exp_f32_e32 v0, v0
	v_pk_mul_f32 v[158:159], v[54:55], v[158:159]
	v_add_f32_e32 v0, 1.0, v0
	v_cvt_pk_bf16_f32 v154, v158, v159
	v_rcp_f32_e32 v158, v0
	v_and_b32_e32 v0, 0xffff0000, v155
	v_mul_f32_e32 v0, 0xbfb8aa3b, v0
	v_exp_f32_e32 v0, v0
	s_nop 0
	v_add_f32_e32 v0, 1.0, v0
	v_rcp_f32_e32 v159, v0
	v_lshlrev_b32_e32 v0, 16, v156
	v_mul_f32_e32 v0, 0xbfb8aa3b, v0
	v_exp_f32_e32 v0, v0
	v_pk_mul_f32 v[158:159], v[56:57], v[158:159]
	v_add_f32_e32 v0, 1.0, v0
	v_cvt_pk_bf16_f32 v155, v158, v159
	v_rcp_f32_e32 v158, v0
	v_and_b32_e32 v0, 0xffff0000, v156
	v_mul_f32_e32 v0, 0xbfb8aa3b, v0
	v_exp_f32_e32 v0, v0
	s_nop 0
	v_add_f32_e32 v0, 1.0, v0
	v_rcp_f32_e32 v159, v0
	v_lshlrev_b32_e32 v0, 16, v157
	v_mul_f32_e32 v0, 0xbfb8aa3b, v0
	v_exp_f32_e32 v0, v0
	v_pk_mul_f32 v[158:159], v[50:51], v[158:159]
	v_add_f32_e32 v0, 1.0, v0
	v_cvt_pk_bf16_f32 v156, v158, v159
	v_rcp_f32_e32 v158, v0
	v_and_b32_e32 v0, 0xffff0000, v157
	v_mul_f32_e32 v0, 0xbfb8aa3b, v0
	v_exp_f32_e32 v0, v0
	s_nop 0
	v_add_f32_e32 v0, 1.0, v0
	v_rcp_f32_e32 v159, v0
	v_lshlrev_b32_e32 v0, 16, v150
	v_mul_f32_e32 v0, 0xbfb8aa3b, v0
	v_exp_f32_e32 v0, v0
	v_pk_mul_f32 v[158:159], v[52:53], v[158:159]
	v_add_f32_e32 v0, 1.0, v0
	v_cvt_pk_bf16_f32 v157, v158, v159
	s_waitcnt lgkmcnt(0)
; __device__ __forceinline__ unsigned cvt_pk_bf16(float lo, float hi) { f32x2 v = {lo, hi}; bf16x2_t b = __builtin_convertvector(v, bf16x2_t); return __builtin_bit_cast(unsigned, b); }
; __device__ __forceinline__ float bf_lo(unsigned w) { return __uint_as_float(w << 16); }
; __device__ __forceinline__ float bf_hi(unsigned w) { return __uint_as_float(w & 0xffff0000u); }
; __device__ __forceinline__ float sigm(float v) { return __builtin_amdgcn_rcpf(1.0f + __builtin_amdgcn_exp2f(-1.44269504089f * v)); }
; __device__ __forceinline__ void epi_run(const Epi& E, f32x4 (&acc)[2][2][4][2], const Unit& u, int wr, int wc, int fr, int fq) {
;     ...
; #pragma unroll
;         for (int ai = 0; ai < 2; ++ai)
; #pragma unroll
;             for (int m = 0; m < 4; ++m)
; #pragma unroll
;                 for (int bj = 0; bj < 2; ++bj) { const f32x4 v0 = acc[ai][bj][m][0], v1 = acc[ai][bj][m][1]; const u32x4 gg = g[ai][m][bj]; u32x4 w;
;                     w.x = cvt_pk_bf16(v0[0] * sigm(bf_lo(gg.x)), v0[1] * sigm(bf_hi(gg.x))); w.y = cvt_pk_bf16(v0[2] * sigm(bf_lo(gg.y)), v0[3] * sigm(bf_hi(gg.y)));
;                     w.z = cvt_pk_bf16(v1[0] * sigm(bf_lo(gg.z)), v1[1] * sigm(bf_hi(gg.z))); w.w = cvt_pk_bf16(v1[2] * sigm(bf_lo(gg.w)), v1[3] * sigm(bf_hi(gg.w)));
;                     *(u32x4*)(E.Z + (size_t)(row0 + ai * 128 + m * 16) * NIN + 3072 + col0 + bj * 128) = w; }
	global_store_dwordx4 v[216:217], v[244:247], off offset:2048
	s_nop 1
	ds_bpermute_b32 v244, v243, v154
	ds_bpermute_b32 v245, v243, v155
	ds_bpermute_b32 v246, v243, v156
	ds_bpermute_b32 v247, v243, v157
	s_nop 1
	v_rcp_f32_e32 v154, v0
	v_and_b32_e32 v0, 0xffff0000, v150
	v_mul_f32_e32 v0, 0xbfb8aa3b, v0
	v_exp_f32_e32 v0, v0
	s_nop 0
	v_add_f32_e32 v0, 1.0, v0
	v_rcp_f32_e32 v155, v0
	v_lshlrev_b32_e32 v0, 16, v151
	v_mul_f32_e32 v0, 0xbfb8aa3b, v0
	v_exp_f32_e32 v0, v0
	v_pk_mul_f32 v[154:155], v[46:47], v[154:155]
	v_add_f32_e32 v0, 1.0, v0
	v_cvt_pk_bf16_f32 v150, v154, v155
	v_rcp_f32_e32 v154, v0
	v_and_b32_e32 v0, 0xffff0000, v151
	v_mul_f32_e32 v0, 0xbfb8aa3b, v0
	v_exp_f32_e32 v0, v0
	s_nop 0
	v_add_f32_e32 v0, 1.0, v0
	v_rcp_f32_e32 v155, v0
	v_lshlrev_b32_e32 v0, 16, v152
	v_mul_f32_e32 v0, 0xbfb8aa3b, v0
	v_exp_f32_e32 v0, v0
	v_pk_mul_f32 v[154:155], v[48:49], v[154:155]
	v_add_f32_e32 v0, 1.0, v0
	v_cvt_pk_bf16_f32 v151, v154, v155
	v_rcp_f32_e32 v154, v0
	v_and_b32_e32 v0, 0xffff0000, v152
	v_mul_f32_e32 v0, 0xbfb8aa3b, v0
	v_exp_f32_e32 v0, v0
	s_nop 0
	v_add_f32_e32 v0, 1.0, v0
	v_rcp_f32_e32 v155, v0
	v_lshlrev_b32_e32 v0, 16, v153
	v_mul_f32_e32 v0, 0xbfb8aa3b, v0
	v_exp_f32_e32 v0, v0
	v_pk_mul_f32 v[154:155], v[42:43], v[154:155]
	v_add_f32_e32 v0, 1.0, v0
	v_cvt_pk_bf16_f32 v152, v154, v155
	v_rcp_f32_e32 v154, v0
	v_and_b32_e32 v0, 0xffff0000, v153
	v_mul_f32_e32 v0, 0xbfb8aa3b, v0
	v_exp_f32_e32 v0, v0
	s_nop 0
	v_add_f32_e32 v0, 1.0, v0
	v_rcp_f32_e32 v155, v0
	v_lshlrev_b32_e32 v0, 16, v146
	v_mul_f32_e32 v0, 0xbfb8aa3b, v0
	v_exp_f32_e32 v0, v0
	v_pk_mul_f32 v[154:155], v[44:45], v[154:155]
	v_add_f32_e32 v0, 1.0, v0
	v_cvt_pk_bf16_f32 v153, v154, v155
	s_waitcnt lgkmcnt(0)
	global_store_dwordx4 v[216:217], v[244:247], off offset:2304
	v_lshl_add_u64 v[214:215], v[214:215], 0, v[248:249]
	ds_bpermute_b32 v244, v243, v150
	ds_bpermute_b32 v245, v243, v151
	ds_bpermute_b32 v246, v243, v152
	ds_bpermute_b32 v247, v243, v153
	s_nop 1
	v_rcp_f32_e32 v150, v0
	v_and_b32_e32 v0, 0xffff0000, v146
	v_mul_f32_e32 v0, 0xbfb8aa3b, v0
	v_exp_f32_e32 v0, v0
	s_nop 0
	v_add_f32_e32 v0, 1.0, v0
	v_rcp_f32_e32 v151, v0
	v_lshlrev_b32_e32 v0, 16, v147
	v_mul_f32_e32 v0, 0xbfb8aa3b, v0
	v_exp_f32_e32 v0, v0
	v_pk_mul_f32 v[150:151], v[38:39], v[150:151]
	v_add_f32_e32 v0, 1.0, v0
	v_cvt_pk_bf16_f32 v146, v150, v151
	v_rcp_f32_e32 v150, v0
	v_and_b32_e32 v0, 0xffff0000, v147
	v_mul_f32_e32 v0, 0xbfb8aa3b, v0
	v_exp_f32_e32 v0, v0
	s_nop 0
	v_add_f32_e32 v0, 1.0, v0
	v_rcp_f32_e32 v151, v0
	v_lshlrev_b32_e32 v0, 16, v148
	v_mul_f32_e32 v0, 0xbfb8aa3b, v0
	v_exp_f32_e32 v0, v0
	v_pk_mul_f32 v[150:151], v[40:41], v[150:151]
	v_add_f32_e32 v0, 1.0, v0
	v_cvt_pk_bf16_f32 v147, v150, v151
	v_rcp_f32_e32 v150, v0
	v_and_b32_e32 v0, 0xffff0000, v148
	v_mul_f32_e32 v0, 0xbfb8aa3b, v0
	v_exp_f32_e32 v0, v0
	s_nop 0
	v_add_f32_e32 v0, 1.0, v0
	v_rcp_f32_e32 v151, v0
	v_lshlrev_b32_e32 v0, 16, v149
	v_mul_f32_e32 v0, 0xbfb8aa3b, v0
	v_exp_f32_e32 v0, v0
	v_pk_mul_f32 v[150:151], v[34:35], v[150:151]
	v_add_f32_e32 v0, 1.0, v0
	v_cvt_pk_bf16_f32 v148, v150, v151
	v_rcp_f32_e32 v150, v0
	v_and_b32_e32 v0, 0xffff0000, v149
	v_mul_f32_e32 v0, 0xbfb8aa3b, v0
	v_exp_f32_e32 v0, v0
	s_nop 0
	v_add_f32_e32 v0, 1.0, v0
	v_rcp_f32_e32 v151, v0
	v_lshlrev_b32_e32 v0, 16, v142
	v_mul_f32_e32 v0, 0xbfb8aa3b, v0
	v_exp_f32_e32 v0, v0
	v_pk_mul_f32 v[150:151], v[36:37], v[150:151]
	v_add_f32_e32 v0, 1.0, v0
	v_cvt_pk_bf16_f32 v149, v150, v151
	s_waitcnt lgkmcnt(0)
	global_store_dwordx4 v[214:215], v[244:247], off offset:2048
	s_nop 1
	ds_bpermute_b32 v244, v243, v146
	ds_bpermute_b32 v245, v243, v147
	ds_bpermute_b32 v246, v243, v148
	ds_bpermute_b32 v247, v243, v149
	s_nop 1
	v_rcp_f32_e32 v146, v0
	v_and_b32_e32 v0, 0xffff0000, v142
	v_mul_f32_e32 v0, 0xbfb8aa3b, v0
	v_exp_f32_e32 v0, v0
	s_nop 0
	v_add_f32_e32 v0, 1.0, v0
	v_rcp_f32_e32 v147, v0
	v_lshlrev_b32_e32 v0, 16, v143
	v_mul_f32_e32 v0, 0xbfb8aa3b, v0
	v_exp_f32_e32 v0, v0
	v_pk_mul_f32 v[146:147], v[30:31], v[146:147]
	v_add_f32_e32 v0, 1.0, v0
	v_cvt_pk_bf16_f32 v142, v146, v147
	v_rcp_f32_e32 v146, v0
	v_and_b32_e32 v0, 0xffff0000, v143
	v_mul_f32_e32 v0, 0xbfb8aa3b, v0
	v_exp_f32_e32 v0, v0
	s_nop 0
	v_add_f32_e32 v0, 1.0, v0
	v_rcp_f32_e32 v147, v0
	v_lshlrev_b32_e32 v0, 16, v144
	v_mul_f32_e32 v0, 0xbfb8aa3b, v0
	v_exp_f32_e32 v0, v0
	v_pk_mul_f32 v[146:147], v[32:33], v[146:147]
	v_add_f32_e32 v0, 1.0, v0
	v_cvt_pk_bf16_f32 v143, v146, v147
	v_rcp_f32_e32 v146, v0
	v_and_b32_e32 v0, 0xffff0000, v144
	v_mul_f32_e32 v0, 0xbfb8aa3b, v0
	v_exp_f32_e32 v0, v0
	s_nop 0
	v_add_f32_e32 v0, 1.0, v0
	v_rcp_f32_e32 v147, v0
	v_lshlrev_b32_e32 v0, 16, v145
	v_mul_f32_e32 v0, 0xbfb8aa3b, v0
	v_exp_f32_e32 v0, v0
	v_pk_mul_f32 v[146:147], v[26:27], v[146:147]
	v_add_f32_e32 v0, 1.0, v0
	v_cvt_pk_bf16_f32 v144, v146, v147
	v_rcp_f32_e32 v146, v0
	v_and_b32_e32 v0, 0xffff0000, v145
	v_mul_f32_e32 v0, 0xbfb8aa3b, v0
	v_exp_f32_e32 v0, v0
	s_nop 0
	v_add_f32_e32 v0, 1.0, v0
	v_rcp_f32_e32 v147, v0
	v_lshlrev_b32_e32 v0, 16, v138
	v_mul_f32_e32 v0, 0xbfb8aa3b, v0
	v_exp_f32_e32 v0, v0
	v_pk_mul_f32 v[146:147], v[28:29], v[146:147]
	v_add_f32_e32 v0, 1.0, v0
	v_cvt_pk_bf16_f32 v145, v146, v147
	s_waitcnt lgkmcnt(0)
; __device__ __forceinline__ unsigned cvt_pk_bf16(float lo, float hi) { f32x2 v = {lo, hi}; bf16x2_t b = __builtin_convertvector(v, bf16x2_t); return __builtin_bit_cast(unsigned, b); }
; __device__ __forceinline__ float bf_lo(unsigned w) { return __uint_as_float(w << 16); }
; __device__ __forceinline__ float bf_hi(unsigned w) { return __uint_as_float(w & 0xffff0000u); }
; __device__ __forceinline__ float sigm(float v) { return __builtin_amdgcn_rcpf(1.0f + __builtin_amdgcn_exp2f(-1.44269504089f * v)); }
; __device__ __forceinline__ void epi_run(const Epi& E, f32x4 (&acc)[2][2][4][2], const Unit& u, int wr, int wc, int fr, int fq) {
;     ...
; #pragma unroll
;         for (int ai = 0; ai < 2; ++ai)
; #pragma unroll
;             for (int m = 0; m < 4; ++m)
; #pragma unroll
;                 for (int bj = 0; bj < 2; ++bj) { const f32x4 v0 = acc[ai][bj][m][0], v1 = acc[ai][bj][m][1]; const u32x4 gg = g[ai][m][bj]; u32x4 w;
;                     w.x = cvt_pk_bf16(v0[0] * sigm(bf_lo(gg.x)), v0[1] * sigm(bf_hi(gg.x))); w.y = cvt_pk_bf16(v0[2] * sigm(bf_lo(gg.y)), v0[3] * sigm(bf_hi(gg.y)));
;                     w.z = cvt_pk_bf16(v1[0] * sigm(bf_lo(gg.z)), v1[1] * sigm(bf_hi(gg.z))); w.w = cvt_pk_bf16(v1[2] * sigm(bf_lo(gg.w)), v1[3] * sigm(bf_hi(gg.w)));
;                     *(u32x4*)(E.Z + (size_t)(row0 + ai * 128 + m * 16) * NIN + 3072 + col0 + bj * 128) = w; }
	global_store_dwordx4 v[214:215], v[244:247], off offset:2304
	v_lshl_add_u64 v[192:193], v[192:193], 0, v[248:249]
	ds_bpermute_b32 v244, v243, v142
	ds_bpermute_b32 v245, v243, v143
	ds_bpermute_b32 v246, v243, v144
	ds_bpermute_b32 v247, v243, v145
	s_nop 1
	v_rcp_f32_e32 v142, v0
	v_and_b32_e32 v0, 0xffff0000, v138
	v_mul_f32_e32 v0, 0xbfb8aa3b, v0
	v_exp_f32_e32 v0, v0
	s_nop 0
	v_add_f32_e32 v0, 1.0, v0
	v_rcp_f32_e32 v143, v0
	v_lshlrev_b32_e32 v0, 16, v139
	v_mul_f32_e32 v0, 0xbfb8aa3b, v0
	v_exp_f32_e32 v0, v0
	v_pk_mul_f32 v[142:143], v[22:23], v[142:143]
	v_add_f32_e32 v0, 1.0, v0
	v_cvt_pk_bf16_f32 v138, v142, v143
	v_rcp_f32_e32 v142, v0
	v_and_b32_e32 v0, 0xffff0000, v139
	v_mul_f32_e32 v0, 0xbfb8aa3b, v0
	v_exp_f32_e32 v0, v0
	s_nop 0
	v_add_f32_e32 v0, 1.0, v0
	v_rcp_f32_e32 v143, v0
	v_lshlrev_b32_e32 v0, 16, v140
	v_mul_f32_e32 v0, 0xbfb8aa3b, v0
	v_exp_f32_e32 v0, v0
	v_pk_mul_f32 v[142:143], v[24:25], v[142:143]
	v_add_f32_e32 v0, 1.0, v0
	v_cvt_pk_bf16_f32 v139, v142, v143
	v_rcp_f32_e32 v142, v0
	v_and_b32_e32 v0, 0xffff0000, v140
	v_mul_f32_e32 v0, 0xbfb8aa3b, v0
	v_exp_f32_e32 v0, v0
	s_nop 0
	v_add_f32_e32 v0, 1.0, v0
	v_rcp_f32_e32 v143, v0
	v_lshlrev_b32_e32 v0, 16, v141
	v_mul_f32_e32 v0, 0xbfb8aa3b, v0
	v_exp_f32_e32 v0, v0
	v_pk_mul_f32 v[142:143], v[18:19], v[142:143]
	v_add_f32_e32 v0, 1.0, v0
	v_cvt_pk_bf16_f32 v140, v142, v143
	v_rcp_f32_e32 v142, v0
	v_and_b32_e32 v0, 0xffff0000, v141
	v_mul_f32_e32 v0, 0xbfb8aa3b, v0
	v_exp_f32_e32 v0, v0
	s_nop 0
	v_add_f32_e32 v0, 1.0, v0
	v_rcp_f32_e32 v143, v0
	v_lshlrev_b32_e32 v0, 16, v134
	v_mul_f32_e32 v0, 0xbfb8aa3b, v0
	v_exp_f32_e32 v0, v0
	v_pk_mul_f32 v[142:143], v[20:21], v[142:143]
	v_add_f32_e32 v0, 1.0, v0
	v_cvt_pk_bf16_f32 v141, v142, v143
	s_waitcnt lgkmcnt(0)
	global_store_dwordx4 v[192:193], v[244:247], off offset:2048
	s_nop 1
	ds_bpermute_b32 v244, v243, v138
	ds_bpermute_b32 v245, v243, v139
	ds_bpermute_b32 v246, v243, v140
	ds_bpermute_b32 v247, v243, v141
	s_nop 1
	v_rcp_f32_e32 v138, v0
	v_and_b32_e32 v0, 0xffff0000, v134
	v_mul_f32_e32 v0, 0xbfb8aa3b, v0
	v_exp_f32_e32 v0, v0
	s_nop 0
	v_add_f32_e32 v0, 1.0, v0
	v_rcp_f32_e32 v139, v0
	v_lshlrev_b32_e32 v0, 16, v135
	v_mul_f32_e32 v0, 0xbfb8aa3b, v0
	v_exp_f32_e32 v0, v0
	v_pk_mul_f32 v[138:139], v[14:15], v[138:139]
	v_add_f32_e32 v0, 1.0, v0
	v_cvt_pk_bf16_f32 v134, v138, v139
	v_rcp_f32_e32 v138, v0
	v_and_b32_e32 v0, 0xffff0000, v135
	v_mul_f32_e32 v0, 0xbfb8aa3b, v0
	v_exp_f32_e32 v0, v0
	s_nop 0
	v_add_f32_e32 v0, 1.0, v0
	v_rcp_f32_e32 v139, v0
	v_lshlrev_b32_e32 v0, 16, v136
	v_mul_f32_e32 v0, 0xbfb8aa3b, v0
	v_exp_f32_e32 v0, v0
	v_pk_mul_f32 v[138:139], v[16:17], v[138:139]
	v_add_f32_e32 v0, 1.0, v0
	v_cvt_pk_bf16_f32 v135, v138, v139
	v_rcp_f32_e32 v138, v0
	v_and_b32_e32 v0, 0xffff0000, v136
	v_mul_f32_e32 v0, 0xbfb8aa3b, v0
	v_exp_f32_e32 v0, v0
	s_nop 0
	v_add_f32_e32 v0, 1.0, v0
	v_rcp_f32_e32 v139, v0
	v_lshlrev_b32_e32 v0, 16, v137
	v_mul_f32_e32 v0, 0xbfb8aa3b, v0
	v_exp_f32_e32 v0, v0
	v_pk_mul_f32 v[138:139], v[10:11], v[138:139]
	v_add_f32_e32 v0, 1.0, v0
	v_cvt_pk_bf16_f32 v136, v138, v139
	v_rcp_f32_e32 v138, v0
	v_and_b32_e32 v0, 0xffff0000, v137
	v_mul_f32_e32 v0, 0xbfb8aa3b, v0
	v_exp_f32_e32 v0, v0
	s_nop 0
	v_add_f32_e32 v0, 1.0, v0
	v_rcp_f32_e32 v139, v0
	v_lshlrev_b32_e32 v0, 16, v130
	v_mul_f32_e32 v0, 0xbfb8aa3b, v0
	v_exp_f32_e32 v0, v0
	v_pk_mul_f32 v[138:139], v[12:13], v[138:139]
	v_add_f32_e32 v0, 1.0, v0
	v_cvt_pk_bf16_f32 v137, v138, v139
	s_waitcnt lgkmcnt(0)
	global_store_dwordx4 v[192:193], v[244:247], off offset:2304
	v_lshl_add_u64 v[190:191], v[190:191], 0, v[248:249]
	ds_bpermute_b32 v244, v243, v134
	ds_bpermute_b32 v245, v243, v135
	ds_bpermute_b32 v246, v243, v136
	ds_bpermute_b32 v247, v243, v137
	s_nop 1
	v_rcp_f32_e32 v134, v0
	v_and_b32_e32 v0, 0xffff0000, v130
	v_mul_f32_e32 v0, 0xbfb8aa3b, v0
	v_exp_f32_e32 v0, v0
	s_nop 0
	v_add_f32_e32 v0, 1.0, v0
	v_rcp_f32_e32 v135, v0
	v_lshlrev_b32_e32 v0, 16, v131
	v_mul_f32_e32 v0, 0xbfb8aa3b, v0
	v_exp_f32_e32 v0, v0
	v_pk_mul_f32 v[134:135], v[6:7], v[134:135]
	v_add_f32_e32 v0, 1.0, v0
	v_cvt_pk_bf16_f32 v130, v134, v135
	v_rcp_f32_e32 v134, v0
	v_and_b32_e32 v0, 0xffff0000, v131
	v_mul_f32_e32 v0, 0xbfb8aa3b, v0
	v_exp_f32_e32 v0, v0
	s_nop 0
	v_add_f32_e32 v0, 1.0, v0
	v_rcp_f32_e32 v135, v0
	v_lshlrev_b32_e32 v0, 16, v132
	v_mul_f32_e32 v0, 0xbfb8aa3b, v0
	v_exp_f32_e32 v0, v0
	v_pk_mul_f32 v[134:135], v[8:9], v[134:135]
	v_add_f32_e32 v0, 1.0, v0
	v_cvt_pk_bf16_f32 v131, v134, v135
	v_rcp_f32_e32 v134, v0
	v_and_b32_e32 v0, 0xffff0000, v132
	v_mul_f32_e32 v0, 0xbfb8aa3b, v0
	v_exp_f32_e32 v0, v0
	s_nop 0
	v_add_f32_e32 v0, 1.0, v0
	v_rcp_f32_e32 v135, v0
	v_lshlrev_b32_e32 v0, 16, v133
	v_mul_f32_e32 v0, 0xbfb8aa3b, v0
	v_exp_f32_e32 v0, v0
	v_pk_mul_f32 v[134:135], v[2:3], v[134:135]
	v_add_f32_e32 v0, 1.0, v0
	v_cvt_pk_bf16_f32 v132, v134, v135
	v_rcp_f32_e32 v134, v0
	v_and_b32_e32 v0, 0xffff0000, v133
	v_mul_f32_e32 v0, 0xbfb8aa3b, v0
	v_exp_f32_e32 v0, v0
	s_nop 0
	v_add_f32_e32 v0, 1.0, v0
	v_rcp_f32_e32 v135, v0
	s_nop 0
	v_pk_mul_f32 v[134:135], v[4:5], v[134:135]
	s_nop 0
	v_cvt_pk_bf16_f32 v133, v134, v135
	s_waitcnt lgkmcnt(0)
	global_store_dwordx4 v[190:191], v[244:247], off offset:2048
	s_nop 1
	ds_bpermute_b32 v244, v243, v130
	ds_bpermute_b32 v245, v243, v131
	ds_bpermute_b32 v246, v243, v132
	ds_bpermute_b32 v247, v243, v133
	s_waitcnt lgkmcnt(0)
	global_store_dwordx4 v[190:191], v[244:247], off offset:2304

; __device__ __forceinline__ float bf_lo(unsigned w) { return __uint_as_float(w << 16); }
; __device__ __forceinline__ float bf_hi(unsigned w) { return __uint_as_float(w & 0xffff0000u); }
; __device__ __forceinline__ float sigm(float v) { return __builtin_amdgcn_rcpf(1.0f + __builtin_amdgcn_exp2f(-1.44269504089f * v)); }
; __device__ __forceinline__ u32x4 pack8(const f32x4& v0, const f32x4& v1) { u32x4 w; w.x = cvt_pk_bf16(v0[0], v0[1]); w.y = cvt_pk_bf16(v0[2], v0[3]); w.z = cvt_pk_bf16(v1[0], v1[1]); w.w = cvt_pk_bf16(v1[2], v1[3]); return w; }
; __device__ __forceinline__ float sumsq8(const f32x4& v0, const f32x4& v1) { return (v0[0] * v0[0] + v0[1] * v0[1]) + (v0[2] * v0[2] + v0[3] * v0[3]) + (v1[0] * v1[0] + v1[1] * v1[1]) + (v1[2] * v1[2] + v1[3] * v1[3]); }
; __device__ __forceinline__ void epi_run(const Epi& E, f32x4 (&acc)[2][2][4][2], const Unit& u, int wr, int wc, int fr, int fq) {
;     ...
;                 for (int mm = 0; mm < 2; ++mm) { const int m = 2 * mh + mm, row = row0 + ai * 128 + m * 16; float sq = 0.f;
; #pragma unroll
;                     for (int bj = 0; bj < 2; ++bj) { const u32x4 xx = x[mm][bj], cc = c[mm][bj];
;                         const f32x4 c0 = (f32x4){bf_lo(cc.x), bf_hi(cc.x), bf_lo(cc.y), bf_hi(cc.y)}, c1 = (f32x4){bf_lo(cc.z), bf_hi(cc.z), bf_lo(cc.w), bf_hi(cc.w)};
;                         f32x4 v0 = acc[ai][bj][m][0] * rs[ai][m], v1 = acc[ai][bj][m][1] * rs[ai][m];
; #pragma unroll
;                         for (int e = 0; e < 4; ++e) { v0[e] = sigm(v0[e]) * c0[e]; v1[e] = sigm(v1[e]) * c1[e]; }
;                         const f32x4 x0 = (f32x4){bf_lo(xx.x), bf_hi(xx.x), bf_lo(xx.y), bf_hi(xx.y)} + v0, x1 = (f32x4){bf_lo(xx.z), bf_hi(xx.z), bf_lo(xx.w), bf_hi(xx.w)} + v1;
;                         sq += sumsq8(x0, x1); *(u32x4*)(E.xout16 + (size_t)row * D + col0 + bj * 128) = pack8(x0, x1); }
;                     sq += __shfl_xor(sq, 16); sq += __shfl_xor(sq, 32); if (fq == 0) sslot[row] = sq; }
.LBB0_311:
	s_or_b64 exec, exec, s[8:9]
	v_add_f32_e32 v148, v151, v152
	v_fmamk_f32 v148, v148, 0x3a800000, v197
	v_rsq_f32_e32 v148, v148
	s_waitcnt lgkmcnt(0)
	global_store_dwordx4 v[228:229], v[222:225], off offset:256
	s_waitcnt vmcnt(3)
	v_lshlrev_b32_e32 v160, 16, v142
	v_and_b32_e32 v161, 0xffff0000, v142
	v_lshlrev_b32_e32 v162, 16, v144
	s_waitcnt lgkmcnt(0)
	v_pk_mul_f32 v[154:155], v[110:111], v[148:149] op_sel_hi:[1,0]
	v_pk_mul_f32 v[152:153], v[112:113], v[148:149] op_sel_hi:[1,0]
	v_pk_mul_f32 v[156:157], v[108:109], v[148:149] op_sel_hi:[1,0]
	v_mul_f32_e32 v149, 0xbfb8aa3b, v154
	v_exp_f32_e32 v149, v149
	v_mul_f32_e32 v154, 0xbfb8aa3b, v155
	v_exp_f32_e32 v155, v154
	v_and_b32_e32 v163, 0xffff0000, v144
	v_pk_mul_f32 v[158:159], v[106:107], v[148:149] op_sel_hi:[1,0]
	v_add_f32_e32 v149, 1.0, v149
	v_mul_f32_e32 v151, 0xbfb8aa3b, v158
	v_exp_f32_e32 v151, v151
	v_rcp_f32_e32 v154, v149
	v_mul_f32_e32 v144, 0xbfb8aa3b, v156
	v_exp_f32_e32 v144, v144
	v_add_f32_e32 v149, 1.0, v151
	v_rcp_f32_e32 v158, v149
	v_add_f32_e32 v149, 1.0, v155
	v_mul_f32_e32 v151, 0xbfb8aa3b, v159
	v_exp_f32_e32 v151, v151
	v_rcp_f32_e32 v155, v149
	v_mul_f32_e32 v149, 0xbfb8aa3b, v152
	v_exp_f32_e32 v149, v149
	v_add_f32_e32 v142, 1.0, v151
	v_rcp_f32_e32 v159, v142
	v_lshlrev_b32_e32 v156, 16, v143
	v_add_f32_e32 v142, 1.0, v149
	v_mul_f32_e32 v149, 0xbfb8aa3b, v153
	v_exp_f32_e32 v149, v149
	v_rcp_f32_e32 v152, v142
	v_add_f32_e32 v142, 1.0, v144
	v_rcp_f32_e32 v142, v142
	v_add_f32_e32 v144, 1.0, v149
	v_mul_f32_e32 v149, 0xbfb8aa3b, v157
	v_exp_f32_e32 v149, v149
	v_rcp_f32_e32 v153, v144
	v_and_b32_e32 v157, 0xffff0000, v143
	v_lshlrev_b32_e32 v164, 16, v138
	v_add_f32_e32 v143, 1.0, v149
	v_rcp_f32_e32 v143, v143
	v_and_b32_e32 v165, 0xffff0000, v138
	v_lshlrev_b32_e32 v138, 16, v139
	v_and_b32_e32 v139, 0xffff0000, v139
	v_lshlrev_b32_e32 v144, 16, v145
	v_and_b32_e32 v145, 0xffff0000, v145
	v_pk_fma_f32 v[152:153], v[152:153], v[156:157], v[138:139]
	v_pk_fma_f32 v[138:139], v[154:155], v[160:161], v[164:165]
	v_lshlrev_b32_e32 v154, 16, v140
	v_and_b32_e32 v155, 0xffff0000, v140
	v_lshlrev_b32_e32 v140, 16, v141
	v_and_b32_e32 v141, 0xffff0000, v141
	v_pk_fma_f32 v[142:143], v[142:143], v[144:145], v[140:141]
	v_mul_f32_e32 v144, v139, v139
	v_mul_f32_e32 v145, v153, v153
	v_pk_fma_f32 v[140:141], v[158:159], v[162:163], v[154:155]
	v_fmac_f32_e32 v144, v138, v138
	v_fmac_f32_e32 v145, v152, v152
	v_add_f32_e32 v144, v144, v145
	v_mul_f32_e32 v145, v141, v141
	v_fmac_f32_e32 v145, v140, v140
	v_add_f32_e32 v144, v145, v144
	v_mul_f32_e32 v145, v143, v143
	v_fmac_f32_e32 v145, v142, v142
	v_add_f32_e32 v151, v145, v144
	v_cvt_pk_bf16_f32 v138, v138, v139
	v_cvt_pk_bf16_f32 v139, v152, v153
	v_cvt_pk_bf16_f32 v140, v140, v141
	v_cvt_pk_bf16_f32 v141, v142, v143
	v_pk_mul_f32 v[142:143], v[102:103], v[148:149] op_sel_hi:[1,0]
	v_pk_mul_f32 v[144:145], v[104:105], v[148:149] op_sel_hi:[1,0]
	v_pk_mul_f32 v[152:153], v[96:97], v[148:149] op_sel_hi:[1,0]
	v_pk_mul_f32 v[148:149], v[94:95], v[148:149] op_sel_hi:[1,0]
	v_mul_f32_e32 v144, 0xbfb8aa3b, v144
	v_mul_f32_e32 v149, 0xbfb8aa3b, v149
	v_exp_f32_e32 v149, v149
	v_exp_f32_e32 v144, v144
	s_waitcnt vmcnt(2)
	v_lshlrev_b32_e32 v154, 16, v134
	v_and_b32_e32 v155, 0xffff0000, v134
	v_add_f32_e32 v134, 1.0, v149
	v_rcp_f32_e32 v149, v134
	v_lshlrev_b32_e32 v156, 16, v136
	v_and_b32_e32 v157, 0xffff0000, v136
	v_add_f32_e32 v134, 1.0, v144
	v_mul_f32_e32 v136, 0xbfb8aa3b, v152
	v_mul_f32_e32 v144, 0xbfb8aa3b, v145
	v_exp_f32_e32 v136, v136
	v_exp_f32_e32 v145, v144
	v_mul_f32_e32 v142, 0xbfb8aa3b, v142
	v_mul_f32_e32 v143, 0xbfb8aa3b, v143
	v_exp_f32_e32 v142, v142
	v_exp_f32_e32 v143, v143
	v_rcp_f32_e32 v144, v134
	v_add_f32_e32 v134, 1.0, v136
	v_add_f32_e32 v136, 1.0, v145
	v_mul_f32_e32 v145, 0xbfb8aa3b, v153
	v_mul_f32_e32 v148, 0xbfb8aa3b, v148
	v_exp_f32_e32 v158, v145
	v_exp_f32_e32 v148, v148
	v_add_f32_e32 v142, 1.0, v142
	v_add_f32_e32 v143, 1.0, v143
	v_rcp_f32_e32 v142, v142
	v_rcp_f32_e32 v143, v143
	v_rcp_f32_e32 v145, v136
	v_lshlrev_b32_e32 v152, 16, v135
	v_and_b32_e32 v153, 0xffff0000, v135
	v_add_f32_e32 v135, 1.0, v158
	v_add_f32_e32 v148, 1.0, v148
	v_rcp_f32_e32 v134, v134
	v_rcp_f32_e32 v135, v135
	v_rcp_f32_e32 v148, v148
	v_lshlrev_b32_e32 v158, 16, v130
	v_and_b32_e32 v159, 0xffff0000, v130
	v_lshlrev_b32_e32 v130, 16, v131
	v_and_b32_e32 v131, 0xffff0000, v131
	v_lshlrev_b32_e32 v136, 16, v137
	v_and_b32_e32 v137, 0xffff0000, v137
	v_pk_fma_f32 v[144:145], v[144:145], v[152:153], v[130:131]
	v_pk_fma_f32 v[130:131], v[142:143], v[154:155], v[158:159]
	v_lshlrev_b32_e32 v142, 16, v132
	v_and_b32_e32 v143, 0xffff0000, v132
	v_lshlrev_b32_e32 v132, 16, v133
	v_and_b32_e32 v133, 0xffff0000, v133
	v_pk_fma_f32 v[136:137], v[134:135], v[136:137], v[132:133]
	v_mul_f32_e32 v132, v131, v131
	v_mul_f32_e32 v133, v145, v145
	v_pk_fma_f32 v[134:135], v[148:149], v[156:157], v[142:143]
	v_fmac_f32_e32 v132, v130, v130
	v_fmac_f32_e32 v133, v144, v144
	v_add_f32_e32 v132, v132, v133
	v_mul_f32_e32 v133, v135, v135
	v_fmac_f32_e32 v133, v134, v134
	v_add_f32_e32 v132, v133, v132
	v_mul_f32_e32 v133, v137, v137
	v_fmac_f32_e32 v133, v136, v136
	v_add_f32_e32 v132, v133, v132
	v_add_f32_e32 v148, v151, v132
	ds_bpermute_b32 v149, v171, v148
	v_lshlrev_b64 v[146:147], 11, v[146:147]
	v_lshl_add_u64 v[132:133], s[78:79], 0, v[146:147]
	v_lshl_add_u64 v[142:143], v[212:213], 1, v[132:133]
	v_cvt_pk_bf16_f32 v132, v130, v131
	s_waitcnt lgkmcnt(0)
	v_add_f32_e32 v130, v148, v149
	ds_bpermute_b32 v131, v170, v130
	v_cvt_pk_bf16_f32 v133, v144, v145
	v_cvt_pk_bf16_f32 v134, v134, v135
	v_cvt_pk_bf16_f32 v135, v136, v137
	v_lshl_add_u64 v[226:227], v[142:143], 0, v[230:231]
	ds_bpermute_b32 v218, v243, v138
	ds_bpermute_b32 v219, v243, v139
	ds_bpermute_b32 v220, v243, v140
	ds_bpermute_b32 v221, v243, v141
	s_waitcnt lgkmcnt(0)
	global_store_dwordx4 v[226:227], v[218:221], off
	v_lshl_add_u64 v[228:229], v[142:143], 0, v[230:231]
	ds_bpermute_b32 v222, v243, v132
	ds_bpermute_b32 v223, v243, v133
	ds_bpermute_b32 v224, v243, v134
	ds_bpermute_b32 v225, v243, v135
	s_and_saveexec_b64 s[8:9], s[40:41]
	s_cbranch_execz .LBB0_313
	v_lshl_add_u64 v[132:133], v[210:211], 2, s[44:45]
	s_waitcnt lgkmcnt(0)
	v_add_f32_e32 v130, v130, v131
	global_store_dword v[132:133], v130, off offset:64
; __device__ __forceinline__ float bf_lo(unsigned w) { return __uint_as_float(w << 16); }
; __device__ __forceinline__ float bf_hi(unsigned w) { return __uint_as_float(w & 0xffff0000u); }
; __device__ __forceinline__ float sigm(float v) { return __builtin_amdgcn_rcpf(1.0f + __builtin_amdgcn_exp2f(-1.44269504089f * v)); }
; __device__ __forceinline__ u32x4 pack8(const f32x4& v0, const f32x4& v1) { u32x4 w; w.x = cvt_pk_bf16(v0[0], v0[1]); w.y = cvt_pk_bf16(v0[2], v0[3]); w.z = cvt_pk_bf16(v1[0], v1[1]); w.w = cvt_pk_bf16(v1[2], v1[3]); return w; }
; __device__ __forceinline__ float sumsq8(const f32x4& v0, const f32x4& v1) { return (v0[0] * v0[0] + v0[1] * v0[1]) + (v0[2] * v0[2] + v0[3] * v0[3]) + (v1[0] * v1[0] + v1[1] * v1[1]) + (v1[2] * v1[2] + v1[3] * v1[3]); }
; __device__ __forceinline__ void epi_run(const Epi& E, f32x4 (&acc)[2][2][4][2], const Unit& u, int wr, int wc, int fr, int fq) {
;     ...
;             for (int mh = 0; mh < 2; ++mh) { u32x4 x[2][2], c[2][2];
; #pragma unroll
;                 for (int mm = 0; mm < 2; ++mm)
; #pragma unroll
;                     for (int bj = 0; bj < 2; ++bj) { const size_t off = (size_t)(row0 + ai * 128 + (2 * mh + mm) * 16) * D + col0 + bj * 128; x[mm][bj] = *(const u32x4*)(E.xin16 + off); c[mm][bj] = *(const u32x4*)(E.C16 + off); }
; #pragma unroll
;                 for (int mm = 0; mm < 2; ++mm) { const int m = 2 * mh + mm, row = row0 + ai * 128 + m * 16; float sq = 0.f;
; #pragma unroll
;                     for (int bj = 0; bj < 2; ++bj) { const u32x4 xx = x[mm][bj], cc = c[mm][bj];
;                         const f32x4 c0 = (f32x4){bf_lo(cc.x), bf_hi(cc.x), bf_lo(cc.y), bf_hi(cc.y)}, c1 = (f32x4){bf_lo(cc.z), bf_hi(cc.z), bf_lo(cc.w), bf_hi(cc.w)};
;                         f32x4 v0 = acc[ai][bj][m][0] * rs[ai][m], v1 = acc[ai][bj][m][1] * rs[ai][m];
; #pragma unroll
;                         for (int e = 0; e < 4; ++e) { v0[e] = sigm(v0[e]) * c0[e]; v1[e] = sigm(v1[e]) * c1[e]; }
;                         const f32x4 x0 = (f32x4){bf_lo(xx.x), bf_hi(xx.x), bf_lo(xx.y), bf_hi(xx.y)} + v0, x1 = (f32x4){bf_lo(xx.z), bf_hi(xx.z), bf_lo(xx.w), bf_hi(xx.w)} + v1;
;                         sq += sumsq8(x0, x1); *(u32x4*)(E.xout16 + (size_t)row * D + col0 + bj * 128) = pack8(x0, x1); }
;                     sq += __shfl_xor(sq, 16); sq += __shfl_xor(sq, 32); if (fq == 0) sslot[row] = sq; }
.LBB0_313:
	s_or_b64 exec, exec, s[8:9]
	v_or_b32_e32 v164, 32, v210
	v_ashrrev_i32_e32 v165, 31, v164
	s_waitcnt lgkmcnt(0)
	v_lshlrev_b64 v[130:131], 10, v[164:165]
	v_lshl_add_u64 v[130:131], v[130:131], 0, v[212:213]
	v_lshlrev_b64 v[130:131], 1, v[130:131]
	v_lshl_add_u64 v[132:133], s[48:49], 0, v[130:131]
	v_lshl_add_u64 v[134:135], s[62:63], 0, v[130:131]
	global_load_dwordx4 v[154:157], v[132:133], off
	global_load_dwordx4 v[158:161], v[134:135], off
	global_load_dwordx4 v[146:149], v[132:133], off offset:256
	v_or_b32_e32 v130, 0x100, v130
	v_lshl_add_u64 v[130:131], s[62:63], 0, v[130:131]
	v_add_f32_e32 v0, v0, v150
	global_load_dwordx4 v[150:153], v[130:131], off
	v_fmamk_f32 v0, v0, 0x3a800000, v197
	v_rsq_f32_e32 v0, v0
	v_or_b32_e32 v162, 48, v210
	v_ashrrev_i32_e32 v163, 31, v162
	v_lshlrev_b64 v[130:131], 10, v[162:163]
	v_pk_mul_f32 v[166:167], v[98:99], v[0:1] op_sel_hi:[1,0]
	v_pk_mul_f32 v[186:187], v[90:91], v[0:1] op_sel_hi:[1,0]
	v_mul_f32_e32 v167, 0xbfb8aa3b, v167
	v_exp_f32_e32 v167, v167
	v_pk_mul_f32 v[182:183], v[100:101], v[0:1] op_sel_hi:[1,0]
	v_mul_f32_e32 v166, 0xbfb8aa3b, v166
	v_exp_f32_e32 v166, v166
	v_add_f32_e32 v167, 1.0, v167
	v_rcp_f32_e32 v169, v167
	v_pk_mul_f32 v[184:185], v[92:93], v[0:1] op_sel_hi:[1,0]
	v_add_f32_e32 v166, 1.0, v166
	v_rcp_f32_e32 v168, v166
	v_mul_f32_e32 v166, 0xbfb8aa3b, v186
	v_exp_f32_e32 v166, v166
	v_lshl_add_u64 v[130:131], v[130:131], 0, v[212:213]
	v_lshlrev_b64 v[134:135], 1, v[130:131]
	v_lshl_add_u64 v[130:131], s[48:49], 0, v[134:135]
	v_add_f32_e32 v166, 1.0, v166
	v_rcp_f32_e32 v166, v166
	v_lshl_add_u64 v[132:133], s[62:63], 0, v[134:135]
	v_or_b32_e32 v134, 0x100, v134
	v_lshl_add_u64 v[134:135], s[62:63], 0, v[134:135]
	global_load_dwordx4 v[138:141], v[130:131], off
	global_load_dwordx4 v[142:145], v[132:133], off
	s_nop 0
	global_load_dwordx4 v[130:133], v[130:131], off offset:256
	v_lshlrev_b64 v[164:165], 11, v[164:165]
	global_load_dwordx4 v[134:137], v[134:135], off
	s_waitcnt lgkmcnt(0)
	global_store_dwordx4 v[228:229], v[222:225], off offset:256
	s_waitcnt vmcnt(6)
	v_lshlrev_b32_e32 v188, 16, v158
	v_and_b32_e32 v189, 0xffff0000, v158
	v_mul_f32_e32 v158, 0xbfb8aa3b, v187
	v_exp_f32_e32 v158, v158
	v_lshlrev_b32_e32 v186, 16, v160
	v_and_b32_e32 v187, 0xffff0000, v160
	v_mul_f32_e32 v160, 0xbfb8aa3b, v183
	v_add_f32_e32 v158, 1.0, v158
	v_rcp_f32_e32 v167, v158
	v_mul_f32_e32 v158, 0xbfb8aa3b, v182
	v_exp_f32_e32 v158, v158
	v_exp_f32_e32 v160, v160
	v_lshlrev_b32_e32 v190, 16, v159
	v_and_b32_e32 v191, 0xffff0000, v159
	v_add_f32_e32 v158, 1.0, v158
	v_rcp_f32_e32 v182, v158
	v_mul_f32_e32 v158, 0xbfb8aa3b, v184
	v_mul_f32_e32 v159, 0xbfb8aa3b, v185
	v_exp_f32_e32 v158, v158
	v_exp_f32_e32 v159, v159
	v_add_f32_e32 v160, 1.0, v160
	v_rcp_f32_e32 v183, v160
	v_add_f32_e32 v158, 1.0, v158
	v_add_f32_e32 v159, 1.0, v159
	v_rcp_f32_e32 v158, v158
	v_rcp_f32_e32 v159, v159
	v_lshlrev_b32_e32 v184, 16, v154
	v_and_b32_e32 v185, 0xffff0000, v154
	v_lshlrev_b32_e32 v154, 16, v155
	v_and_b32_e32 v155, 0xffff0000, v155
	v_lshlrev_b32_e32 v160, 16, v161
	v_and_b32_e32 v161, 0xffff0000, v161
	v_pk_fma_f32 v[154:155], v[182:183], v[190:191], v[154:155]
	v_pk_fma_f32 v[168:169], v[168:169], v[188:189], v[184:185]
	v_lshlrev_b32_e32 v182, 16, v156
	v_and_b32_e32 v183, 0xffff0000, v156
	v_lshlrev_b32_e32 v156, 16, v157
	v_and_b32_e32 v157, 0xffff0000, v157
	v_pk_fma_f32 v[160:161], v[158:159], v[160:161], v[156:157]
	v_mul_f32_e32 v156, v169, v169
	v_mul_f32_e32 v157, v155, v155
	v_pk_fma_f32 v[158:159], v[166:167], v[186:187], v[182:183]
	v_fmac_f32_e32 v156, v168, v168
	v_fmac_f32_e32 v157, v154, v154
	v_add_f32_e32 v156, v156, v157
	v_mul_f32_e32 v157, v159, v159
	v_fmac_f32_e32 v157, v158, v158
	v_add_f32_e32 v156, v157, v156
	v_mul_f32_e32 v157, v161, v161
	v_fmac_f32_e32 v157, v160, v160
	v_add_f32_e32 v184, v157, v156
	v_cvt_pk_bf16_f32 v157, v154, v155
	v_lshl_add_u64 v[154:155], s[78:79], 0, v[164:165]
	v_cvt_pk_bf16_f32 v156, v168, v169
	v_cvt_pk_bf16_f32 v158, v158, v159
	v_cvt_pk_bf16_f32 v159, v160, v161
	v_lshl_add_u64 v[154:155], v[212:213], 1, v[154:155]
	v_lshl_add_u64 v[226:227], v[154:155], 0, v[230:231]
	ds_bpermute_b32 v218, v243, v156
	ds_bpermute_b32 v219, v243, v157
	ds_bpermute_b32 v220, v243, v158
	ds_bpermute_b32 v221, v243, v159
	v_pk_mul_f32 v[160:161], v[80:81], v[0:1] op_sel_hi:[1,0]
	v_pk_mul_f32 v[164:165], v[78:79], v[0:1] op_sel_hi:[1,0]
	v_pk_mul_f32 v[158:159], v[86:87], v[0:1] op_sel_hi:[1,0]
	v_pk_mul_f32 v[156:157], v[88:89], v[0:1] op_sel_hi:[1,0]
	v_mul_f32_e32 v0, 0xbfb8aa3b, v158
	v_exp_f32_e32 v0, v0
	s_waitcnt lgkmcnt(0)
	global_store_dwordx4 v[226:227], v[218:221], off
	s_waitcnt vmcnt(5)
; __device__ __forceinline__ float bf_lo(unsigned w) { return __uint_as_float(w << 16); }
; __device__ __forceinline__ float bf_hi(unsigned w) { return __uint_as_float(w & 0xffff0000u); }
; __device__ __forceinline__ float sigm(float v) { return __builtin_amdgcn_rcpf(1.0f + __builtin_amdgcn_exp2f(-1.44269504089f * v)); }
; __device__ __forceinline__ u32x4 pack8(const f32x4& v0, const f32x4& v1) { u32x4 w; w.x = cvt_pk_bf16(v0[0], v0[1]); w.y = cvt_pk_bf16(v0[2], v0[3]); w.z = cvt_pk_bf16(v1[0], v1[1]); w.w = cvt_pk_bf16(v1[2], v1[3]); return w; }
; __device__ __forceinline__ float sumsq8(const f32x4& v0, const f32x4& v1) { return (v0[0] * v0[0] + v0[1] * v0[1]) + (v0[2] * v0[2] + v0[3] * v0[3]) + (v1[0] * v1[0] + v1[1] * v1[1]) + (v1[2] * v1[2] + v1[3] * v1[3]); }
; __device__ __forceinline__ void epi_run(const Epi& E, f32x4 (&acc)[2][2][4][2], const Unit& u, int wr, int wc, int fr, int fq) {
;     ...
;                 for (int mm = 0; mm < 2; ++mm) { const int m = 2 * mh + mm, row = row0 + ai * 128 + m * 16; float sq = 0.f;
; #pragma unroll
;                     for (int bj = 0; bj < 2; ++bj) { const u32x4 xx = x[mm][bj], cc = c[mm][bj];
;                         const f32x4 c0 = (f32x4){bf_lo(cc.x), bf_hi(cc.x), bf_lo(cc.y), bf_hi(cc.y)}, c1 = (f32x4){bf_lo(cc.z), bf_hi(cc.z), bf_lo(cc.w), bf_hi(cc.w)};
;                         f32x4 v0 = acc[ai][bj][m][0] * rs[ai][m], v1 = acc[ai][bj][m][1] * rs[ai][m];
; #pragma unroll
;                         for (int e = 0; e < 4; ++e) { v0[e] = sigm(v0[e]) * c0[e]; v1[e] = sigm(v1[e]) * c1[e]; }
;                         const f32x4 x0 = (f32x4){bf_lo(xx.x), bf_hi(xx.x), bf_lo(xx.y), bf_hi(xx.y)} + v0, x1 = (f32x4){bf_lo(xx.z), bf_hi(xx.z), bf_lo(xx.w), bf_hi(xx.w)} + v1;
;                         sq += sumsq8(x0, x1); *(u32x4*)(E.xout16 + (size_t)row * D + col0 + bj * 128) = pack8(x0, x1); }
;                     sq += __shfl_xor(sq, 16); sq += __shfl_xor(sq, 32); if (fq == 0) sslot[row] = sq; }
	v_lshlrev_b32_e32 v166, 16, v150
	v_and_b32_e32 v167, 0xffff0000, v150
	v_lshlrev_b32_e32 v182, 16, v151
	v_add_f32_e32 v0, 1.0, v0
	v_rcp_f32_e32 v158, v0
	v_mul_f32_e32 v0, 0xbfb8aa3b, v164
	v_exp_f32_e32 v0, v0
	v_and_b32_e32 v183, 0xffff0000, v151
	v_lshlrev_b32_e32 v168, 16, v152
	v_and_b32_e32 v169, 0xffff0000, v152
	v_add_f32_e32 v0, 1.0, v0
	v_rcp_f32_e32 v164, v0
	v_mul_f32_e32 v0, 0xbfb8aa3b, v159
	v_exp_f32_e32 v0, v0
	v_lshlrev_b32_e32 v152, 16, v153
	v_and_b32_e32 v153, 0xffff0000, v153
	v_add_f32_e32 v0, 1.0, v0
	v_rcp_f32_e32 v159, v0
	v_mul_f32_e32 v0, 0xbfb8aa3b, v165
	v_exp_f32_e32 v0, v0
	s_nop 0
	v_add_f32_e32 v0, 1.0, v0
	v_rcp_f32_e32 v165, v0
	v_mul_f32_e32 v0, 0xbfb8aa3b, v156
	v_exp_f32_e32 v0, v0
	s_nop 0
	v_add_f32_e32 v0, 1.0, v0
	v_rcp_f32_e32 v156, v0
	v_mul_f32_e32 v0, 0xbfb8aa3b, v160
	v_exp_f32_e32 v0, v0
	v_lshlrev_b32_e32 v160, 16, v146
	v_add_f32_e32 v0, 1.0, v0
	v_rcp_f32_e32 v150, v0
	v_mul_f32_e32 v0, 0xbfb8aa3b, v157
	v_exp_f32_e32 v0, v0
	s_nop 0
	v_add_f32_e32 v0, 1.0, v0
	v_rcp_f32_e32 v157, v0
	v_mul_f32_e32 v0, 0xbfb8aa3b, v161
	v_exp_f32_e32 v0, v0
	v_and_b32_e32 v161, 0xffff0000, v146
	v_lshlrev_b32_e32 v146, 16, v147
	v_and_b32_e32 v147, 0xffff0000, v147
	v_add_f32_e32 v0, 1.0, v0
	v_rcp_f32_e32 v151, v0
	v_pk_fma_f32 v[156:157], v[156:157], v[182:183], v[146:147]
	v_pk_fma_f32 v[146:147], v[158:159], v[166:167], v[160:161]
	v_lshlrev_b32_e32 v158, 16, v148
	v_and_b32_e32 v159, 0xffff0000, v148
	v_lshlrev_b32_e32 v148, 16, v149
	v_and_b32_e32 v149, 0xffff0000, v149
	v_pk_fma_f32 v[150:151], v[150:151], v[152:153], v[148:149]
	v_mul_f32_e32 v0, v147, v147
	v_mul_f32_e32 v152, v157, v157
	v_pk_fma_f32 v[148:149], v[164:165], v[168:169], v[158:159]
	v_fmac_f32_e32 v0, v146, v146
	v_fmac_f32_e32 v152, v156, v156
	v_add_f32_e32 v0, v0, v152
	v_mul_f32_e32 v152, v149, v149
	v_fmac_f32_e32 v152, v148, v148
	v_add_f32_e32 v0, v152, v0
	v_mul_f32_e32 v152, v151, v151
	v_fmac_f32_e32 v152, v150, v150
	v_add_f32_e32 v0, v152, v0
	v_add_f32_e32 v0, v184, v0
	v_cvt_pk_bf16_f32 v146, v146, v147
	v_cvt_pk_bf16_f32 v147, v156, v157
	v_cvt_pk_bf16_f32 v148, v148, v149
	v_cvt_pk_bf16_f32 v149, v150, v151
	v_lshl_add_u64 v[228:229], v[154:155], 0, v[230:231]
	ds_bpermute_b32 v222, v243, v146
	ds_bpermute_b32 v223, v243, v147
	ds_bpermute_b32 v224, v243, v148
	ds_bpermute_b32 v225, v243, v149
	ds_bpermute_b32 v146, v171, v0
	s_waitcnt lgkmcnt(0)
	v_add_f32_e32 v0, v0, v146
	ds_bpermute_b32 v146, v170, v0
	s_and_saveexec_b64 s[8:9], s[40:41]
	s_cbranch_execz .LBB0_315
	v_lshl_add_u64 v[148:149], v[210:211], 2, s[44:45]
	s_waitcnt lgkmcnt(0)
	v_add_f32_e32 v0, v0, v146
	global_store_dword v[148:149], v0, off offset:128
.LBB0_315:
	s_or_b64 exec, exec, s[8:9]
	v_add_f32_e32 v0, v180, v181
	v_fmamk_f32 v0, v0, 0x3a800000, v197
	v_rsq_f32_e32 v0, v0
	s_waitcnt lgkmcnt(0)
	global_store_dwordx4 v[228:229], v[222:225], off offset:256
	s_waitcnt vmcnt(4)
	v_lshlrev_b32_e32 v156, 16, v142
	v_and_b32_e32 v157, 0xffff0000, v142
	v_lshlrev_b32_e32 v158, 16, v144
	v_pk_mul_f32 v[154:155], v[74:75], v[0:1] op_sel_hi:[1,0]
	v_pk_mul_f32 v[148:149], v[84:85], v[0:1] op_sel_hi:[1,0]
	v_mul_f32_e32 v155, 0xbfb8aa3b, v155
	v_exp_f32_e32 v155, v155
	v_mul_f32_e32 v148, 0xbfb8aa3b, v148
	v_exp_f32_e32 v148, v148
	v_pk_mul_f32 v[152:153], v[76:77], v[0:1] op_sel_hi:[1,0]
	v_add_f32_e32 v142, 1.0, v155
	v_rcp_f32_e32 v155, v142
	v_and_b32_e32 v159, 0xffff0000, v144
	v_add_f32_e32 v142, 1.0, v148
	v_mul_f32_e32 v144, 0xbfb8aa3b, v152
	v_mul_f32_e32 v148, 0xbfb8aa3b, v149
	v_exp_f32_e32 v144, v144
	v_exp_f32_e32 v149, v148
	v_pk_mul_f32 v[150:151], v[82:83], v[0:1] op_sel_hi:[1,0]
	v_rcp_f32_e32 v148, v142
	v_mul_f32_e32 v150, 0xbfb8aa3b, v150
	v_mul_f32_e32 v151, 0xbfb8aa3b, v151
	v_exp_f32_e32 v150, v150
	v_exp_f32_e32 v151, v151
	v_add_f32_e32 v142, 1.0, v144
	v_add_f32_e32 v144, 1.0, v149
	v_mul_f32_e32 v149, 0xbfb8aa3b, v153
	v_mul_f32_e32 v154, 0xbfb8aa3b, v154
	v_exp_f32_e32 v160, v149
	v_exp_f32_e32 v154, v154
	v_add_f32_e32 v150, 1.0, v150
	v_add_f32_e32 v151, 1.0, v151
	v_rcp_f32_e32 v150, v150
	v_rcp_f32_e32 v151, v151
	v_rcp_f32_e32 v149, v144
	v_lshlrev_b32_e32 v152, 16, v143
	v_and_b32_e32 v153, 0xffff0000, v143
	v_add_f32_e32 v143, 1.0, v160
	v_add_f32_e32 v154, 1.0, v154
	v_rcp_f32_e32 v142, v142
	v_rcp_f32_e32 v143, v143
	v_rcp_f32_e32 v154, v154
	v_lshlrev_b32_e32 v160, 16, v138
	v_and_b32_e32 v161, 0xffff0000, v138
	v_lshlrev_b32_e32 v138, 16, v139
	v_and_b32_e32 v139, 0xffff0000, v139
	v_lshlrev_b32_e32 v144, 16, v145
	v_and_b32_e32 v145, 0xffff0000, v145
	v_pk_fma_f32 v[148:149], v[148:149], v[152:153], v[138:139]
	v_pk_fma_f32 v[138:139], v[150:151], v[156:157], v[160:161]
	v_lshlrev_b32_e32 v150, 16, v140
	v_and_b32_e32 v151, 0xffff0000, v140
	v_lshlrev_b32_e32 v140, 16, v141
	v_and_b32_e32 v141, 0xffff0000, v141
	v_pk_fma_f32 v[142:143], v[142:143], v[144:145], v[140:141]
	v_mul_f32_e32 v144, v139, v139
	v_mul_f32_e32 v145, v149, v149
	v_pk_fma_f32 v[140:141], v[154:155], v[158:159], v[150:151]
	v_fmac_f32_e32 v144, v138, v138
	v_fmac_f32_e32 v145, v148, v148
	v_add_f32_e32 v144, v144, v145
	v_mul_f32_e32 v145, v141, v141
	v_fmac_f32_e32 v145, v140, v140
	v_add_f32_e32 v144, v145, v144
	v_mul_f32_e32 v145, v143, v143
	v_fmac_f32_e32 v145, v142, v142
	v_cvt_pk_bf16_f32 v140, v140, v141
	v_cvt_pk_bf16_f32 v141, v142, v143
	v_pk_mul_f32 v[142:143], v[70:71], v[0:1] op_sel_hi:[1,0]
	v_pk_mul_f32 v[150:151], v[66:67], v[0:1] op_sel_hi:[1,0]
	v_mul_f32_e32 v142, 0xbfb8aa3b, v142
	v_exp_f32_e32 v142, v142
	v_add_f32_e32 v158, v145, v144
	v_cvt_pk_bf16_f32 v138, v138, v139
	v_cvt_pk_bf16_f32 v139, v148, v149
	v_pk_mul_f32 v[144:145], v[72:73], v[0:1] op_sel_hi:[1,0]
	v_pk_mul_f32 v[148:149], v[68:69], v[0:1] op_sel_hi:[1,0]
	v_add_f32_e32 v0, 1.0, v142
	v_mul_f32_e32 v142, 0xbfb8aa3b, v150
	v_exp_f32_e32 v150, v142
	v_mul_f32_e32 v142, 0xbfb8aa3b, v143
	v_exp_f32_e32 v143, v142
	v_rcp_f32_e32 v142, v0
	v_add_f32_e32 v0, 1.0, v150
	v_rcp_f32_e32 v150, v0
	v_add_f32_e32 v0, 1.0, v143
	v_mul_f32_e32 v143, 0xbfb8aa3b, v151
	v_exp_f32_e32 v151, v143
	s_waitcnt vmcnt(2)
; __device__ __forceinline__ float bf_lo(unsigned w) { return __uint_as_float(w << 16); }
; __device__ __forceinline__ float bf_hi(unsigned w) { return __uint_as_float(w & 0xffff0000u); }
; __device__ __forceinline__ float sigm(float v) { return __builtin_amdgcn_rcpf(1.0f + __builtin_amdgcn_exp2f(-1.44269504089f * v)); }
; __device__ __forceinline__ u32x4 pack8(const f32x4& v0, const f32x4& v1) { u32x4 w; w.x = cvt_pk_bf16(v0[0], v0[1]); w.y = cvt_pk_bf16(v0[2], v0[3]); w.z = cvt_pk_bf16(v1[0], v1[1]); w.w = cvt_pk_bf16(v1[2], v1[3]); return w; }
; __device__ __forceinline__ float sumsq8(const f32x4& v0, const f32x4& v1) { return (v0[0] * v0[0] + v0[1] * v0[1]) + (v0[2] * v0[2] + v0[3] * v0[3]) + (v1[0] * v1[0] + v1[1] * v1[1]) + (v1[2] * v1[2] + v1[3] * v1[3]); }
; __device__ __forceinline__ void epi_run(const Epi& E, f32x4 (&acc)[2][2][4][2], const Unit& u, int wr, int wc, int fr, int fq) {
;     ...
;                 for (int mm = 0; mm < 2; ++mm) { const int m = 2 * mh + mm, row = row0 + ai * 128 + m * 16; float sq = 0.f;
; #pragma unroll
;                     for (int bj = 0; bj < 2; ++bj) { const u32x4 xx = x[mm][bj], cc = c[mm][bj];
;                         const f32x4 c0 = (f32x4){bf_lo(cc.x), bf_hi(cc.x), bf_lo(cc.y), bf_hi(cc.y)}, c1 = (f32x4){bf_lo(cc.z), bf_hi(cc.z), bf_lo(cc.w), bf_hi(cc.w)};
;                         f32x4 v0 = acc[ai][bj][m][0] * rs[ai][m], v1 = acc[ai][bj][m][1] * rs[ai][m];
; #pragma unroll
;                         for (int e = 0; e < 4; ++e) { v0[e] = sigm(v0[e]) * c0[e]; v1[e] = sigm(v1[e]) * c1[e]; }
;                         const f32x4 x0 = (f32x4){bf_lo(xx.x), bf_hi(xx.x), bf_lo(xx.y), bf_hi(xx.y)} + v0, x1 = (f32x4){bf_lo(xx.z), bf_hi(xx.z), bf_lo(xx.w), bf_hi(xx.w)} + v1;
;                         sq += sumsq8(x0, x1); *(u32x4*)(E.xout16 + (size_t)row * D + col0 + bj * 128) = pack8(x0, x1); }
;                     sq += __shfl_xor(sq, 16); sq += __shfl_xor(sq, 32); if (fq == 0) sslot[row] = sq; }
	v_lshlrev_b32_e32 v152, 16, v134
	v_and_b32_e32 v153, 0xffff0000, v134
	v_mul_f32_e32 v134, 0xbfb8aa3b, v144
	v_exp_f32_e32 v134, v134
	v_rcp_f32_e32 v143, v0
	v_add_f32_e32 v0, 1.0, v151
	v_rcp_f32_e32 v151, v0
	v_add_f32_e32 v0, 1.0, v134
	v_mul_f32_e32 v134, 0xbfb8aa3b, v148
	v_lshlrev_b32_e32 v154, 16, v136
	v_and_b32_e32 v155, 0xffff0000, v136
	v_exp_f32_e32 v134, v134
	v_mul_f32_e32 v136, 0xbfb8aa3b, v145
	v_exp_f32_e32 v136, v136
	v_rcp_f32_e32 v144, v0
	v_add_f32_e32 v0, 1.0, v134
	v_rcp_f32_e32 v134, v0
	v_add_f32_e32 v0, 1.0, v136
	v_mul_f32_e32 v136, 0xbfb8aa3b, v149
	v_exp_f32_e32 v136, v136
	v_rcp_f32_e32 v145, v0
	v_lshlrev_b32_e32 v148, 16, v135
	v_and_b32_e32 v149, 0xffff0000, v135
	v_add_f32_e32 v0, 1.0, v136
	v_rcp_f32_e32 v135, v0
	v_lshlrev_b32_e32 v156, 16, v130
	v_and_b32_e32 v157, 0xffff0000, v130
	v_lshlrev_b32_e32 v130, 16, v131
	v_and_b32_e32 v131, 0xffff0000, v131
	v_lshlrev_b32_e32 v136, 16, v137
	v_and_b32_e32 v137, 0xffff0000, v137
	v_pk_fma_f32 v[144:145], v[144:145], v[148:149], v[130:131]
	v_pk_fma_f32 v[130:131], v[142:143], v[152:153], v[156:157]
	v_lshlrev_b32_e32 v142, 16, v132
	v_and_b32_e32 v143, 0xffff0000, v132
	v_lshlrev_b32_e32 v132, 16, v133
	v_and_b32_e32 v133, 0xffff0000, v133
	v_pk_fma_f32 v[136:137], v[134:135], v[136:137], v[132:133]
	v_mul_f32_e32 v0, v131, v131
	v_mul_f32_e32 v132, v145, v145
	v_pk_fma_f32 v[134:135], v[150:151], v[154:155], v[142:143]
	v_fmac_f32_e32 v0, v130, v130
	v_fmac_f32_e32 v132, v144, v144
	v_add_f32_e32 v0, v0, v132
	v_mul_f32_e32 v132, v135, v135
	v_fmac_f32_e32 v132, v134, v134
	v_add_f32_e32 v0, v132, v0
	v_mul_f32_e32 v132, v137, v137
	v_fmac_f32_e32 v132, v136, v136
	v_add_f32_e32 v0, v132, v0
	v_add_f32_e32 v0, v158, v0
	ds_bpermute_b32 v148, v171, v0
	s_waitcnt lgkmcnt(1)
	v_lshlrev_b64 v[146:147], 11, v[162:163]
	v_lshl_add_u64 v[132:133], s[78:79], 0, v[146:147]
	v_lshl_add_u64 v[142:143], v[212:213], 1, v[132:133]
	v_cvt_pk_bf16_f32 v132, v130, v131
	s_waitcnt lgkmcnt(0)
	v_add_f32_e32 v0, v0, v148
	ds_bpermute_b32 v130, v170, v0
	v_cvt_pk_bf16_f32 v133, v144, v145
	v_cvt_pk_bf16_f32 v134, v134, v135
	v_cvt_pk_bf16_f32 v135, v136, v137
	v_lshl_add_u64 v[226:227], v[142:143], 0, v[230:231]
	ds_bpermute_b32 v218, v243, v138
	ds_bpermute_b32 v219, v243, v139
	ds_bpermute_b32 v220, v243, v140
	ds_bpermute_b32 v221, v243, v141
	s_waitcnt lgkmcnt(0)
	global_store_dwordx4 v[226:227], v[218:221], off
	v_lshl_add_u64 v[228:229], v[142:143], 0, v[230:231]
	ds_bpermute_b32 v222, v243, v132
	ds_bpermute_b32 v223, v243, v133
	ds_bpermute_b32 v224, v243, v134
	ds_bpermute_b32 v225, v243, v135
	s_and_saveexec_b64 s[8:9], s[40:41]
	s_cbranch_execz .LBB0_317
	v_lshl_add_u64 v[132:133], v[210:211], 2, s[44:45]
	s_waitcnt lgkmcnt(0)
	v_add_f32_e32 v0, v0, v130
	global_store_dword v[132:133], v0, off offset:192
.LBB0_317:
	s_or_b64 exec, exec, s[8:9]
	v_add_u32_e32 v164, 0x80, v210
	v_ashrrev_i32_e32 v165, 31, v164
	s_waitcnt lgkmcnt(0)
	v_lshlrev_b64 v[130:131], 10, v[164:165]
	v_lshl_add_u64 v[130:131], v[130:131], 0, v[212:213]
	v_lshlrev_b64 v[130:131], 1, v[130:131]
	v_lshl_add_u64 v[132:133], s[48:49], 0, v[130:131]
	v_lshl_add_u64 v[134:135], s[62:63], 0, v[130:131]
	global_load_dwordx4 v[154:157], v[132:133], off
	global_load_dwordx4 v[158:161], v[134:135], off
	global_load_dwordx4 v[146:149], v[132:133], off offset:256
	v_or_b32_e32 v130, 0x100, v130
	v_lshl_add_u64 v[130:131], s[62:63], 0, v[130:131]
	global_load_dwordx4 v[150:153], v[130:131], off
	v_add_f32_e32 v0, v178, v179
	v_fmamk_f32 v0, v0, 0x3a800000, v197
	v_rsq_f32_e32 v0, v0
	v_add_u32_e32 v162, 0x90, v210
	v_ashrrev_i32_e32 v163, 31, v162
	v_lshlrev_b64 v[130:131], 10, v[162:163]
	v_pk_mul_f32 v[166:167], v[62:63], v[0:1] op_sel_hi:[1,0]
	v_pk_mul_f32 v[182:183], v[58:59], v[0:1] op_sel_hi:[1,0]
	v_mul_f32_e32 v167, 0xbfb8aa3b, v167
	v_exp_f32_e32 v167, v167
	v_pk_mul_f32 v[178:179], v[64:65], v[0:1] op_sel_hi:[1,0]
	v_mul_f32_e32 v166, 0xbfb8aa3b, v166
	v_exp_f32_e32 v166, v166
	v_add_f32_e32 v167, 1.0, v167
	v_rcp_f32_e32 v169, v167
	v_pk_mul_f32 v[180:181], v[60:61], v[0:1] op_sel_hi:[1,0]
	v_add_f32_e32 v166, 1.0, v166
	v_rcp_f32_e32 v168, v166
	v_mul_f32_e32 v166, 0xbfb8aa3b, v182
	v_exp_f32_e32 v166, v166
	v_lshl_add_u64 v[130:131], v[130:131], 0, v[212:213]
	v_lshlrev_b64 v[134:135], 1, v[130:131]
	v_lshl_add_u64 v[130:131], s[48:49], 0, v[134:135]
	v_add_f32_e32 v166, 1.0, v166
	v_rcp_f32_e32 v166, v166
	v_lshl_add_u64 v[132:133], s[62:63], 0, v[134:135]
	v_or_b32_e32 v134, 0x100, v134
	v_lshl_add_u64 v[134:135], s[62:63], 0, v[134:135]
	global_load_dwordx4 v[138:141], v[130:131], off
	global_load_dwordx4 v[142:145], v[132:133], off
	s_nop 0
	global_load_dwordx4 v[130:133], v[130:131], off offset:256
	v_lshlrev_b64 v[164:165], 11, v[164:165]
	global_load_dwordx4 v[134:137], v[134:135], off
	s_waitcnt lgkmcnt(0)
	global_store_dwordx4 v[228:229], v[222:225], off offset:256
	s_waitcnt vmcnt(6)
; __device__ __forceinline__ float bf_lo(unsigned w) { return __uint_as_float(w << 16); }
; __device__ __forceinline__ float bf_hi(unsigned w) { return __uint_as_float(w & 0xffff0000u); }
; __device__ __forceinline__ float sigm(float v) { return __builtin_amdgcn_rcpf(1.0f + __builtin_amdgcn_exp2f(-1.44269504089f * v)); }
; __device__ __forceinline__ u32x4 pack8(const f32x4& v0, const f32x4& v1) { u32x4 w; w.x = cvt_pk_bf16(v0[0], v0[1]); w.y = cvt_pk_bf16(v0[2], v0[3]); w.z = cvt_pk_bf16(v1[0], v1[1]); w.w = cvt_pk_bf16(v1[2], v1[3]); return w; }
; __device__ __forceinline__ float sumsq8(const f32x4& v0, const f32x4& v1) { return (v0[0] * v0[0] + v0[1] * v0[1]) + (v0[2] * v0[2] + v0[3] * v0[3]) + (v1[0] * v1[0] + v1[1] * v1[1]) + (v1[2] * v1[2] + v1[3] * v1[3]); }
; __device__ __forceinline__ void epi_run(const Epi& E, f32x4 (&acc)[2][2][4][2], const Unit& u, int wr, int wc, int fr, int fq) {
;     ...
;                 for (int mm = 0; mm < 2; ++mm) { const int m = 2 * mh + mm, row = row0 + ai * 128 + m * 16; float sq = 0.f;
; #pragma unroll
;                     for (int bj = 0; bj < 2; ++bj) { const u32x4 xx = x[mm][bj], cc = c[mm][bj];
;                         const f32x4 c0 = (f32x4){bf_lo(cc.x), bf_hi(cc.x), bf_lo(cc.y), bf_hi(cc.y)}, c1 = (f32x4){bf_lo(cc.z), bf_hi(cc.z), bf_lo(cc.w), bf_hi(cc.w)};
;                         f32x4 v0 = acc[ai][bj][m][0] * rs[ai][m], v1 = acc[ai][bj][m][1] * rs[ai][m];
; #pragma unroll
;                         for (int e = 0; e < 4; ++e) { v0[e] = sigm(v0[e]) * c0[e]; v1[e] = sigm(v1[e]) * c1[e]; }
;                         const f32x4 x0 = (f32x4){bf_lo(xx.x), bf_hi(xx.x), bf_lo(xx.y), bf_hi(xx.y)} + v0, x1 = (f32x4){bf_lo(xx.z), bf_hi(xx.z), bf_lo(xx.w), bf_hi(xx.w)} + v1;
;                         sq += sumsq8(x0, x1); *(u32x4*)(E.xout16 + (size_t)row * D + col0 + bj * 128) = pack8(x0, x1); }
;                     sq += __shfl_xor(sq, 16); sq += __shfl_xor(sq, 32); if (fq == 0) sslot[row] = sq; }
	v_lshlrev_b32_e32 v184, 16, v158
	v_and_b32_e32 v185, 0xffff0000, v158
	v_mul_f32_e32 v158, 0xbfb8aa3b, v183
	v_exp_f32_e32 v158, v158
	v_lshlrev_b32_e32 v182, 16, v160
	v_and_b32_e32 v183, 0xffff0000, v160
	v_mul_f32_e32 v160, 0xbfb8aa3b, v179
	v_add_f32_e32 v158, 1.0, v158
	v_rcp_f32_e32 v167, v158
	v_mul_f32_e32 v158, 0xbfb8aa3b, v178
	v_exp_f32_e32 v158, v158
	v_exp_f32_e32 v160, v160
	v_lshlrev_b32_e32 v186, 16, v159
	v_and_b32_e32 v187, 0xffff0000, v159
	v_add_f32_e32 v158, 1.0, v158
	v_rcp_f32_e32 v178, v158
	v_mul_f32_e32 v158, 0xbfb8aa3b, v180
	v_mul_f32_e32 v159, 0xbfb8aa3b, v181
	v_exp_f32_e32 v158, v158
	v_exp_f32_e32 v159, v159
	v_add_f32_e32 v160, 1.0, v160
	v_rcp_f32_e32 v179, v160
	v_add_f32_e32 v158, 1.0, v158
	v_add_f32_e32 v159, 1.0, v159
	v_rcp_f32_e32 v158, v158
	v_rcp_f32_e32 v159, v159
	v_lshlrev_b32_e32 v180, 16, v154
	v_and_b32_e32 v181, 0xffff0000, v154
	v_lshlrev_b32_e32 v154, 16, v155
	v_and_b32_e32 v155, 0xffff0000, v155
	v_lshlrev_b32_e32 v160, 16, v161
	v_and_b32_e32 v161, 0xffff0000, v161
	v_pk_fma_f32 v[154:155], v[178:179], v[186:187], v[154:155]
	v_pk_fma_f32 v[168:169], v[168:169], v[184:185], v[180:181]
	v_lshlrev_b32_e32 v178, 16, v156
	v_and_b32_e32 v179, 0xffff0000, v156
	v_lshlrev_b32_e32 v156, 16, v157
	v_and_b32_e32 v157, 0xffff0000, v157
	v_pk_fma_f32 v[160:161], v[158:159], v[160:161], v[156:157]
	v_mul_f32_e32 v156, v169, v169
	v_mul_f32_e32 v157, v155, v155
	v_pk_fma_f32 v[158:159], v[166:167], v[182:183], v[178:179]
	v_fmac_f32_e32 v156, v168, v168
	v_fmac_f32_e32 v157, v154, v154
	v_add_f32_e32 v156, v156, v157
	v_mul_f32_e32 v157, v159, v159
	v_fmac_f32_e32 v157, v158, v158
	v_add_f32_e32 v156, v157, v156
	v_mul_f32_e32 v157, v161, v161
	v_fmac_f32_e32 v157, v160, v160
	v_add_f32_e32 v180, v157, v156
	v_cvt_pk_bf16_f32 v157, v154, v155
	v_lshl_add_u64 v[154:155], s[78:79], 0, v[164:165]
	v_cvt_pk_bf16_f32 v156, v168, v169
	v_cvt_pk_bf16_f32 v158, v158, v159
	v_cvt_pk_bf16_f32 v159, v160, v161
	v_lshl_add_u64 v[154:155], v[212:213], 1, v[154:155]
	v_lshl_add_u64 v[226:227], v[154:155], 0, v[230:231]
	ds_bpermute_b32 v218, v243, v156
	ds_bpermute_b32 v219, v243, v157
	ds_bpermute_b32 v220, v243, v158
	ds_bpermute_b32 v221, v243, v159
	v_pk_mul_f32 v[160:161], v[52:53], v[0:1] op_sel_hi:[1,0]
	v_pk_mul_f32 v[164:165], v[50:51], v[0:1] op_sel_hi:[1,0]
	v_pk_mul_f32 v[158:159], v[54:55], v[0:1] op_sel_hi:[1,0]
	v_pk_mul_f32 v[156:157], v[56:57], v[0:1] op_sel_hi:[1,0]
	v_mul_f32_e32 v0, 0xbfb8aa3b, v158
	v_exp_f32_e32 v0, v0
	s_waitcnt lgkmcnt(0)
	global_store_dwordx4 v[226:227], v[218:221], off
	s_waitcnt vmcnt(5)
	v_lshlrev_b32_e32 v166, 16, v150
	v_and_b32_e32 v167, 0xffff0000, v150
	v_lshlrev_b32_e32 v178, 16, v151
	v_add_f32_e32 v0, 1.0, v0
	v_rcp_f32_e32 v158, v0
	v_mul_f32_e32 v0, 0xbfb8aa3b, v164
	v_exp_f32_e32 v0, v0
	v_and_b32_e32 v179, 0xffff0000, v151
	v_lshlrev_b32_e32 v168, 16, v152
	v_and_b32_e32 v169, 0xffff0000, v152
	v_add_f32_e32 v0, 1.0, v0
	v_rcp_f32_e32 v164, v0
	v_mul_f32_e32 v0, 0xbfb8aa3b, v159
	v_exp_f32_e32 v0, v0
	v_lshlrev_b32_e32 v152, 16, v153
	v_and_b32_e32 v153, 0xffff0000, v153
	v_add_f32_e32 v0, 1.0, v0
	v_rcp_f32_e32 v159, v0
	v_mul_f32_e32 v0, 0xbfb8aa3b, v165
	v_exp_f32_e32 v0, v0
	s_nop 0
	v_add_f32_e32 v0, 1.0, v0
	v_rcp_f32_e32 v165, v0
	v_mul_f32_e32 v0, 0xbfb8aa3b, v156
	v_exp_f32_e32 v0, v0
	s_nop 0
	v_add_f32_e32 v0, 1.0, v0
	v_rcp_f32_e32 v156, v0
	v_mul_f32_e32 v0, 0xbfb8aa3b, v160
	v_exp_f32_e32 v0, v0
	v_lshlrev_b32_e32 v160, 16, v146
	v_add_f32_e32 v0, 1.0, v0
	v_rcp_f32_e32 v150, v0
	v_mul_f32_e32 v0, 0xbfb8aa3b, v157
	v_exp_f32_e32 v0, v0
	s_nop 0
	v_add_f32_e32 v0, 1.0, v0
	v_rcp_f32_e32 v157, v0
	v_mul_f32_e32 v0, 0xbfb8aa3b, v161
	v_exp_f32_e32 v0, v0
	v_and_b32_e32 v161, 0xffff0000, v146
	v_lshlrev_b32_e32 v146, 16, v147
	v_and_b32_e32 v147, 0xffff0000, v147
	v_add_f32_e32 v0, 1.0, v0
	v_rcp_f32_e32 v151, v0
	v_pk_fma_f32 v[156:157], v[156:157], v[178:179], v[146:147]
	v_pk_fma_f32 v[146:147], v[158:159], v[166:167], v[160:161]
	v_lshlrev_b32_e32 v158, 16, v148
	v_and_b32_e32 v159, 0xffff0000, v148
	v_lshlrev_b32_e32 v148, 16, v149
	v_and_b32_e32 v149, 0xffff0000, v149
	v_pk_fma_f32 v[150:151], v[150:151], v[152:153], v[148:149]
	v_mul_f32_e32 v0, v147, v147
	v_mul_f32_e32 v152, v157, v157
	v_pk_fma_f32 v[148:149], v[164:165], v[168:169], v[158:159]
	v_fmac_f32_e32 v0, v146, v146
	v_fmac_f32_e32 v152, v156, v156
	v_add_f32_e32 v0, v0, v152
	v_mul_f32_e32 v152, v149, v149
	v_fmac_f32_e32 v152, v148, v148
	v_add_f32_e32 v0, v152, v0
	v_mul_f32_e32 v152, v151, v151
	v_fmac_f32_e32 v152, v150, v150
	v_add_f32_e32 v0, v152, v0
	v_add_f32_e32 v0, v180, v0
	v_cvt_pk_bf16_f32 v146, v146, v147
	v_cvt_pk_bf16_f32 v147, v156, v157
	v_cvt_pk_bf16_f32 v148, v148, v149
	v_cvt_pk_bf16_f32 v149, v150, v151
	v_lshl_add_u64 v[228:229], v[154:155], 0, v[230:231]
	ds_bpermute_b32 v222, v243, v146
	ds_bpermute_b32 v223, v243, v147
	ds_bpermute_b32 v224, v243, v148
	ds_bpermute_b32 v225, v243, v149
	ds_bpermute_b32 v146, v171, v0
	s_waitcnt lgkmcnt(0)
	v_add_f32_e32 v0, v0, v146
	ds_bpermute_b32 v146, v170, v0
	s_and_saveexec_b64 s[8:9], s[40:41]
	s_cbranch_execz .LBB0_319
	v_lshl_add_u64 v[148:149], v[210:211], 2, s[44:45]
	s_waitcnt lgkmcnt(0)
	v_add_f32_e32 v0, v0, v146
	global_store_dword v[148:149], v0, off offset:512
; __device__ __forceinline__ float bf_lo(unsigned w) { return __uint_as_float(w << 16); }
; __device__ __forceinline__ float bf_hi(unsigned w) { return __uint_as_float(w & 0xffff0000u); }
; __device__ __forceinline__ float sigm(float v) { return __builtin_amdgcn_rcpf(1.0f + __builtin_amdgcn_exp2f(-1.44269504089f * v)); }
; __device__ __forceinline__ u32x4 pack8(const f32x4& v0, const f32x4& v1) { u32x4 w; w.x = cvt_pk_bf16(v0[0], v0[1]); w.y = cvt_pk_bf16(v0[2], v0[3]); w.z = cvt_pk_bf16(v1[0], v1[1]); w.w = cvt_pk_bf16(v1[2], v1[3]); return w; }
; __device__ __forceinline__ float sumsq8(const f32x4& v0, const f32x4& v1) { return (v0[0] * v0[0] + v0[1] * v0[1]) + (v0[2] * v0[2] + v0[3] * v0[3]) + (v1[0] * v1[0] + v1[1] * v1[1]) + (v1[2] * v1[2] + v1[3] * v1[3]); }
; __device__ __forceinline__ void epi_run(const Epi& E, f32x4 (&acc)[2][2][4][2], const Unit& u, int wr, int wc, int fr, int fq) {
;     ...
;                 for (int mm = 0; mm < 2; ++mm) { const int m = 2 * mh + mm, row = row0 + ai * 128 + m * 16; float sq = 0.f;
; #pragma unroll
;                     for (int bj = 0; bj < 2; ++bj) { const u32x4 xx = x[mm][bj], cc = c[mm][bj];
;                         const f32x4 c0 = (f32x4){bf_lo(cc.x), bf_hi(cc.x), bf_lo(cc.y), bf_hi(cc.y)}, c1 = (f32x4){bf_lo(cc.z), bf_hi(cc.z), bf_lo(cc.w), bf_hi(cc.w)};
;                         f32x4 v0 = acc[ai][bj][m][0] * rs[ai][m], v1 = acc[ai][bj][m][1] * rs[ai][m];
; #pragma unroll
;                         for (int e = 0; e < 4; ++e) { v0[e] = sigm(v0[e]) * c0[e]; v1[e] = sigm(v1[e]) * c1[e]; }
;                         const f32x4 x0 = (f32x4){bf_lo(xx.x), bf_hi(xx.x), bf_lo(xx.y), bf_hi(xx.y)} + v0, x1 = (f32x4){bf_lo(xx.z), bf_hi(xx.z), bf_lo(xx.w), bf_hi(xx.w)} + v1;
;                         sq += sumsq8(x0, x1); *(u32x4*)(E.xout16 + (size_t)row * D + col0 + bj * 128) = pack8(x0, x1); }
;                     sq += __shfl_xor(sq, 16); sq += __shfl_xor(sq, 32); if (fq == 0) sslot[row] = sq; }
.LBB0_319:
	s_or_b64 exec, exec, s[8:9]
	v_add_f32_e32 v0, v176, v177
	v_fmamk_f32 v0, v0, 0x3a800000, v197
	v_rsq_f32_e32 v0, v0
	s_waitcnt lgkmcnt(0)
	global_store_dwordx4 v[228:229], v[222:225], off offset:256
	s_waitcnt vmcnt(4)
	v_lshlrev_b32_e32 v156, 16, v142
	v_and_b32_e32 v157, 0xffff0000, v142
	v_lshlrev_b32_e32 v158, 16, v144
	v_pk_mul_f32 v[154:155], v[42:43], v[0:1] op_sel_hi:[1,0]
	v_pk_mul_f32 v[148:149], v[48:49], v[0:1] op_sel_hi:[1,0]
	v_mul_f32_e32 v155, 0xbfb8aa3b, v155
	v_exp_f32_e32 v155, v155
	v_mul_f32_e32 v148, 0xbfb8aa3b, v148
	v_exp_f32_e32 v148, v148
	v_pk_mul_f32 v[152:153], v[44:45], v[0:1] op_sel_hi:[1,0]
	v_add_f32_e32 v142, 1.0, v155
	v_rcp_f32_e32 v155, v142
	v_and_b32_e32 v159, 0xffff0000, v144
	v_add_f32_e32 v142, 1.0, v148
	v_mul_f32_e32 v144, 0xbfb8aa3b, v152
	v_mul_f32_e32 v148, 0xbfb8aa3b, v149
	v_exp_f32_e32 v144, v144
	v_exp_f32_e32 v149, v148
	v_pk_mul_f32 v[150:151], v[46:47], v[0:1] op_sel_hi:[1,0]
	v_rcp_f32_e32 v148, v142
	v_mul_f32_e32 v150, 0xbfb8aa3b, v150
	v_mul_f32_e32 v151, 0xbfb8aa3b, v151
	v_exp_f32_e32 v150, v150
	v_exp_f32_e32 v151, v151
	v_add_f32_e32 v142, 1.0, v144
	v_add_f32_e32 v144, 1.0, v149
	v_mul_f32_e32 v149, 0xbfb8aa3b, v153
	v_mul_f32_e32 v154, 0xbfb8aa3b, v154
	v_exp_f32_e32 v160, v149
	v_exp_f32_e32 v154, v154
	v_add_f32_e32 v150, 1.0, v150
	v_add_f32_e32 v151, 1.0, v151
	v_rcp_f32_e32 v150, v150
	v_rcp_f32_e32 v151, v151
	v_rcp_f32_e32 v149, v144
	v_lshlrev_b32_e32 v152, 16, v143
	v_and_b32_e32 v153, 0xffff0000, v143
	v_add_f32_e32 v143, 1.0, v160
	v_add_f32_e32 v154, 1.0, v154
	v_rcp_f32_e32 v142, v142
	v_rcp_f32_e32 v143, v143
	v_rcp_f32_e32 v154, v154
	v_lshlrev_b32_e32 v160, 16, v138
	v_and_b32_e32 v161, 0xffff0000, v138
	v_lshlrev_b32_e32 v138, 16, v139
	v_and_b32_e32 v139, 0xffff0000, v139
	v_lshlrev_b32_e32 v144, 16, v145
	v_and_b32_e32 v145, 0xffff0000, v145
	v_pk_fma_f32 v[148:149], v[148:149], v[152:153], v[138:139]
	v_pk_fma_f32 v[138:139], v[150:151], v[156:157], v[160:161]
	v_lshlrev_b32_e32 v150, 16, v140
	v_and_b32_e32 v151, 0xffff0000, v140
	v_lshlrev_b32_e32 v140, 16, v141
	v_and_b32_e32 v141, 0xffff0000, v141
	v_pk_fma_f32 v[142:143], v[142:143], v[144:145], v[140:141]
	v_mul_f32_e32 v144, v139, v139
	v_mul_f32_e32 v145, v149, v149
	v_pk_fma_f32 v[140:141], v[154:155], v[158:159], v[150:151]
	v_fmac_f32_e32 v144, v138, v138
	v_fmac_f32_e32 v145, v148, v148
	v_add_f32_e32 v144, v144, v145
	v_mul_f32_e32 v145, v141, v141
	v_fmac_f32_e32 v145, v140, v140
	v_add_f32_e32 v144, v145, v144
	v_mul_f32_e32 v145, v143, v143
	v_fmac_f32_e32 v145, v142, v142
	v_cvt_pk_bf16_f32 v140, v140, v141
	v_cvt_pk_bf16_f32 v141, v142, v143
	v_pk_mul_f32 v[142:143], v[38:39], v[0:1] op_sel_hi:[1,0]
	v_pk_mul_f32 v[150:151], v[34:35], v[0:1] op_sel_hi:[1,0]
	v_mul_f32_e32 v142, 0xbfb8aa3b, v142
	v_exp_f32_e32 v142, v142
	v_add_f32_e32 v158, v145, v144
	v_cvt_pk_bf16_f32 v138, v138, v139
	v_cvt_pk_bf16_f32 v139, v148, v149
	v_pk_mul_f32 v[144:145], v[40:41], v[0:1] op_sel_hi:[1,0]
	v_pk_mul_f32 v[148:149], v[36:37], v[0:1] op_sel_hi:[1,0]
	v_add_f32_e32 v0, 1.0, v142
	v_mul_f32_e32 v142, 0xbfb8aa3b, v150
	v_exp_f32_e32 v150, v142
	v_mul_f32_e32 v142, 0xbfb8aa3b, v143
	v_exp_f32_e32 v143, v142
	v_rcp_f32_e32 v142, v0
	v_add_f32_e32 v0, 1.0, v150
	v_rcp_f32_e32 v150, v0
	v_add_f32_e32 v0, 1.0, v143
	v_mul_f32_e32 v143, 0xbfb8aa3b, v151
	v_exp_f32_e32 v151, v143
	s_waitcnt vmcnt(2)
	v_lshlrev_b32_e32 v152, 16, v134
	v_and_b32_e32 v153, 0xffff0000, v134
	v_mul_f32_e32 v134, 0xbfb8aa3b, v144
	v_exp_f32_e32 v134, v134
	v_rcp_f32_e32 v143, v0
	v_add_f32_e32 v0, 1.0, v151
	v_rcp_f32_e32 v151, v0
	v_add_f32_e32 v0, 1.0, v134
	v_mul_f32_e32 v134, 0xbfb8aa3b, v148
	v_lshlrev_b32_e32 v154, 16, v136
	v_and_b32_e32 v155, 0xffff0000, v136
	v_exp_f32_e32 v134, v134
	v_mul_f32_e32 v136, 0xbfb8aa3b, v145
	v_exp_f32_e32 v136, v136
	v_rcp_f32_e32 v144, v0
	v_add_f32_e32 v0, 1.0, v134
	v_rcp_f32_e32 v134, v0
	v_add_f32_e32 v0, 1.0, v136
	v_mul_f32_e32 v136, 0xbfb8aa3b, v149
	v_exp_f32_e32 v136, v136
	v_rcp_f32_e32 v145, v0
	v_lshlrev_b32_e32 v148, 16, v135
	v_and_b32_e32 v149, 0xffff0000, v135
	v_add_f32_e32 v0, 1.0, v136
	v_rcp_f32_e32 v135, v0
	v_lshlrev_b32_e32 v156, 16, v130
	v_and_b32_e32 v157, 0xffff0000, v130
	v_lshlrev_b32_e32 v130, 16, v131
	v_and_b32_e32 v131, 0xffff0000, v131
	v_lshlrev_b32_e32 v136, 16, v137
	v_and_b32_e32 v137, 0xffff0000, v137
	v_pk_fma_f32 v[144:145], v[144:145], v[148:149], v[130:131]
	v_pk_fma_f32 v[130:131], v[142:143], v[152:153], v[156:157]
	v_lshlrev_b32_e32 v142, 16, v132
	v_and_b32_e32 v143, 0xffff0000, v132
	v_lshlrev_b32_e32 v132, 16, v133
	v_and_b32_e32 v133, 0xffff0000, v133
	v_pk_fma_f32 v[136:137], v[134:135], v[136:137], v[132:133]
	v_mul_f32_e32 v0, v131, v131
	v_mul_f32_e32 v132, v145, v145
	v_pk_fma_f32 v[134:135], v[150:151], v[154:155], v[142:143]
	v_fmac_f32_e32 v0, v130, v130
	v_fmac_f32_e32 v132, v144, v144
	v_add_f32_e32 v0, v0, v132
	v_mul_f32_e32 v132, v135, v135
	v_fmac_f32_e32 v132, v134, v134
	v_add_f32_e32 v0, v132, v0
	v_mul_f32_e32 v132, v137, v137
	v_fmac_f32_e32 v132, v136, v136
	v_add_f32_e32 v0, v132, v0
	v_add_f32_e32 v0, v158, v0
	ds_bpermute_b32 v148, v171, v0
	s_waitcnt lgkmcnt(1)
	v_lshlrev_b64 v[146:147], 11, v[162:163]
	v_lshl_add_u64 v[132:133], s[78:79], 0, v[146:147]
	v_lshl_add_u64 v[142:143], v[212:213], 1, v[132:133]
	v_cvt_pk_bf16_f32 v132, v130, v131
	s_waitcnt lgkmcnt(0)
	v_add_f32_e32 v0, v0, v148
	ds_bpermute_b32 v130, v170, v0
	v_cvt_pk_bf16_f32 v133, v144, v145
	v_cvt_pk_bf16_f32 v134, v134, v135
	v_cvt_pk_bf16_f32 v135, v136, v137
	v_lshl_add_u64 v[226:227], v[142:143], 0, v[230:231]
	ds_bpermute_b32 v218, v243, v138
	ds_bpermute_b32 v219, v243, v139
	ds_bpermute_b32 v220, v243, v140
	ds_bpermute_b32 v221, v243, v141
	s_waitcnt lgkmcnt(0)
	global_store_dwordx4 v[226:227], v[218:221], off
	v_lshl_add_u64 v[228:229], v[142:143], 0, v[230:231]
	ds_bpermute_b32 v222, v243, v132
	ds_bpermute_b32 v223, v243, v133
	ds_bpermute_b32 v224, v243, v134
	ds_bpermute_b32 v225, v243, v135
	s_and_saveexec_b64 s[8:9], s[40:41]
	s_cbranch_execz .LBB0_321
	v_lshl_add_u64 v[132:133], v[210:211], 2, s[44:45]
	s_waitcnt lgkmcnt(0)
	v_add_f32_e32 v0, v0, v130
	global_store_dword v[132:133], v0, off offset:576
; __device__ __forceinline__ float bf_lo(unsigned w) { return __uint_as_float(w << 16); }
; __device__ __forceinline__ float bf_hi(unsigned w) { return __uint_as_float(w & 0xffff0000u); }
; __device__ __forceinline__ float sigm(float v) { return __builtin_amdgcn_rcpf(1.0f + __builtin_amdgcn_exp2f(-1.44269504089f * v)); }
; __device__ __forceinline__ u32x4 pack8(const f32x4& v0, const f32x4& v1) { u32x4 w; w.x = cvt_pk_bf16(v0[0], v0[1]); w.y = cvt_pk_bf16(v0[2], v0[3]); w.z = cvt_pk_bf16(v1[0], v1[1]); w.w = cvt_pk_bf16(v1[2], v1[3]); return w; }
; __device__ __forceinline__ float sumsq8(const f32x4& v0, const f32x4& v1) { return (v0[0] * v0[0] + v0[1] * v0[1]) + (v0[2] * v0[2] + v0[3] * v0[3]) + (v1[0] * v1[0] + v1[1] * v1[1]) + (v1[2] * v1[2] + v1[3] * v1[3]); }
; __device__ __forceinline__ void epi_run(const Epi& E, f32x4 (&acc)[2][2][4][2], const Unit& u, int wr, int wc, int fr, int fq) {
;     ...
;             for (int mh = 0; mh < 2; ++mh) { u32x4 x[2][2], c[2][2];
; #pragma unroll
;                 for (int mm = 0; mm < 2; ++mm)
; #pragma unroll
;                     for (int bj = 0; bj < 2; ++bj) { const size_t off = (size_t)(row0 + ai * 128 + (2 * mh + mm) * 16) * D + col0 + bj * 128; x[mm][bj] = *(const u32x4*)(E.xin16 + off); c[mm][bj] = *(const u32x4*)(E.C16 + off); }
; #pragma unroll
;                 for (int mm = 0; mm < 2; ++mm) { const int m = 2 * mh + mm, row = row0 + ai * 128 + m * 16; float sq = 0.f;
; #pragma unroll
;                     for (int bj = 0; bj < 2; ++bj) { const u32x4 xx = x[mm][bj], cc = c[mm][bj];
;                         const f32x4 c0 = (f32x4){bf_lo(cc.x), bf_hi(cc.x), bf_lo(cc.y), bf_hi(cc.y)}, c1 = (f32x4){bf_lo(cc.z), bf_hi(cc.z), bf_lo(cc.w), bf_hi(cc.w)};
;                         f32x4 v0 = acc[ai][bj][m][0] * rs[ai][m], v1 = acc[ai][bj][m][1] * rs[ai][m];
; #pragma unroll
;                         for (int e = 0; e < 4; ++e) { v0[e] = sigm(v0[e]) * c0[e]; v1[e] = sigm(v1[e]) * c1[e]; }
;                         const f32x4 x0 = (f32x4){bf_lo(xx.x), bf_hi(xx.x), bf_lo(xx.y), bf_hi(xx.y)} + v0, x1 = (f32x4){bf_lo(xx.z), bf_hi(xx.z), bf_lo(xx.w), bf_hi(xx.w)} + v1;
;                         sq += sumsq8(x0, x1); *(u32x4*)(E.xout16 + (size_t)row * D + col0 + bj * 128) = pack8(x0, x1); }
;                     sq += __shfl_xor(sq, 16); sq += __shfl_xor(sq, 32); if (fq == 0) sslot[row] = sq; }
.LBB0_321:
	s_or_b64 exec, exec, s[8:9]
	v_add_u32_e32 v164, 0xa0, v210
	v_ashrrev_i32_e32 v165, 31, v164
	s_waitcnt lgkmcnt(0)
	v_lshlrev_b64 v[130:131], 10, v[164:165]
	v_lshl_add_u64 v[130:131], v[130:131], 0, v[212:213]
	v_lshlrev_b64 v[130:131], 1, v[130:131]
	v_lshl_add_u64 v[132:133], s[48:49], 0, v[130:131]
	v_lshl_add_u64 v[134:135], s[62:63], 0, v[130:131]
	global_load_dwordx4 v[154:157], v[132:133], off
	global_load_dwordx4 v[158:161], v[134:135], off
	global_load_dwordx4 v[146:149], v[132:133], off offset:256
	v_or_b32_e32 v130, 0x100, v130
	v_lshl_add_u64 v[130:131], s[62:63], 0, v[130:131]
	global_load_dwordx4 v[150:153], v[130:131], off
	v_add_f32_e32 v0, v174, v175
	v_fmamk_f32 v0, v0, 0x3a800000, v197
	v_rsq_f32_e32 v0, v0
	v_add_u32_e32 v162, 0xb0, v210
	v_ashrrev_i32_e32 v163, 31, v162
	v_lshlrev_b64 v[130:131], 10, v[162:163]
	v_pk_mul_f32 v[166:167], v[30:31], v[0:1] op_sel_hi:[1,0]
	v_pk_mul_f32 v[178:179], v[26:27], v[0:1] op_sel_hi:[1,0]
	v_mul_f32_e32 v167, 0xbfb8aa3b, v167
	v_exp_f32_e32 v167, v167
	v_pk_mul_f32 v[174:175], v[32:33], v[0:1] op_sel_hi:[1,0]
	v_mul_f32_e32 v166, 0xbfb8aa3b, v166
	v_exp_f32_e32 v166, v166
	v_add_f32_e32 v167, 1.0, v167
	v_rcp_f32_e32 v169, v167
	v_pk_mul_f32 v[176:177], v[28:29], v[0:1] op_sel_hi:[1,0]
	v_add_f32_e32 v166, 1.0, v166
	v_rcp_f32_e32 v168, v166
	v_mul_f32_e32 v166, 0xbfb8aa3b, v178
	v_exp_f32_e32 v166, v166
	v_lshl_add_u64 v[130:131], v[130:131], 0, v[212:213]
	v_lshlrev_b64 v[134:135], 1, v[130:131]
	v_lshl_add_u64 v[130:131], s[48:49], 0, v[134:135]
	v_add_f32_e32 v166, 1.0, v166
	v_rcp_f32_e32 v166, v166
	v_lshl_add_u64 v[132:133], s[62:63], 0, v[134:135]
	v_or_b32_e32 v134, 0x100, v134
	v_lshl_add_u64 v[134:135], s[62:63], 0, v[134:135]
	global_load_dwordx4 v[138:141], v[130:131], off
	global_load_dwordx4 v[142:145], v[132:133], off
	s_nop 0
	global_load_dwordx4 v[130:133], v[130:131], off offset:256
	v_lshlrev_b64 v[164:165], 11, v[164:165]
	global_load_dwordx4 v[134:137], v[134:135], off
	s_waitcnt lgkmcnt(0)
	global_store_dwordx4 v[228:229], v[222:225], off offset:256
	s_waitcnt vmcnt(6)
	v_lshlrev_b32_e32 v180, 16, v158
	v_and_b32_e32 v181, 0xffff0000, v158
	v_mul_f32_e32 v158, 0xbfb8aa3b, v179
	v_exp_f32_e32 v158, v158
	v_lshlrev_b32_e32 v178, 16, v160
	v_and_b32_e32 v179, 0xffff0000, v160
	v_mul_f32_e32 v160, 0xbfb8aa3b, v175
	v_add_f32_e32 v158, 1.0, v158
	v_rcp_f32_e32 v167, v158
	v_mul_f32_e32 v158, 0xbfb8aa3b, v174
	v_exp_f32_e32 v158, v158
	v_exp_f32_e32 v160, v160
	v_lshlrev_b32_e32 v182, 16, v159
	v_and_b32_e32 v183, 0xffff0000, v159
	v_add_f32_e32 v158, 1.0, v158
	v_rcp_f32_e32 v174, v158
	v_mul_f32_e32 v158, 0xbfb8aa3b, v176
	v_mul_f32_e32 v159, 0xbfb8aa3b, v177
	v_exp_f32_e32 v158, v158
	v_exp_f32_e32 v159, v159
	v_add_f32_e32 v160, 1.0, v160
	v_rcp_f32_e32 v175, v160
	v_add_f32_e32 v158, 1.0, v158
	v_add_f32_e32 v159, 1.0, v159
	v_rcp_f32_e32 v158, v158
	v_rcp_f32_e32 v159, v159
	v_lshlrev_b32_e32 v176, 16, v154
	v_and_b32_e32 v177, 0xffff0000, v154
	v_lshlrev_b32_e32 v154, 16, v155
	v_and_b32_e32 v155, 0xffff0000, v155
	v_lshlrev_b32_e32 v160, 16, v161
	v_and_b32_e32 v161, 0xffff0000, v161
	v_pk_fma_f32 v[154:155], v[174:175], v[182:183], v[154:155]
	v_pk_fma_f32 v[168:169], v[168:169], v[180:181], v[176:177]
	v_lshlrev_b32_e32 v174, 16, v156
	v_and_b32_e32 v175, 0xffff0000, v156
	v_lshlrev_b32_e32 v156, 16, v157
	v_and_b32_e32 v157, 0xffff0000, v157
	v_pk_fma_f32 v[160:161], v[158:159], v[160:161], v[156:157]
	v_mul_f32_e32 v156, v169, v169
	v_mul_f32_e32 v157, v155, v155
	v_pk_fma_f32 v[158:159], v[166:167], v[178:179], v[174:175]
	v_fmac_f32_e32 v156, v168, v168
	v_fmac_f32_e32 v157, v154, v154
	v_add_f32_e32 v156, v156, v157
	v_mul_f32_e32 v157, v159, v159
	v_fmac_f32_e32 v157, v158, v158
	v_add_f32_e32 v156, v157, v156
	v_mul_f32_e32 v157, v161, v161
	v_fmac_f32_e32 v157, v160, v160
	v_add_f32_e32 v176, v157, v156
	v_cvt_pk_bf16_f32 v157, v154, v155
	v_lshl_add_u64 v[154:155], s[78:79], 0, v[164:165]
	v_cvt_pk_bf16_f32 v156, v168, v169
	v_cvt_pk_bf16_f32 v158, v158, v159
	v_cvt_pk_bf16_f32 v159, v160, v161
	v_lshl_add_u64 v[154:155], v[212:213], 1, v[154:155]
	v_lshl_add_u64 v[226:227], v[154:155], 0, v[230:231]
	ds_bpermute_b32 v218, v243, v156
	ds_bpermute_b32 v219, v243, v157
	ds_bpermute_b32 v220, v243, v158
	ds_bpermute_b32 v221, v243, v159
	v_pk_mul_f32 v[160:161], v[20:21], v[0:1] op_sel_hi:[1,0]
	v_pk_mul_f32 v[164:165], v[18:19], v[0:1] op_sel_hi:[1,0]
	v_pk_mul_f32 v[158:159], v[22:23], v[0:1] op_sel_hi:[1,0]
	v_pk_mul_f32 v[156:157], v[24:25], v[0:1] op_sel_hi:[1,0]
	v_mul_f32_e32 v0, 0xbfb8aa3b, v158
	v_exp_f32_e32 v0, v0
	s_waitcnt lgkmcnt(0)
	global_store_dwordx4 v[226:227], v[218:221], off
	s_waitcnt vmcnt(5)
; __device__ __forceinline__ float bf_lo(unsigned w) { return __uint_as_float(w << 16); }
; __device__ __forceinline__ float bf_hi(unsigned w) { return __uint_as_float(w & 0xffff0000u); }
; __device__ __forceinline__ float sigm(float v) { return __builtin_amdgcn_rcpf(1.0f + __builtin_amdgcn_exp2f(-1.44269504089f * v)); }
; __device__ __forceinline__ u32x4 pack8(const f32x4& v0, const f32x4& v1) { u32x4 w; w.x = cvt_pk_bf16(v0[0], v0[1]); w.y = cvt_pk_bf16(v0[2], v0[3]); w.z = cvt_pk_bf16(v1[0], v1[1]); w.w = cvt_pk_bf16(v1[2], v1[3]); return w; }
; __device__ __forceinline__ float sumsq8(const f32x4& v0, const f32x4& v1) { return (v0[0] * v0[0] + v0[1] * v0[1]) + (v0[2] * v0[2] + v0[3] * v0[3]) + (v1[0] * v1[0] + v1[1] * v1[1]) + (v1[2] * v1[2] + v1[3] * v1[3]); }
; __device__ __forceinline__ void epi_run(const Epi& E, f32x4 (&acc)[2][2][4][2], const Unit& u, int wr, int wc, int fr, int fq) {
;     ...
;                 for (int mm = 0; mm < 2; ++mm) { const int m = 2 * mh + mm, row = row0 + ai * 128 + m * 16; float sq = 0.f;
; #pragma unroll
;                     for (int bj = 0; bj < 2; ++bj) { const u32x4 xx = x[mm][bj], cc = c[mm][bj];
;                         const f32x4 c0 = (f32x4){bf_lo(cc.x), bf_hi(cc.x), bf_lo(cc.y), bf_hi(cc.y)}, c1 = (f32x4){bf_lo(cc.z), bf_hi(cc.z), bf_lo(cc.w), bf_hi(cc.w)};
;                         f32x4 v0 = acc[ai][bj][m][0] * rs[ai][m], v1 = acc[ai][bj][m][1] * rs[ai][m];
; #pragma unroll
;                         for (int e = 0; e < 4; ++e) { v0[e] = sigm(v0[e]) * c0[e]; v1[e] = sigm(v1[e]) * c1[e]; }
;                         const f32x4 x0 = (f32x4){bf_lo(xx.x), bf_hi(xx.x), bf_lo(xx.y), bf_hi(xx.y)} + v0, x1 = (f32x4){bf_lo(xx.z), bf_hi(xx.z), bf_lo(xx.w), bf_hi(xx.w)} + v1;
;                         sq += sumsq8(x0, x1); *(u32x4*)(E.xout16 + (size_t)row * D + col0 + bj * 128) = pack8(x0, x1); }
;                     sq += __shfl_xor(sq, 16); sq += __shfl_xor(sq, 32); if (fq == 0) sslot[row] = sq; }
	v_lshlrev_b32_e32 v166, 16, v150
	v_and_b32_e32 v167, 0xffff0000, v150
	v_lshlrev_b32_e32 v174, 16, v151
	v_add_f32_e32 v0, 1.0, v0
	v_rcp_f32_e32 v158, v0
	v_mul_f32_e32 v0, 0xbfb8aa3b, v164
	v_exp_f32_e32 v0, v0
	v_and_b32_e32 v175, 0xffff0000, v151
	v_lshlrev_b32_e32 v168, 16, v152
	v_and_b32_e32 v169, 0xffff0000, v152
	v_add_f32_e32 v0, 1.0, v0
	v_rcp_f32_e32 v164, v0
	v_mul_f32_e32 v0, 0xbfb8aa3b, v159
	v_exp_f32_e32 v0, v0
	v_lshlrev_b32_e32 v152, 16, v153
	v_and_b32_e32 v153, 0xffff0000, v153
	v_add_f32_e32 v0, 1.0, v0
	v_rcp_f32_e32 v159, v0
	v_mul_f32_e32 v0, 0xbfb8aa3b, v165
	v_exp_f32_e32 v0, v0
	s_nop 0
	v_add_f32_e32 v0, 1.0, v0
	v_rcp_f32_e32 v165, v0
	v_mul_f32_e32 v0, 0xbfb8aa3b, v156
	v_exp_f32_e32 v0, v0
	s_nop 0
	v_add_f32_e32 v0, 1.0, v0
	v_rcp_f32_e32 v156, v0
	v_mul_f32_e32 v0, 0xbfb8aa3b, v160
	v_exp_f32_e32 v0, v0
	v_lshlrev_b32_e32 v160, 16, v146
	v_add_f32_e32 v0, 1.0, v0
	v_rcp_f32_e32 v150, v0
	v_mul_f32_e32 v0, 0xbfb8aa3b, v157
	v_exp_f32_e32 v0, v0
	s_nop 0
	v_add_f32_e32 v0, 1.0, v0
	v_rcp_f32_e32 v157, v0
	v_mul_f32_e32 v0, 0xbfb8aa3b, v161
	v_exp_f32_e32 v0, v0
	v_and_b32_e32 v161, 0xffff0000, v146
	v_lshlrev_b32_e32 v146, 16, v147
	v_and_b32_e32 v147, 0xffff0000, v147
	v_add_f32_e32 v0, 1.0, v0
	v_rcp_f32_e32 v151, v0
	v_pk_fma_f32 v[156:157], v[156:157], v[174:175], v[146:147]
	v_pk_fma_f32 v[146:147], v[158:159], v[166:167], v[160:161]
	v_lshlrev_b32_e32 v158, 16, v148
	v_and_b32_e32 v159, 0xffff0000, v148
	v_lshlrev_b32_e32 v148, 16, v149
	v_and_b32_e32 v149, 0xffff0000, v149
	v_pk_fma_f32 v[150:151], v[150:151], v[152:153], v[148:149]
	v_mul_f32_e32 v0, v147, v147
	v_mul_f32_e32 v152, v157, v157
	v_pk_fma_f32 v[148:149], v[164:165], v[168:169], v[158:159]
	v_fmac_f32_e32 v0, v146, v146
	v_fmac_f32_e32 v152, v156, v156
	v_add_f32_e32 v0, v0, v152
	v_mul_f32_e32 v152, v149, v149
	v_fmac_f32_e32 v152, v148, v148
	v_add_f32_e32 v0, v152, v0
	v_mul_f32_e32 v152, v151, v151
	v_fmac_f32_e32 v152, v150, v150
	v_add_f32_e32 v0, v152, v0
	v_add_f32_e32 v0, v176, v0
	v_cvt_pk_bf16_f32 v146, v146, v147
	v_cvt_pk_bf16_f32 v147, v156, v157
	v_cvt_pk_bf16_f32 v148, v148, v149
	v_cvt_pk_bf16_f32 v149, v150, v151
	v_lshl_add_u64 v[228:229], v[154:155], 0, v[230:231]
	ds_bpermute_b32 v222, v243, v146
	ds_bpermute_b32 v223, v243, v147
	ds_bpermute_b32 v224, v243, v148
	ds_bpermute_b32 v225, v243, v149
	ds_bpermute_b32 v146, v171, v0
	s_waitcnt lgkmcnt(0)
	v_add_f32_e32 v0, v0, v146
	ds_bpermute_b32 v146, v170, v0
	s_and_saveexec_b64 s[8:9], s[40:41]
	s_cbranch_execz .LBB0_323
	v_lshl_add_u64 v[148:149], v[210:211], 2, s[44:45]
	s_waitcnt lgkmcnt(0)
	v_add_f32_e32 v0, v0, v146
	global_store_dword v[148:149], v0, off offset:640
; __device__ __forceinline__ float bf_lo(unsigned w) { return __uint_as_float(w << 16); }
; __device__ __forceinline__ float bf_hi(unsigned w) { return __uint_as_float(w & 0xffff0000u); }
; __device__ __forceinline__ float sigm(float v) { return __builtin_amdgcn_rcpf(1.0f + __builtin_amdgcn_exp2f(-1.44269504089f * v)); }
; __device__ __forceinline__ u32x4 pack8(const f32x4& v0, const f32x4& v1) { u32x4 w; w.x = cvt_pk_bf16(v0[0], v0[1]); w.y = cvt_pk_bf16(v0[2], v0[3]); w.z = cvt_pk_bf16(v1[0], v1[1]); w.w = cvt_pk_bf16(v1[2], v1[3]); return w; }
; __device__ __forceinline__ float sumsq8(const f32x4& v0, const f32x4& v1) { return (v0[0] * v0[0] + v0[1] * v0[1]) + (v0[2] * v0[2] + v0[3] * v0[3]) + (v1[0] * v1[0] + v1[1] * v1[1]) + (v1[2] * v1[2] + v1[3] * v1[3]); }
; __device__ __forceinline__ void epi_run(const Epi& E, f32x4 (&acc)[2][2][4][2], const Unit& u, int wr, int wc, int fr, int fq) {
;     ...
;                 for (int mm = 0; mm < 2; ++mm) { const int m = 2 * mh + mm, row = row0 + ai * 128 + m * 16; float sq = 0.f;
; #pragma unroll
;                     for (int bj = 0; bj < 2; ++bj) { const u32x4 xx = x[mm][bj], cc = c[mm][bj];
;                         const f32x4 c0 = (f32x4){bf_lo(cc.x), bf_hi(cc.x), bf_lo(cc.y), bf_hi(cc.y)}, c1 = (f32x4){bf_lo(cc.z), bf_hi(cc.z), bf_lo(cc.w), bf_hi(cc.w)};
;                         f32x4 v0 = acc[ai][bj][m][0] * rs[ai][m], v1 = acc[ai][bj][m][1] * rs[ai][m];
; #pragma unroll
;                         for (int e = 0; e < 4; ++e) { v0[e] = sigm(v0[e]) * c0[e]; v1[e] = sigm(v1[e]) * c1[e]; }
;                         const f32x4 x0 = (f32x4){bf_lo(xx.x), bf_hi(xx.x), bf_lo(xx.y), bf_hi(xx.y)} + v0, x1 = (f32x4){bf_lo(xx.z), bf_hi(xx.z), bf_lo(xx.w), bf_hi(xx.w)} + v1;
;                         sq += sumsq8(x0, x1); *(u32x4*)(E.xout16 + (size_t)row * D + col0 + bj * 128) = pack8(x0, x1); }
;                     sq += __shfl_xor(sq, 16); sq += __shfl_xor(sq, 32); if (fq == 0) sslot[row] = sq; }
.LBB0_323:
	s_or_b64 exec, exec, s[8:9]
	v_add_f32_e32 v0, v172, v173
	v_fmamk_f32 v0, v0, 0x3a800000, v197
	v_rsq_f32_e32 v0, v0
	s_waitcnt lgkmcnt(0)
	global_store_dwordx4 v[228:229], v[222:225], off offset:256
	s_waitcnt vmcnt(4)
	v_lshlrev_b32_e32 v156, 16, v142
	v_and_b32_e32 v157, 0xffff0000, v142
	v_lshlrev_b32_e32 v158, 16, v144
	v_pk_mul_f32 v[154:155], v[10:11], v[0:1] op_sel_hi:[1,0]
	v_pk_mul_f32 v[148:149], v[16:17], v[0:1] op_sel_hi:[1,0]
	v_mul_f32_e32 v155, 0xbfb8aa3b, v155
	v_exp_f32_e32 v155, v155
	v_mul_f32_e32 v148, 0xbfb8aa3b, v148
	v_exp_f32_e32 v148, v148
	v_pk_mul_f32 v[152:153], v[12:13], v[0:1] op_sel_hi:[1,0]
	v_add_f32_e32 v142, 1.0, v155
	v_rcp_f32_e32 v155, v142
	v_and_b32_e32 v159, 0xffff0000, v144
	v_add_f32_e32 v142, 1.0, v148
	v_mul_f32_e32 v144, 0xbfb8aa3b, v152
	v_mul_f32_e32 v148, 0xbfb8aa3b, v149
	v_exp_f32_e32 v144, v144
	v_exp_f32_e32 v149, v148
	v_pk_mul_f32 v[150:151], v[14:15], v[0:1] op_sel_hi:[1,0]
	v_rcp_f32_e32 v148, v142
	v_mul_f32_e32 v150, 0xbfb8aa3b, v150
	v_mul_f32_e32 v151, 0xbfb8aa3b, v151
	v_exp_f32_e32 v150, v150
	v_exp_f32_e32 v151, v151
	v_add_f32_e32 v142, 1.0, v144
	v_add_f32_e32 v144, 1.0, v149
	v_mul_f32_e32 v149, 0xbfb8aa3b, v153
	v_mul_f32_e32 v154, 0xbfb8aa3b, v154
	v_exp_f32_e32 v160, v149
	v_exp_f32_e32 v154, v154
	v_add_f32_e32 v150, 1.0, v150
	v_add_f32_e32 v151, 1.0, v151
	v_rcp_f32_e32 v150, v150
	v_rcp_f32_e32 v151, v151
	v_rcp_f32_e32 v149, v144
	v_lshlrev_b32_e32 v152, 16, v143
	v_and_b32_e32 v153, 0xffff0000, v143
	v_add_f32_e32 v143, 1.0, v160
	v_add_f32_e32 v154, 1.0, v154
	v_rcp_f32_e32 v142, v142
	v_rcp_f32_e32 v143, v143
	v_rcp_f32_e32 v154, v154
	v_lshlrev_b32_e32 v160, 16, v138
	v_and_b32_e32 v161, 0xffff0000, v138
	v_lshlrev_b32_e32 v138, 16, v139
	v_and_b32_e32 v139, 0xffff0000, v139
	v_lshlrev_b32_e32 v144, 16, v145
	v_and_b32_e32 v145, 0xffff0000, v145
	v_pk_fma_f32 v[148:149], v[148:149], v[152:153], v[138:139]
	v_pk_fma_f32 v[138:139], v[150:151], v[156:157], v[160:161]
	v_lshlrev_b32_e32 v150, 16, v140
	v_and_b32_e32 v151, 0xffff0000, v140
	v_lshlrev_b32_e32 v140, 16, v141
	v_and_b32_e32 v141, 0xffff0000, v141
	v_pk_fma_f32 v[142:143], v[142:143], v[144:145], v[140:141]
	v_mul_f32_e32 v144, v139, v139
	v_mul_f32_e32 v145, v149, v149
	v_pk_fma_f32 v[140:141], v[154:155], v[158:159], v[150:151]
	v_fmac_f32_e32 v144, v138, v138
	v_fmac_f32_e32 v145, v148, v148
	v_add_f32_e32 v144, v144, v145
	v_mul_f32_e32 v145, v141, v141
	v_fmac_f32_e32 v145, v140, v140
	v_add_f32_e32 v144, v145, v144
	v_mul_f32_e32 v145, v143, v143
	v_fmac_f32_e32 v145, v142, v142
	v_cvt_pk_bf16_f32 v140, v140, v141
	v_cvt_pk_bf16_f32 v141, v142, v143
	v_pk_mul_f32 v[142:143], v[6:7], v[0:1] op_sel_hi:[1,0]
	v_pk_mul_f32 v[150:151], v[2:3], v[0:1] op_sel_hi:[1,0]
	v_mul_f32_e32 v142, 0xbfb8aa3b, v142
	v_exp_f32_e32 v142, v142
	v_add_f32_e32 v158, v145, v144
	v_cvt_pk_bf16_f32 v138, v138, v139
	v_cvt_pk_bf16_f32 v139, v148, v149
	v_pk_mul_f32 v[144:145], v[8:9], v[0:1] op_sel_hi:[1,0]
	v_pk_mul_f32 v[148:149], v[4:5], v[0:1] op_sel_hi:[1,0]
	v_add_f32_e32 v0, 1.0, v142
	v_mul_f32_e32 v142, 0xbfb8aa3b, v150
	v_exp_f32_e32 v150, v142
	v_mul_f32_e32 v142, 0xbfb8aa3b, v143
	v_exp_f32_e32 v143, v142
	v_rcp_f32_e32 v142, v0
	v_add_f32_e32 v0, 1.0, v150
	v_rcp_f32_e32 v150, v0
	v_add_f32_e32 v0, 1.0, v143
	v_mul_f32_e32 v143, 0xbfb8aa3b, v151
	v_exp_f32_e32 v151, v143
	s_waitcnt vmcnt(2)
	v_lshlrev_b32_e32 v152, 16, v134
	v_and_b32_e32 v153, 0xffff0000, v134
	v_mul_f32_e32 v134, 0xbfb8aa3b, v144
	v_exp_f32_e32 v134, v134
	v_rcp_f32_e32 v143, v0
	v_add_f32_e32 v0, 1.0, v151
	v_rcp_f32_e32 v151, v0
	v_add_f32_e32 v0, 1.0, v134
	v_mul_f32_e32 v134, 0xbfb8aa3b, v148
	v_lshlrev_b32_e32 v154, 16, v136
	v_and_b32_e32 v155, 0xffff0000, v136
	v_exp_f32_e32 v134, v134
	v_mul_f32_e32 v136, 0xbfb8aa3b, v145
	v_exp_f32_e32 v136, v136
	v_rcp_f32_e32 v144, v0
	v_add_f32_e32 v0, 1.0, v134
	v_rcp_f32_e32 v134, v0
	v_add_f32_e32 v0, 1.0, v136
	v_mul_f32_e32 v136, 0xbfb8aa3b, v149
	v_exp_f32_e32 v136, v136
	v_rcp_f32_e32 v145, v0
	v_lshlrev_b32_e32 v148, 16, v135
	v_and_b32_e32 v149, 0xffff0000, v135
	v_add_f32_e32 v0, 1.0, v136
	v_rcp_f32_e32 v135, v0
	v_lshlrev_b32_e32 v156, 16, v130
	v_and_b32_e32 v157, 0xffff0000, v130
	v_lshlrev_b32_e32 v130, 16, v131
	v_and_b32_e32 v131, 0xffff0000, v131
	v_lshlrev_b32_e32 v136, 16, v137
	v_and_b32_e32 v137, 0xffff0000, v137
	v_pk_fma_f32 v[144:145], v[144:145], v[148:149], v[130:131]
	v_pk_fma_f32 v[130:131], v[142:143], v[152:153], v[156:157]
	v_lshlrev_b32_e32 v142, 16, v132
	v_and_b32_e32 v143, 0xffff0000, v132
	v_lshlrev_b32_e32 v132, 16, v133
	v_and_b32_e32 v133, 0xffff0000, v133
	v_pk_fma_f32 v[136:137], v[134:135], v[136:137], v[132:133]
	v_mul_f32_e32 v0, v131, v131
	v_mul_f32_e32 v132, v145, v145
	v_pk_fma_f32 v[134:135], v[150:151], v[154:155], v[142:143]
	v_fmac_f32_e32 v0, v130, v130
	v_fmac_f32_e32 v132, v144, v144
	v_add_f32_e32 v0, v0, v132
	v_mul_f32_e32 v132, v135, v135
	v_fmac_f32_e32 v132, v134, v134
	v_add_f32_e32 v0, v132, v0
	v_mul_f32_e32 v132, v137, v137
	v_fmac_f32_e32 v132, v136, v136
	v_add_f32_e32 v0, v132, v0
	v_add_f32_e32 v0, v158, v0
	ds_bpermute_b32 v148, v171, v0
	s_waitcnt lgkmcnt(1)
	v_lshlrev_b64 v[146:147], 11, v[162:163]
	v_lshl_add_u64 v[132:133], s[78:79], 0, v[146:147]
	v_lshl_add_u64 v[142:143], v[212:213], 1, v[132:133]
	v_cvt_pk_bf16_f32 v132, v130, v131
	s_waitcnt lgkmcnt(0)
	v_add_f32_e32 v0, v0, v148
	ds_bpermute_b32 v130, v170, v0
	v_cvt_pk_bf16_f32 v133, v144, v145
	v_cvt_pk_bf16_f32 v134, v134, v135
	v_cvt_pk_bf16_f32 v135, v136, v137
	v_lshl_add_u64 v[226:227], v[142:143], 0, v[230:231]
	ds_bpermute_b32 v218, v243, v138
	ds_bpermute_b32 v219, v243, v139
	ds_bpermute_b32 v220, v243, v140
	ds_bpermute_b32 v221, v243, v141
	s_waitcnt lgkmcnt(0)
	global_store_dwordx4 v[226:227], v[218:221], off
	v_lshl_add_u64 v[228:229], v[142:143], 0, v[230:231]
	ds_bpermute_b32 v222, v243, v132
	ds_bpermute_b32 v223, v243, v133
	ds_bpermute_b32 v224, v243, v134
	ds_bpermute_b32 v225, v243, v135
	s_waitcnt lgkmcnt(0)
	global_store_dwordx4 v[228:229], v[222:225], off offset:256
	s_and_saveexec_b64 s[8:9], s[40:41]
	s_cbranch_execz .LBB0_325
	v_lshl_add_u64 v[132:133], v[210:211], 2, s[44:45]
	s_waitcnt lgkmcnt(0)
	v_add_f32_e32 v0, v0, v130
	global_store_dword v[132:133], v0, off offset:704
